# v28: v22 plus 64-byte alignment of the MFMA loop heads
# speedup vs baseline: 1.0174x; 1.0174x over previous
.LBB0_273:
	s_waitcnt lgkmcnt(0)
	s_cmp_lg_u64 s[8:9], 0
	s_cselect_b64 s[12:13], -1, 0
	s_add_u32 s14, s10, 0x12100000
	s_addc_u32 s15, s11, 0
	s_add_u32 s10, s10, 0x3100000
	s_mov_b64 s[16:17], 0x80
	s_addc_u32 s11, s11, 0
	s_and_b32 s7, s1, 3
	s_add_i32 m0, s29, 0x18000
	v_lshl_add_u64 v[8:9], v[8:9], 0, s[16:17]
	s_lshl_b32 s47, s0, 6
	s_lshl_b32 s18, s0, 13
	s_lshl_b32 s48, s7, 5
	s_lshl_b32 s19, s7, 12
	s_waitcnt vmcnt(4)
	s_barrier
	global_load_lds_dwordx4 v[8:9], off
	v_lshl_add_u64 v[6:7], v[6:7], 0, s[16:17]
	s_add_i32 m0, s29, 0x1a000
	s_add_i32 s49, s29, 0x8000
	s_add_i32 s51, s29, 0xa000
	global_load_lds_dwordx4 v[6:7], off
	v_lshl_add_u64 v[4:5], v[4:5], 0, s[16:17]
	s_mov_b32 m0, s49
	s_add_u32 s0, s30, 0x40080
	global_load_lds_dwordx4 v[4:5], off
	v_lshl_add_u64 v[2:3], v[2:3], 0, s[16:17]
	s_mov_b32 m0, s51
	s_addc_u32 s1, s31, 0
	global_load_lds_dwordx4 v[2:3], off
	s_add_i32 m0, s29, 0x1c000
	v_lshl_add_u64 v[2:3], s[0:1], 0, v[142:143]
	global_load_lds_dwordx4 v[2:3], off
	v_lshl_add_u64 v[2:3], s[0:1], 0, v[138:139]
	s_add_i32 m0, s29, 0x1e000
	v_bfe_u32 v156, v10, 4, 2
	global_load_lds_dwordx4 v[2:3], off
	v_and_b32_e32 v1, 15, v10
	v_lshlrev_b32_e32 v2, 4, v156
	v_lshlrev_b32_e32 v3, 2, v10
	v_lshl_or_b32 v2, v1, 6, v2
	v_and_b32_e32 v3, 32, v3
	v_bitop3_b32 v4, v2, s18, v3 bitop3:0xde
	v_bitop3_b32 v157, v2, s19, v3 bitop3:0xde
	v_lshlrev_b32_e32 v2, 14, v11
	v_and_b32_e32 v2, 0xffff8000, v2
	v_lshl_add_u32 v2, v12, 11, v2
	v_and_b32_e32 v3, 1, v11
	v_lshl_or_b32 v2, v3, 6, v2
	v_lshl_add_u32 v146, v13, 1, v2
	v_lshlrev_b32_e32 v2, 14, v15
	v_and_b32_e32 v2, 0xffff8000, v2
	s_waitcnt vmcnt(6)
	s_cmp_eq_u32 s7, 0
	v_lshl_add_u32 v2, v14, 11, v2
	v_and_b32_e32 v3, 1, v15
	s_cselect_b64 s[18:19], -1, 0
	v_lshl_or_b32 v2, v3, 6, v2
	s_add_i32 s52, 0, 0x10000
	s_add_i32 s53, 0, 0x14000
	s_sext_i32_i8 s55, s6
	v_mov_b32_e32 v147, v143
	v_lshl_add_u32 v148, v16, 1, v2
	v_mov_b32_e32 v149, v143
	v_mov_b64_e32 v[150:151], 0xd00
	v_mov_b64_e32 v[152:153], 0xcff
	v_add_u32_e32 v158, s52, v157
	v_add_u32_e32 v159, 0, v4
	v_add_u32_e32 v160, s53, v157
	s_movk_i32 s54, 0x1800
	v_mov_b32_e32 v161, 0x3db504f3
	s_barrier
	s_branch .LBB0_275
	.p2align 6

.LBB0_277:
	s_ashr_i32 s23, s22, 31
	s_lshl_b64 s[0:1], s[22:23], 19
	v_cmp_lt_i64_e32 vcc, s[24:25], v[150:151]
	s_add_u32 s24, s5, s0
	s_addc_u32 s25, s38, s1
	s_and_b64 s[0:1], vcc, exec
	s_cselect_b32 s23, s25, s35
	s_cselect_b32 s56, s24, s34
	s_ashr_i32 s21, s20, 31
	s_lshl_b64 s[0:1], s[20:21], 19
	s_add_u32 s26, s39, s0
	s_addc_u32 s27, s40, s1
	s_and_b64 s[0:1], vcc, exec
	s_cselect_b32 s21, s27, s31
	s_cselect_b32 s57, s26, s30
	s_add_u32 s58, s30, 0x100
	s_addc_u32 s59, s31, 0
	s_add_u32 s30, s34, 0x40080
	v_mov_b32_e32 v2, 0
	s_addc_u32 s31, s35, 0
	s_mov_b32 s60, -2
	v_mov_b32_e32 v3, v2
	v_mov_b32_e32 v4, v2
	v_mov_b32_e32 v5, v2
	v_mov_b32_e32 v6, v2
	v_mov_b32_e32 v7, v2
	v_mov_b32_e32 v8, v2
	v_mov_b32_e32 v9, v2
	v_mov_b32_e32 v10, v2
	v_mov_b32_e32 v11, v2
	v_mov_b32_e32 v12, v2
	v_mov_b32_e32 v13, v2
	v_mov_b32_e32 v18, v2
	v_mov_b32_e32 v19, v2
	v_mov_b32_e32 v20, v2
	v_mov_b32_e32 v21, v2
	v_mov_b32_e32 v26, v2
	v_mov_b32_e32 v27, v2
	v_mov_b32_e32 v28, v2
	v_mov_b32_e32 v29, v2
	v_mov_b32_e32 v34, v2
	v_mov_b32_e32 v35, v2
	v_mov_b32_e32 v36, v2
	v_mov_b32_e32 v37, v2
	v_mov_b32_e32 v42, v2
	v_mov_b32_e32 v43, v2
	v_mov_b32_e32 v44, v2
	v_mov_b32_e32 v45, v2
	v_mov_b32_e32 v50, v2
	v_mov_b32_e32 v51, v2
	v_mov_b32_e32 v52, v2
	v_mov_b32_e32 v53, v2
	v_mov_b32_e32 v14, v2
	v_mov_b32_e32 v15, v2
	v_mov_b32_e32 v16, v2
	v_mov_b32_e32 v17, v2
	v_mov_b32_e32 v22, v2
	v_mov_b32_e32 v23, v2
	v_mov_b32_e32 v24, v2
	v_mov_b32_e32 v25, v2
	v_mov_b32_e32 v30, v2
	v_mov_b32_e32 v31, v2
	v_mov_b32_e32 v32, v2
	v_mov_b32_e32 v33, v2
	v_mov_b32_e32 v38, v2
	v_mov_b32_e32 v39, v2
	v_mov_b32_e32 v40, v2
	v_mov_b32_e32 v41, v2
	v_mov_b32_e32 v46, v2
	v_mov_b32_e32 v47, v2
	v_mov_b32_e32 v48, v2
	v_mov_b32_e32 v49, v2
	v_mov_b32_e32 v54, v2
	v_mov_b32_e32 v55, v2
	v_mov_b32_e32 v56, v2
	v_mov_b32_e32 v57, v2
	v_mov_b32_e32 v58, v2
	v_mov_b32_e32 v59, v2
	v_mov_b32_e32 v60, v2
	v_mov_b32_e32 v61, v2
	v_mov_b32_e32 v62, v2
	v_mov_b32_e32 v63, v2
	v_mov_b32_e32 v64, v2
	v_mov_b32_e32 v65, v2
	v_mov_b32_e32 v66, v2
	v_mov_b32_e32 v67, v2
	v_mov_b32_e32 v68, v2
	v_mov_b32_e32 v69, v2
	v_mov_b32_e32 v70, v2
	v_mov_b32_e32 v71, v2
	v_mov_b32_e32 v72, v2
	v_mov_b32_e32 v73, v2
	v_mov_b32_e32 v74, v2
	v_mov_b32_e32 v75, v2
	v_mov_b32_e32 v76, v2
	v_mov_b32_e32 v77, v2
	v_mov_b32_e32 v82, v2
	v_mov_b32_e32 v83, v2
	v_mov_b32_e32 v84, v2
	v_mov_b32_e32 v85, v2
	v_mov_b32_e32 v90, v2
	v_mov_b32_e32 v91, v2
	v_mov_b32_e32 v92, v2
	v_mov_b32_e32 v93, v2
	v_mov_b32_e32 v98, v2
	v_mov_b32_e32 v99, v2
	v_mov_b32_e32 v100, v2
	v_mov_b32_e32 v101, v2
	v_mov_b32_e32 v106, v2
	v_mov_b32_e32 v107, v2
	v_mov_b32_e32 v108, v2
	v_mov_b32_e32 v109, v2
	v_mov_b32_e32 v114, v2
	v_mov_b32_e32 v115, v2
	v_mov_b32_e32 v116, v2
	v_mov_b32_e32 v117, v2
	v_mov_b32_e32 v78, v2
	v_mov_b32_e32 v79, v2
	v_mov_b32_e32 v80, v2
	v_mov_b32_e32 v81, v2
	v_mov_b32_e32 v86, v2
	v_mov_b32_e32 v87, v2
	v_mov_b32_e32 v88, v2
	v_mov_b32_e32 v89, v2
	v_mov_b32_e32 v94, v2
	v_mov_b32_e32 v95, v2
	v_mov_b32_e32 v96, v2
	v_mov_b32_e32 v97, v2
	v_mov_b32_e32 v102, v2
	v_mov_b32_e32 v103, v2
	v_mov_b32_e32 v104, v2
	v_mov_b32_e32 v105, v2
	v_mov_b32_e32 v110, v2
	v_mov_b32_e32 v111, v2
	v_mov_b32_e32 v112, v2
	v_mov_b32_e32 v113, v2
	v_mov_b32_e32 v118, v2
	v_mov_b32_e32 v119, v2
	v_mov_b32_e32 v120, v2
	v_mov_b32_e32 v121, v2
	v_mov_b32_e32 v122, v2
	v_mov_b32_e32 v123, v2
	v_mov_b32_e32 v124, v2
	v_mov_b32_e32 v125, v2
	v_mov_b32_e32 v126, v2
	v_mov_b32_e32 v127, v2
	v_mov_b32_e32 v128, v2
	v_mov_b32_e32 v129, v2
	.p2align 6

.LBB0_354:
	s_ashr_i32 s23, s22, 31
	s_lshl_b64 s[0:1], s[22:23], 27
	s_add_u32 s34, s48, s0
	s_addc_u32 s35, s49, s1
	s_cmpk_lt_u32 s69, 0x80
	s_cselect_b64 s[20:21], -1, 0
	s_and_b64 s[0:1], s[20:21], exec
	s_cselect_b32 s0, 0, 0x7c0
	v_cndmask_b32_e64 v2, v161, v160, s[20:21]
	s_or_b32 s38, s72, s0
	v_add_u32_e32 v4, s38, v2
	v_mov_b64_e32 v[2:3], s[30:31]
	v_mad_i64_i32 v[4:5], s[0:1], v4, s57, v[2:3]
	s_lshl_b32 s0, s25, 8
	s_mov_b32 s1, s24
	v_lshl_add_u64 v[4:5], v[4:5], 0, s[0:1]
	v_mov_b32_e32 v153, v151
	v_lshl_add_u64 v[4:5], v[4:5], 0, v[152:153]
	s_waitcnt vmcnt(0)
	global_load_dwordx4 v[98:101], v[4:5], off
	global_load_dwordx4 v[102:105], v[4:5], off offset:1024
	v_cndmask_b32_e64 v4, v163, v162, s[20:21]
	v_add_u32_e32 v4, s38, v4
	v_mad_i64_i32 v[4:5], s[22:23], v4, s57, v[2:3]
	v_lshl_add_u64 v[4:5], v[4:5], 0, s[0:1]
	v_lshl_add_u64 v[4:5], v[4:5], 0, v[152:153]
	global_load_dwordx4 v[106:109], v[4:5], off
	global_load_dwordx4 v[110:113], v[4:5], off offset:1024
	v_cndmask_b32_e64 v4, v165, v164, s[20:21]
	v_add_u32_e32 v4, s38, v4
	v_cndmask_b32_e64 v6, v167, v166, s[20:21]
	v_mad_i64_i32 v[4:5], s[22:23], v4, s57, v[2:3]
	s_lshl_b32 s36, s25, 9
	s_mov_b32 s37, s24
	v_add_u32_e32 v6, s38, v6
	v_lshl_add_u64 v[4:5], v[4:5], 0, s[36:37]
	v_mov_b32_e32 v155, v151
	v_mad_i64_i32 v[6:7], s[22:23], v6, s57, v[2:3]
	v_lshl_add_u64 v[4:5], v[4:5], 0, v[154:155]
	v_lshl_add_u64 v[6:7], v[6:7], 0, s[36:37]
	v_lshl_add_u64 v[6:7], v[6:7], 0, v[154:155]
	global_load_dwordx4 v[114:117], v[4:5], off offset:2048
	global_load_dwordx4 v[118:121], v[6:7], off offset:2048
	v_cndmask_b32_e64 v4, v169, v168, s[20:21]
	v_add_u32_e32 v4, s38, v4
	v_cndmask_b32_e64 v6, v171, v170, s[20:21]
	v_mad_i64_i32 v[4:5], s[22:23], v4, s57, v[2:3]
	v_add_u32_e32 v6, s38, v6
	v_lshl_add_u64 v[4:5], v[4:5], 0, s[36:37]
	v_mad_i64_i32 v[2:3], s[22:23], v6, s57, v[2:3]
	v_lshl_add_u64 v[4:5], v[4:5], 0, v[154:155]
	v_lshl_add_u64 v[2:3], v[2:3], 0, s[36:37]
	v_lshl_add_u64 v[2:3], v[2:3], 0, v[154:155]
	global_load_dwordx4 v[122:125], v[4:5], off offset:2048
	global_load_dwordx4 v[126:129], v[2:3], off offset:2048
	s_add_u32 s1, s34, s36
	s_addc_u32 s23, s35, 0
	s_add_u32 s22, s1, s58
	s_addc_u32 s23, s23, 0
	s_add_u32 s34, s30, s0
	s_addc_u32 s35, s31, 0
	s_add_u32 s36, s30, s36
	s_mov_b32 s73, 0
	s_addc_u32 s37, s31, 0
	s_mov_b32 s76, 30
	v_mov_b32_e32 v155, 0
	v_mov_b32_e32 v2, 0
	v_mov_b32_e32 v3, 0
	v_mov_b32_e32 v4, 0
	v_mov_b32_e32 v5, 0
	v_mov_b32_e32 v6, 0
	v_mov_b32_e32 v7, 0
	v_mov_b32_e32 v8, 0
	v_mov_b32_e32 v9, 0
	v_mov_b32_e32 v10, 0
	v_mov_b32_e32 v11, 0
	v_mov_b32_e32 v12, 0
	v_mov_b32_e32 v13, 0
	v_mov_b32_e32 v14, 0
	v_mov_b32_e32 v15, 0
	v_mov_b32_e32 v16, 0
	v_mov_b32_e32 v17, 0
	v_mov_b32_e32 v18, 0
	v_mov_b32_e32 v19, 0
	v_mov_b32_e32 v20, 0
	v_mov_b32_e32 v21, 0
	v_mov_b32_e32 v22, 0
	v_mov_b32_e32 v23, 0
	v_mov_b32_e32 v24, 0
	v_mov_b32_e32 v25, 0
	v_mov_b32_e32 v26, 0
	v_mov_b32_e32 v27, 0
	v_mov_b32_e32 v28, 0
	v_mov_b32_e32 v29, 0
	v_mov_b32_e32 v30, 0
	v_mov_b32_e32 v31, 0
	v_mov_b32_e32 v32, 0
	v_mov_b32_e32 v33, 0
	v_mov_b32_e32 v34, 0
	v_mov_b32_e32 v35, 0
	v_mov_b32_e32 v36, 0
	v_mov_b32_e32 v37, 0
	v_mov_b32_e32 v38, 0
	v_mov_b32_e32 v39, 0
	v_mov_b32_e32 v40, 0
	v_mov_b32_e32 v41, 0
	v_mov_b32_e32 v42, 0
	v_mov_b32_e32 v43, 0
	v_mov_b32_e32 v44, 0
	v_mov_b32_e32 v45, 0
	v_mov_b32_e32 v46, 0
	v_mov_b32_e32 v47, 0
	v_mov_b32_e32 v48, 0
	v_mov_b32_e32 v49, 0
	v_mov_b32_e32 v50, 0
	v_mov_b32_e32 v51, 0
	v_mov_b32_e32 v52, 0
	v_mov_b32_e32 v53, 0
	v_mov_b32_e32 v54, 0
	v_mov_b32_e32 v55, 0
	v_mov_b32_e32 v56, 0
	v_mov_b32_e32 v57, 0
	v_mov_b32_e32 v58, 0
	v_mov_b32_e32 v59, 0
	v_mov_b32_e32 v60, 0
	v_mov_b32_e32 v61, 0
	v_mov_b32_e32 v62, 0
	v_mov_b32_e32 v63, 0
	v_mov_b32_e32 v64, 0
	v_mov_b32_e32 v65, 0
	s_mov_b32 s77, 0
	s_mov_b32 s80, 0
	s_waitcnt lgkmcnt(0)
	s_barrier
	s_branch .LBB0_356
	.p2align 6

.LBB0_432:
	s_lshl_b32 s0, s0, 5
	s_and_b32 s45, s0, 0x60
	s_lshl_b32 s44, s1, 6
	s_lshl_b32 s28, s1, 13
	s_lshl_b32 s30, s45, 7
	s_add_u32 s0, s22, 0x780080
	s_addc_u32 s1, s23, 0
	s_add_i32 m0, s6, 0x18000
	v_lshl_add_u64 v[14:15], s[0:1], 0, v[138:139]
	s_waitcnt vmcnt(4)
	s_barrier
	global_load_lds_dwordx4 v[14:15], off
	v_lshl_add_u64 v[14:15], s[0:1], 0, v[134:135]
	s_add_i32 m0, s6, 0x1a000
	s_mov_b64 s[26:27], 0x80
	s_add_i32 s46, s6, 0x8000
	s_add_i32 s47, s6, 0xa000
	global_load_lds_dwordx4 v[14:15], off
	v_lshl_add_u64 v[4:5], v[4:5], 0, s[26:27]
	s_mov_b32 m0, s46
	s_add_u32 s0, s22, 0x7c0080
	global_load_lds_dwordx4 v[4:5], off
	v_lshl_add_u64 v[2:3], v[2:3], 0, s[26:27]
	s_mov_b32 m0, s47
	s_addc_u32 s1, s23, 0
	global_load_lds_dwordx4 v[2:3], off
	s_add_i32 m0, s6, 0x1c000
	v_lshl_add_u64 v[2:3], s[0:1], 0, v[138:139]
	global_load_lds_dwordx4 v[2:3], off
	v_lshl_add_u64 v[2:3], s[0:1], 0, v[134:135]
	s_add_i32 m0, s6, 0x1e000
	v_bfe_u32 v133, v6, 4, 2
	global_load_lds_dwordx4 v[2:3], off
	v_and_b32_e32 v131, 15, v6
	v_lshlrev_b32_e32 v2, 4, v133
	v_lshlrev_b32_e32 v3, 2, v6
	v_lshl_or_b32 v2, v131, 6, v2
	v_and_b32_e32 v3, 32, v3
	v_bitop3_b32 v4, v2, s28, v3 bitop3:0xde
	v_bitop3_b32 v151, v2, s30, v3 bitop3:0xde
	v_lshlrev_b32_e32 v2, 14, v7
	v_and_b32_e32 v2, 0xffff8000, v2
	v_lshl_add_u32 v2, v8, 11, v2
	v_and_b32_e32 v3, 1, v7
	v_lshl_or_b32 v2, v3, 6, v2
	v_lshl_add_u32 v142, v9, 1, v2
	v_lshlrev_b32_e32 v2, 14, v11
	v_and_b32_e32 v2, 0xffff8000, v2
	s_waitcnt vmcnt(6)
	v_lshl_add_u32 v2, v10, 11, v2
	v_and_b32_e32 v3, 1, v11
	s_add_i32 s52, 0, 0x10000
	v_lshl_or_b32 v2, v3, 6, v2
	v_add_u32_e32 v152, s52, v151
	s_add_i32 s54, 0, 0x14000
	s_add_i32 s52, s52, s5
	s_mov_b32 s48, 0x18000
	s_mov_b32 s49, 0x8000
	v_mov_b32_e32 v143, v139
	v_lshl_add_u32 v144, v12, 1, v2
	v_mov_b32_e32 v145, v139
	v_add_u32_e32 v153, 0, v4
	v_add_u32_e32 v154, s54, v151
	s_mov_b32 s28, 0x3fd744fd
	s_add_i32 s50, s6, 0xc000
	s_add_i32 s51, s6, 0xe000
	s_add_i32 s53, s52, 0x2000
	s_add_i32 s54, s54, s5
	s_mov_b32 s59, s2
	s_mov_b64 s[34:35], s[8:9]
	s_mov_b32 s55, 0
	s_barrier
	.p2align 6
.LBB0_433:
	s_add_i32 s55, s55, 1
	s_mov_b64 s[0:1], s[14:15]
	s_lshr_b32 s14, s55, 2
	s_mul_i32 s14, s14, s74
	s_mov_b64 s[36:37], s[34:35]
	s_mov_b32 s35, s56
	s_add_i32 s56, s14, s2
	s_cmpk_lt_i32 s56, 0x100
	s_cselect_b64 s[38:39], -1, 0
	s_cmpk_gt_i32 s56, 0xff
	s_mov_b32 s34, s57
	s_cselect_b64 s[30:31], -1, 0
	s_and_b32 s57, s55, 3
	s_and_b64 s[14:15], s[38:39], exec
	s_cselect_b32 s14, s56, s35
	s_cselect_b32 s34, s57, s34
	s_ashr_i32 s15, s14, 31
	s_lshl_b64 s[14:15], s[14:15], 19
	s_add_u32 s14, s20, s14
	s_addc_u32 s15, s21, s15
	s_and_b64 s[40:41], s[38:39], exec
	s_cselect_b32 s60, s15, s1
	s_cselect_b32 s61, s14, s0
	s_ashr_i32 s35, s34, 31
	s_lshl_b64 s[34:35], s[34:35], 19
	s_add_u32 s34, s8, s34
	s_addc_u32 s35, s9, s35
	s_and_b64 s[38:39], s[38:39], exec
	s_cselect_b32 s62, s35, s37
	s_cselect_b32 s63, s34, s36
	s_add_u32 s66, s36, 0x100
	s_addc_u32 s67, s37, 0
	s_add_u32 s36, s0, 0x40080
	v_mov_b32_e32 v2, 0
	s_addc_u32 s37, s1, 0
	s_mov_b32 s69, -2
	v_mov_b32_e32 v3, v2
	v_mov_b32_e32 v4, v2
	v_mov_b32_e32 v5, v2
	v_mov_b32_e32 v6, v2
	v_mov_b32_e32 v7, v2
	v_mov_b32_e32 v8, v2
	v_mov_b32_e32 v9, v2
	v_mov_b32_e32 v14, v2
	v_mov_b32_e32 v15, v2
	v_mov_b32_e32 v16, v2
	v_mov_b32_e32 v17, v2
	v_mov_b32_e32 v22, v2
	v_mov_b32_e32 v23, v2
	v_mov_b32_e32 v24, v2
	v_mov_b32_e32 v25, v2
	s_waitcnt vmcnt(0)
	v_mov_b32_e32 v30, v2
	v_mov_b32_e32 v31, v2
	v_mov_b32_e32 v32, v2
	v_mov_b32_e32 v33, v2
	v_mov_b32_e32 v38, v2
	v_mov_b32_e32 v39, v2
	v_mov_b32_e32 v40, v2
	v_mov_b32_e32 v41, v2
	v_mov_b32_e32 v46, v2
	v_mov_b32_e32 v47, v2
	v_mov_b32_e32 v48, v2
	v_mov_b32_e32 v49, v2
	v_mov_b32_e32 v54, v2
	v_mov_b32_e32 v55, v2
	v_mov_b32_e32 v56, v2
	v_mov_b32_e32 v57, v2
	v_mov_b32_e32 v10, v2
	v_mov_b32_e32 v11, v2
	v_mov_b32_e32 v12, v2
	v_mov_b32_e32 v13, v2
	v_mov_b32_e32 v18, v2
	v_mov_b32_e32 v19, v2
	v_mov_b32_e32 v20, v2
	v_mov_b32_e32 v21, v2
	v_mov_b32_e32 v26, v2
	v_mov_b32_e32 v27, v2
	v_mov_b32_e32 v28, v2
	v_mov_b32_e32 v29, v2
	v_mov_b32_e32 v34, v2
	v_mov_b32_e32 v35, v2
	v_mov_b32_e32 v36, v2
	v_mov_b32_e32 v37, v2
	v_mov_b32_e32 v42, v2
	v_mov_b32_e32 v43, v2
	v_mov_b32_e32 v44, v2
	v_mov_b32_e32 v45, v2
	v_mov_b32_e32 v50, v2
	v_mov_b32_e32 v51, v2
	v_mov_b32_e32 v52, v2
	v_mov_b32_e32 v53, v2
	v_mov_b32_e32 v58, v2
	v_mov_b32_e32 v59, v2
	v_mov_b32_e32 v60, v2
	v_mov_b32_e32 v61, v2
	v_mov_b32_e32 v62, v2
	v_mov_b32_e32 v63, v2
	v_mov_b32_e32 v64, v2
	v_mov_b32_e32 v65, v2
	v_mov_b32_e32 v66, v2
	v_mov_b32_e32 v67, v2
	v_mov_b32_e32 v68, v2
	v_mov_b32_e32 v69, v2
	v_mov_b32_e32 v70, v2
	v_mov_b32_e32 v71, v2
	v_mov_b32_e32 v72, v2
	v_mov_b32_e32 v73, v2
	v_mov_b32_e32 v78, v2
	v_mov_b32_e32 v79, v2
	v_mov_b32_e32 v80, v2
	v_mov_b32_e32 v81, v2
	v_mov_b32_e32 v86, v2
	v_mov_b32_e32 v87, v2
	v_mov_b32_e32 v88, v2
	v_mov_b32_e32 v89, v2
	v_mov_b32_e32 v94, v2
	v_mov_b32_e32 v95, v2
	v_mov_b32_e32 v96, v2
	v_mov_b32_e32 v97, v2
	v_mov_b32_e32 v102, v2
	v_mov_b32_e32 v103, v2
	v_mov_b32_e32 v104, v2
	v_mov_b32_e32 v105, v2
	v_mov_b32_e32 v110, v2
	v_mov_b32_e32 v111, v2
	v_mov_b32_e32 v112, v2
	v_mov_b32_e32 v113, v2
	v_mov_b32_e32 v118, v2
	v_mov_b32_e32 v119, v2
	v_mov_b32_e32 v120, v2
	v_mov_b32_e32 v121, v2
	v_mov_b32_e32 v74, v2
	v_mov_b32_e32 v75, v2
	v_mov_b32_e32 v76, v2
	v_mov_b32_e32 v77, v2
	v_mov_b32_e32 v82, v2
	v_mov_b32_e32 v83, v2
	v_mov_b32_e32 v84, v2
	v_mov_b32_e32 v85, v2
	v_mov_b32_e32 v90, v2
	v_mov_b32_e32 v91, v2
	v_mov_b32_e32 v92, v2
	v_mov_b32_e32 v93, v2
	v_mov_b32_e32 v98, v2
	v_mov_b32_e32 v99, v2
	v_mov_b32_e32 v100, v2
	v_mov_b32_e32 v101, v2
	v_mov_b32_e32 v106, v2
	v_mov_b32_e32 v107, v2
	v_mov_b32_e32 v108, v2
	v_mov_b32_e32 v109, v2
	v_mov_b32_e32 v114, v2
	v_mov_b32_e32 v115, v2
	v_mov_b32_e32 v116, v2
	v_mov_b32_e32 v117, v2
	v_mov_b32_e32 v122, v2
	v_mov_b32_e32 v123, v2
	v_mov_b32_e32 v124, v2
	v_mov_b32_e32 v125, v2
	v_mov_b32_e32 v126, v2
	v_mov_b32_e32 v127, v2
	v_mov_b32_e32 v128, v2
	v_mov_b32_e32 v129, v2
	.p2align 6

.LBB0_676:
	v_bfe_u32 v196, v2, 4, 2
	v_and_b32_e32 v195, 15, v2
	v_lshlrev_b32_e32 v3, 4, v196
	v_lshlrev_b32_e32 v2, 2, v2
	v_lshl_or_b32 v3, v195, 6, v3
	s_lshl_b32 s0, s8, 13
	v_and_b32_e32 v2, 32, v2
	v_bitop3_b32 v8, v3, s0, v2 bitop3:0xde
	s_lshl_b32 s0, s1, 5
	v_mov_b32_e32 v165, v163
	s_and_b32 s50, s0, 0x60
	v_lshl_add_u64 v[4:5], s[30:31], 0, v[164:165]
	v_mov_b32_e32 v167, v163
	s_lshl_b32 s0, s50, 7
	v_lshl_add_u64 v[6:7], s[30:31], 0, v[166:167]
	v_bitop3_b32 v197, v3, s0, v2 bitop3:0xde
	s_add_i32 m0, s45, 0x18000
	v_lshl_add_u64 v[2:3], v[4:5], 0, s[20:21]
	v_mov_b32_e32 v169, v163
	s_lshl_b32 s49, s8, 6
	s_waitcnt vmcnt(4)
	s_barrier
	global_load_lds_dwordx4 v[2:3], off
	v_lshl_add_u64 v[2:3], v[6:7], 0, s[20:21]
	s_add_i32 m0, s45, 0x1a000
	s_add_i32 s51, s45, 0x8000
	s_add_i32 s52, s45, 0xa000
	v_mov_b32_e32 v171, v163
	global_load_lds_dwordx4 v[2:3], off
	v_lshl_add_u64 v[2:3], s[18:19], 0, v[168:169]
	s_mov_b32 m0, s51
	s_add_u32 s0, s30, 0x20080
	global_load_lds_dwordx4 v[2:3], off
	v_lshl_add_u64 v[2:3], s[18:19], 0, v[170:171]
	s_mov_b32 m0, s52
	s_addc_u32 s1, s31, 0
	global_load_lds_dwordx4 v[2:3], off
	s_add_i32 m0, s45, 0x1c000
	v_lshl_add_u64 v[2:3], s[0:1], 0, v[164:165]
	global_load_lds_dwordx4 v[2:3], off
	v_lshl_add_u64 v[2:3], s[0:1], 0, v[166:167]
	s_add_i32 m0, s45, 0x1e000
	s_mov_b32 s53, 0
	global_load_lds_dwordx4 v[2:3], off
	s_waitcnt vmcnt(6)
	v_add_u32_e32 v169, 0, v8
	s_barrier
	s_waitcnt vmcnt(0)
	.p2align 6

.LBB0_687:
	s_ashr_i32 s0, s54, 5
	s_ashr_i32 s1, s0, 31
	s_lshl_b64 s[0:1], s[0:1], 21
	s_add_u32 s12, s4, s0
	s_addc_u32 s13, s5, s1
	s_ashr_i32 s25, s24, 31
	s_lshl_b64 s[0:1], s[24:25], 18
	s_add_u32 s12, s12, s0
	s_addc_u32 s13, s13, s1
	s_and_b64 s[0:1], s[10:11], exec
	s_cselect_b32 s25, s13, s31
	s_cselect_b32 s27, s12, s30
	v_mov_b32_e32 v173, v163
	v_mov_b32_e32 v175, v163
	s_add_u32 s29, s30, 0x100
	v_mov_b32_e32 v34, 0
	s_addc_u32 s55, s31, 0
	v_lshl_add_u64 v[176:177], s[18:19], 0, v[174:175]
	v_lshl_add_u64 v[178:179], s[18:19], 0, v[172:173]
	s_mov_b32 s56, -2
	s_mov_b64 s[34:35], 0
	v_mov_b32_e32 v35, v34
	v_mov_b32_e32 v36, v34
	v_mov_b32_e32 v37, v34
	v_mov_b32_e32 v42, v34
	v_mov_b32_e32 v43, v34
	v_mov_b32_e32 v44, v34
	v_mov_b32_e32 v45, v34
	v_mov_b32_e32 v50, v34
	v_mov_b32_e32 v51, v34
	v_mov_b32_e32 v52, v34
	v_mov_b32_e32 v53, v34
	v_mov_b32_e32 v58, v34
	v_mov_b32_e32 v59, v34
	v_mov_b32_e32 v60, v34
	v_mov_b32_e32 v61, v34
	v_mov_b32_e32 v66, v34
	v_mov_b32_e32 v67, v34
	v_mov_b32_e32 v68, v34
	v_mov_b32_e32 v69, v34
	v_mov_b32_e32 v74, v34
	v_mov_b32_e32 v75, v34
	v_mov_b32_e32 v76, v34
	v_mov_b32_e32 v77, v34
	v_mov_b32_e32 v82, v34
	v_mov_b32_e32 v83, v34
	v_mov_b32_e32 v84, v34
	v_mov_b32_e32 v85, v34
	v_mov_b32_e32 v90, v34
	v_mov_b32_e32 v91, v34
	v_mov_b32_e32 v92, v34
	v_mov_b32_e32 v93, v34
	v_mov_b32_e32 v38, v34
	v_mov_b32_e32 v39, v34
	v_mov_b32_e32 v40, v34
	v_mov_b32_e32 v41, v34
	v_mov_b32_e32 v46, v34
	v_mov_b32_e32 v47, v34
	v_mov_b32_e32 v48, v34
	v_mov_b32_e32 v49, v34
	v_mov_b32_e32 v54, v34
	v_mov_b32_e32 v55, v34
	v_mov_b32_e32 v56, v34
	v_mov_b32_e32 v57, v34
	v_mov_b32_e32 v62, v34
	v_mov_b32_e32 v63, v34
	v_mov_b32_e32 v64, v34
	v_mov_b32_e32 v65, v34
	v_mov_b32_e32 v70, v34
	v_mov_b32_e32 v71, v34
	v_mov_b32_e32 v72, v34
	v_mov_b32_e32 v73, v34
	v_mov_b32_e32 v78, v34
	v_mov_b32_e32 v79, v34
	v_mov_b32_e32 v80, v34
	v_mov_b32_e32 v81, v34
	v_mov_b32_e32 v86, v34
	v_mov_b32_e32 v87, v34
	v_mov_b32_e32 v88, v34
	v_mov_b32_e32 v89, v34
	v_mov_b32_e32 v94, v34
	v_mov_b32_e32 v95, v34
	v_mov_b32_e32 v96, v34
	v_mov_b32_e32 v97, v34
	v_mov_b32_e32 v98, v34
	v_mov_b32_e32 v99, v34
	v_mov_b32_e32 v100, v34
	v_mov_b32_e32 v101, v34
	v_mov_b32_e32 v106, v34
	v_mov_b32_e32 v107, v34
	v_mov_b32_e32 v108, v34
	v_mov_b32_e32 v109, v34
	v_mov_b32_e32 v114, v34
	v_mov_b32_e32 v115, v34
	v_mov_b32_e32 v116, v34
	v_mov_b32_e32 v117, v34
	v_mov_b32_e32 v122, v34
	v_mov_b32_e32 v123, v34
	v_mov_b32_e32 v124, v34
	v_mov_b32_e32 v125, v34
	v_mov_b32_e32 v130, v34
	v_mov_b32_e32 v131, v34
	v_mov_b32_e32 v132, v34
	v_mov_b32_e32 v133, v34
	v_mov_b32_e32 v138, v34
	v_mov_b32_e32 v139, v34
	v_mov_b32_e32 v140, v34
	v_mov_b32_e32 v141, v34
	v_mov_b32_e32 v146, v34
	v_mov_b32_e32 v147, v34
	v_mov_b32_e32 v148, v34
	v_mov_b32_e32 v149, v34
	v_mov_b32_e32 v154, v34
	v_mov_b32_e32 v155, v34
	v_mov_b32_e32 v156, v34
	v_mov_b32_e32 v157, v34
	v_mov_b32_e32 v102, v34
	v_mov_b32_e32 v103, v34
	v_mov_b32_e32 v104, v34
	v_mov_b32_e32 v105, v34
	v_mov_b32_e32 v110, v34
	v_mov_b32_e32 v111, v34
	v_mov_b32_e32 v112, v34
	v_mov_b32_e32 v113, v34
	v_mov_b32_e32 v118, v34
	v_mov_b32_e32 v119, v34
	v_mov_b32_e32 v120, v34
	v_mov_b32_e32 v121, v34
	v_mov_b32_e32 v126, v34
	v_mov_b32_e32 v127, v34
	v_mov_b32_e32 v128, v34
	v_mov_b32_e32 v129, v34
	v_mov_b32_e32 v134, v34
	v_mov_b32_e32 v135, v34
	v_mov_b32_e32 v136, v34
	v_mov_b32_e32 v137, v34
	v_mov_b32_e32 v142, v34
	v_mov_b32_e32 v143, v34
	v_mov_b32_e32 v144, v34
	v_mov_b32_e32 v145, v34
	v_mov_b32_e32 v150, v34
	v_mov_b32_e32 v151, v34
	v_mov_b32_e32 v152, v34
	v_mov_b32_e32 v153, v34
	v_mov_b32_e32 v158, v34
	v_mov_b32_e32 v159, v34
	v_mov_b32_e32 v160, v34
	v_mov_b32_e32 v161, v34
	.p2align 6

.LBB0_747:
	s_add_u32 s10, s10, 0x12100000
	s_addc_u32 s11, s11, 0
	s_lshl_b32 s0, s0, 5
	s_mov_b64 s[12:13], 0x80
	s_and_b32 s42, s0, 0x60
	s_add_i32 m0, s25, 0x18000
	v_lshl_add_u64 v[4:5], v[4:5], 0, s[12:13]
	s_lshl_b32 s41, s1, 6
	s_lshl_b32 s9, s1, 13
	s_lshl_b32 s14, s42, 7
	s_waitcnt vmcnt(4)
	s_barrier
	global_load_lds_dwordx4 v[4:5], off
	s_add_i32 m0, s25, 0x1a000
	s_add_u32 s0, s28, 0x8000
	v_lshl_add_u64 v[2:3], v[2:3], 0, s[12:13]
	s_addc_u32 s1, s29, 0
	s_add_i32 s43, s25, 0x8000
	global_load_lds_dwordx4 v[2:3], off
	v_lshl_add_u64 v[2:3], s[0:1], 0, v[152:153]
	s_mov_b32 m0, s43
	s_add_i32 s44, s25, 0xa000
	global_load_lds_dwordx4 v[2:3], off
	v_lshl_add_u64 v[2:3], s[0:1], 0, v[148:149]
	s_add_u32 s0, s26, 0x20080
	s_mov_b32 m0, s44
	s_addc_u32 s1, s27, 0
	global_load_lds_dwordx4 v[2:3], off
	s_add_i32 m0, s25, 0x1c000
	v_lshl_add_u64 v[2:3], s[0:1], 0, v[150:151]
	global_load_lds_dwordx4 v[2:3], off
	v_lshl_add_u64 v[2:3], s[0:1], 0, v[146:147]
	s_add_i32 m0, s25, 0x1e000
	v_bfe_u32 v167, v6, 4, 2
	global_load_lds_dwordx4 v[2:3], off
	v_and_b32_e32 v166, 15, v6
	v_lshlrev_b32_e32 v2, 4, v167
	v_lshlrev_b32_e32 v3, 2, v6
	v_lshl_or_b32 v2, v166, 6, v2
	v_and_b32_e32 v3, 32, v3
	v_bitop3_b32 v4, v2, s9, v3 bitop3:0xde
	v_bitop3_b32 v168, v2, s14, v3 bitop3:0xde
	v_lshlrev_b32_e32 v2, 10, v7
	v_and_b32_e32 v2, 0xfffff800, v2
	v_lshl_add_u32 v2, v8, 7, v2
	v_and_b32_e32 v3, 1, v7
	v_lshl_or_b32 v2, v3, 6, v2
	v_lshl_add_u32 v154, v9, 1, v2
	v_lshlrev_b32_e32 v2, 10, v11
	v_and_b32_e32 v2, 0xfffff800, v2
	s_waitcnt vmcnt(6)
	v_lshl_add_u32 v2, v10, 7, v2
	v_and_b32_e32 v3, 1, v11
	v_lshl_or_b32 v2, v3, 6, v2
	s_add_i32 s45, 0, 0x10000
	s_add_i32 s46, 0, 0x14000
	s_sext_i32_i8 s48, s8
	v_mov_b32_e32 v155, v151
	v_lshl_add_u32 v156, v12, 1, v2
	v_mov_b32_e32 v157, v151
	v_mov_b64_e32 v[158:159], 0x800
	v_mov_b64_e32 v[160:161], 0x7ff
	v_add_u32_e32 v169, s45, v168
	v_add_u32_e32 v170, 0, v4
	v_mov_b32_e32 v171, 0x7f7f7f7f
	v_add_u32_e32 v172, s46, v168
	s_mov_b32 s14, 0x3d000000
	s_mov_b32 s47, 0xc3d00000
	v_mov_b32_e32 v173, 0x43d00000
	s_barrier
	.p2align 6

.LBB0_754:
	s_ashr_i32 s19, s18, 31
	s_lshl_b64 s[0:1], s[18:19], 18
	v_cmp_lt_i64_e32 vcc, s[20:21], v[158:159]
	s_add_u32 s20, s5, s0
	s_addc_u32 s21, s6, s1
	s_and_b64 s[0:1], vcc, exec
	s_cselect_b32 s19, s21, s29
	s_cselect_b32 s49, s20, s28
	s_ashr_i32 s0, s18, 5
	s_ashr_i32 s1, s0, 31
	s_lshl_b64 s[0:1], s[0:1], 20
	s_add_u32 s22, s7, s0
	s_addc_u32 s23, s15, s1
	s_ashr_i32 s17, s16, 31
	s_lshl_b64 s[0:1], s[16:17], 18
	s_add_u32 s22, s22, s0
	s_addc_u32 s23, s23, s1
	s_and_b64 s[0:1], vcc, exec
	s_cselect_b32 s17, s23, s27
	s_cselect_b32 s50, s22, s26
	s_add_u32 s51, s26, 0x100
	s_addc_u32 s52, s27, 0
	s_add_u32 s26, s28, 0xc000
	v_mov_b32_e32 v18, 0
	s_addc_u32 s27, s29, 0
	s_mov_b32 s53, -2
	v_mov_b32_e32 v19, v18
	v_mov_b32_e32 v20, v18
	v_mov_b32_e32 v21, v18
	v_mov_b32_e32 v22, v18
	v_mov_b32_e32 v23, v18
	v_mov_b32_e32 v24, v18
	v_mov_b32_e32 v25, v18
	v_mov_b32_e32 v34, v18
	v_mov_b32_e32 v35, v18
	v_mov_b32_e32 v36, v18
	v_mov_b32_e32 v37, v18
	v_mov_b32_e32 v38, v18
	v_mov_b32_e32 v39, v18
	v_mov_b32_e32 v40, v18
	v_mov_b32_e32 v41, v18
	v_mov_b32_e32 v50, v18
	v_mov_b32_e32 v51, v18
	v_mov_b32_e32 v52, v18
	v_mov_b32_e32 v53, v18
	v_mov_b32_e32 v54, v18
	v_mov_b32_e32 v55, v18
	v_mov_b32_e32 v56, v18
	v_mov_b32_e32 v57, v18
	v_mov_b32_e32 v66, v18
	v_mov_b32_e32 v67, v18
	v_mov_b32_e32 v68, v18
	v_mov_b32_e32 v69, v18
	v_mov_b32_e32 v70, v18
	v_mov_b32_e32 v71, v18
	v_mov_b32_e32 v72, v18
	v_mov_b32_e32 v73, v18
	v_mov_b32_e32 v26, v18
	v_mov_b32_e32 v27, v18
	v_mov_b32_e32 v28, v18
	v_mov_b32_e32 v29, v18
	v_mov_b32_e32 v30, v18
	v_mov_b32_e32 v31, v18
	v_mov_b32_e32 v32, v18
	v_mov_b32_e32 v33, v18
	v_mov_b32_e32 v42, v18
	v_mov_b32_e32 v43, v18
	v_mov_b32_e32 v44, v18
	v_mov_b32_e32 v45, v18
	v_mov_b32_e32 v46, v18
	v_mov_b32_e32 v47, v18
	v_mov_b32_e32 v48, v18
	v_mov_b32_e32 v49, v18
	v_mov_b32_e32 v58, v18
	v_mov_b32_e32 v59, v18
	v_mov_b32_e32 v60, v18
	v_mov_b32_e32 v61, v18
	v_mov_b32_e32 v62, v18
	v_mov_b32_e32 v63, v18
	v_mov_b32_e32 v64, v18
	v_mov_b32_e32 v65, v18
	v_mov_b32_e32 v74, v18
	v_mov_b32_e32 v75, v18
	v_mov_b32_e32 v76, v18
	v_mov_b32_e32 v77, v18
	v_mov_b32_e32 v78, v18
	v_mov_b32_e32 v79, v18
	v_mov_b32_e32 v80, v18
	v_mov_b32_e32 v81, v18
	v_mov_b32_e32 v82, v18
	v_mov_b32_e32 v83, v18
	v_mov_b32_e32 v84, v18
	v_mov_b32_e32 v85, v18
	v_mov_b32_e32 v86, v18
	v_mov_b32_e32 v87, v18
	v_mov_b32_e32 v88, v18
	v_mov_b32_e32 v89, v18
	v_mov_b32_e32 v98, v18
	v_mov_b32_e32 v99, v18
	v_mov_b32_e32 v100, v18
	v_mov_b32_e32 v101, v18
	v_mov_b32_e32 v102, v18
	v_mov_b32_e32 v103, v18
	v_mov_b32_e32 v104, v18
	v_mov_b32_e32 v105, v18
	v_mov_b32_e32 v114, v18
	v_mov_b32_e32 v115, v18
	v_mov_b32_e32 v116, v18
	v_mov_b32_e32 v117, v18
	v_mov_b32_e32 v118, v18
	v_mov_b32_e32 v119, v18
	v_mov_b32_e32 v120, v18
	v_mov_b32_e32 v121, v18
	v_mov_b32_e32 v130, v18
	v_mov_b32_e32 v131, v18
	v_mov_b32_e32 v132, v18
	v_mov_b32_e32 v133, v18
	v_mov_b32_e32 v134, v18
	v_mov_b32_e32 v135, v18
	v_mov_b32_e32 v136, v18
	v_mov_b32_e32 v137, v18
	v_mov_b32_e32 v90, v18
	v_mov_b32_e32 v91, v18
	v_mov_b32_e32 v92, v18
	v_mov_b32_e32 v93, v18
	v_mov_b32_e32 v94, v18
	v_mov_b32_e32 v95, v18
	v_mov_b32_e32 v96, v18
	v_mov_b32_e32 v97, v18
	v_mov_b32_e32 v106, v18
	v_mov_b32_e32 v107, v18
	v_mov_b32_e32 v108, v18
	v_mov_b32_e32 v109, v18
	v_mov_b32_e32 v110, v18
	v_mov_b32_e32 v111, v18
	v_mov_b32_e32 v112, v18
	v_mov_b32_e32 v113, v18
	v_mov_b32_e32 v122, v18
	v_mov_b32_e32 v123, v18
	v_mov_b32_e32 v124, v18
	v_mov_b32_e32 v125, v18
	v_mov_b32_e32 v126, v18
	v_mov_b32_e32 v127, v18
	v_mov_b32_e32 v128, v18
	v_mov_b32_e32 v129, v18
	v_mov_b32_e32 v138, v18
	v_mov_b32_e32 v139, v18
	v_mov_b32_e32 v140, v18
	v_mov_b32_e32 v141, v18
	v_mov_b32_e32 v142, v18
	v_mov_b32_e32 v143, v18
	v_mov_b32_e32 v144, v18
	v_mov_b32_e32 v145, v18
	.p2align 6

.LBB0_890:
	s_add_u32 s12, s14, 0x12100000
	s_addc_u32 s13, s15, 0
	v_bfe_u32 v150, v16, 4, 2
	s_add_u32 s14, s14, 0x3100000
	v_and_b32_e32 v147, 15, v16
	v_lshlrev_b32_e32 v17, 4, v150
	v_lshlrev_b32_e32 v16, 2, v16
	s_mov_b64 s[16:17], 0x80
	s_sext_i32_i8 s50, s8
	s_addc_u32 s15, s15, 0
	s_and_b32 s8, s1, 3
	s_lshl_b32 s43, s0, 6
	v_lshl_or_b32 v17, v147, 6, v17
	s_lshl_b32 s0, s0, 13
	v_and_b32_e32 v16, 32, v16
	s_add_i32 m0, s25, 0x18000
	v_lshl_add_u64 v[8:9], v[8:9], 0, s[16:17]
	v_bitop3_b32 v18, v17, s0, v16 bitop3:0xde
	s_lshl_b32 s44, s8, 5
	s_lshl_b32 s0, s8, 12
	s_waitcnt vmcnt(4)
	s_barrier
	global_load_lds_dwordx4 v[8:9], off
	v_lshl_add_u64 v[6:7], v[6:7], 0, s[16:17]
	s_add_i32 m0, s25, 0x1a000
	s_add_i32 s45, s25, 0x8000
	s_add_i32 s46, s25, 0xa000
	v_bitop3_b32 v151, v17, s0, v16 bitop3:0xde
	global_load_lds_dwordx4 v[6:7], off
	v_lshl_add_u64 v[4:5], v[4:5], 0, s[16:17]
	s_mov_b32 m0, s45
	s_add_u32 s0, s30, 0x40080
	global_load_lds_dwordx4 v[4:5], off
	v_lshl_add_u64 v[2:3], v[2:3], 0, s[16:17]
	s_mov_b32 m0, s46
	s_addc_u32 s1, s31, 0
	global_load_lds_dwordx4 v[2:3], off
	s_add_i32 m0, s25, 0x1c000
	v_lshl_add_u64 v[2:3], s[0:1], 0, v[134:135]
	global_load_lds_dwordx4 v[2:3], off
	v_lshl_add_u64 v[2:3], s[0:1], 0, v[130:131]
	s_add_i32 m0, s25, 0x1e000
	s_cmp_eq_u32 s8, 0
	global_load_lds_dwordx4 v[2:3], off
	v_lshlrev_b32_e32 v2, 14, v10
	v_and_b32_e32 v2, 0xffff8000, v2
	v_lshl_add_u32 v2, v11, 11, v2
	v_and_b32_e32 v3, 1, v10
	v_lshl_or_b32 v2, v3, 6, v2
	v_lshl_add_u32 v138, v12, 1, v2
	v_lshlrev_b32_e32 v2, 14, v14
	v_and_b32_e32 v2, 0xffff8000, v2
	s_waitcnt vmcnt(6)
	v_lshl_add_u32 v2, v13, 11, v2
	v_and_b32_e32 v3, 1, v14
	s_cselect_b64 s[18:19], -1, 0
	v_lshl_or_b32 v2, v3, 6, v2
	s_add_i32 s47, 0, 0x10000
	s_add_i32 s48, 0, 0x14000
	v_mov_b32_e32 v139, v135
	v_lshl_add_u32 v140, v15, 1, v2
	v_mov_b32_e32 v141, v135
	v_mov_b64_e32 v[142:143], 0xd00
	v_mov_b64_e32 v[144:145], 0xcff
	v_add_u32_e32 v152, s47, v151
	v_add_u32_e32 v153, 0, v18
	v_add_u32_e32 v154, s48, v151
	s_movk_i32 s49, 0x1800
	v_mov_b32_e32 v155, 0x3db504f3
	s_barrier
	s_branch .LBB0_892
	.p2align 6

.LBB0_894:
	s_ashr_i32 s23, s22, 31
	s_lshl_b64 s[0:1], s[22:23], 19
	v_cmp_lt_i64_e32 vcc, s[26:27], v[142:143]
	s_add_u32 s26, s5, s0
	s_addc_u32 s27, s6, s1
	s_and_b64 s[0:1], vcc, exec
	s_cselect_b32 s23, s27, s35
	s_cselect_b32 s51, s26, s34
	s_ashr_i32 s21, s20, 31
	s_lshl_b64 s[0:1], s[20:21], 19
	s_add_u32 s28, s7, s0
	s_addc_u32 s29, s10, s1
	s_and_b64 s[0:1], vcc, exec
	s_cselect_b32 s21, s29, s31
	s_cselect_b32 s52, s28, s30
	s_add_u32 s53, s30, 0x100
	s_addc_u32 s54, s31, 0
	s_add_u32 s30, s34, 0x40080
	v_mov_b32_e32 v2, 0
	s_addc_u32 s31, s35, 0
	s_mov_b32 s55, -2
	v_mov_b32_e32 v3, v2
	v_mov_b32_e32 v4, v2
	v_mov_b32_e32 v5, v2
	v_mov_b32_e32 v6, v2
	v_mov_b32_e32 v7, v2
	v_mov_b32_e32 v8, v2
	v_mov_b32_e32 v9, v2
	v_mov_b32_e32 v10, v2
	v_mov_b32_e32 v11, v2
	v_mov_b32_e32 v12, v2
	v_mov_b32_e32 v13, v2
	v_mov_b32_e32 v18, v2
	v_mov_b32_e32 v19, v2
	v_mov_b32_e32 v20, v2
	v_mov_b32_e32 v21, v2
	v_mov_b32_e32 v26, v2
	v_mov_b32_e32 v27, v2
	v_mov_b32_e32 v28, v2
	v_mov_b32_e32 v29, v2
	v_mov_b32_e32 v34, v2
	v_mov_b32_e32 v35, v2
	v_mov_b32_e32 v36, v2
	v_mov_b32_e32 v37, v2
	v_mov_b32_e32 v42, v2
	v_mov_b32_e32 v43, v2
	v_mov_b32_e32 v44, v2
	v_mov_b32_e32 v45, v2
	v_mov_b32_e32 v50, v2
	v_mov_b32_e32 v51, v2
	v_mov_b32_e32 v52, v2
	v_mov_b32_e32 v53, v2
	v_mov_b32_e32 v14, v2
	v_mov_b32_e32 v15, v2
	v_mov_b32_e32 v16, v2
	v_mov_b32_e32 v17, v2
	v_mov_b32_e32 v22, v2
	v_mov_b32_e32 v23, v2
	v_mov_b32_e32 v24, v2
	v_mov_b32_e32 v25, v2
	v_mov_b32_e32 v30, v2
	v_mov_b32_e32 v31, v2
	v_mov_b32_e32 v32, v2
	v_mov_b32_e32 v33, v2
	v_mov_b32_e32 v38, v2
	v_mov_b32_e32 v39, v2
	v_mov_b32_e32 v40, v2
	v_mov_b32_e32 v41, v2
	v_mov_b32_e32 v46, v2
	v_mov_b32_e32 v47, v2
	v_mov_b32_e32 v48, v2
	v_mov_b32_e32 v49, v2
	v_mov_b32_e32 v54, v2
	v_mov_b32_e32 v55, v2
	v_mov_b32_e32 v56, v2
	v_mov_b32_e32 v57, v2
	v_mov_b32_e32 v58, v2
	v_mov_b32_e32 v59, v2
	v_mov_b32_e32 v60, v2
	v_mov_b32_e32 v61, v2
	v_mov_b32_e32 v62, v2
	v_mov_b32_e32 v63, v2
	v_mov_b32_e32 v64, v2
	v_mov_b32_e32 v65, v2
	v_mov_b32_e32 v66, v2
	v_mov_b32_e32 v67, v2
	v_mov_b32_e32 v68, v2
	v_mov_b32_e32 v69, v2
	v_mov_b32_e32 v70, v2
	v_mov_b32_e32 v71, v2
	v_mov_b32_e32 v72, v2
	v_mov_b32_e32 v73, v2
	v_mov_b32_e32 v74, v2
	v_mov_b32_e32 v75, v2
	v_mov_b32_e32 v76, v2
	v_mov_b32_e32 v77, v2
	v_mov_b32_e32 v82, v2
	v_mov_b32_e32 v83, v2
	v_mov_b32_e32 v84, v2
	v_mov_b32_e32 v85, v2
	v_mov_b32_e32 v90, v2
	v_mov_b32_e32 v91, v2
	v_mov_b32_e32 v92, v2
	v_mov_b32_e32 v93, v2
	v_mov_b32_e32 v98, v2
	v_mov_b32_e32 v99, v2
	v_mov_b32_e32 v100, v2
	v_mov_b32_e32 v101, v2
	v_mov_b32_e32 v106, v2
	v_mov_b32_e32 v107, v2
	v_mov_b32_e32 v108, v2
	v_mov_b32_e32 v109, v2
	v_mov_b32_e32 v114, v2
	v_mov_b32_e32 v115, v2
	v_mov_b32_e32 v116, v2
	v_mov_b32_e32 v117, v2
	v_mov_b32_e32 v78, v2
	v_mov_b32_e32 v79, v2
	v_mov_b32_e32 v80, v2
	v_mov_b32_e32 v81, v2
	v_mov_b32_e32 v86, v2
	v_mov_b32_e32 v87, v2
	v_mov_b32_e32 v88, v2
	v_mov_b32_e32 v89, v2
	v_mov_b32_e32 v94, v2
	v_mov_b32_e32 v95, v2
	v_mov_b32_e32 v96, v2
	v_mov_b32_e32 v97, v2
	v_mov_b32_e32 v102, v2
	v_mov_b32_e32 v103, v2
	v_mov_b32_e32 v104, v2
	v_mov_b32_e32 v105, v2
	v_mov_b32_e32 v110, v2
	v_mov_b32_e32 v111, v2
	v_mov_b32_e32 v112, v2
	v_mov_b32_e32 v113, v2
	v_mov_b32_e32 v118, v2
	v_mov_b32_e32 v119, v2
	v_mov_b32_e32 v120, v2
	v_mov_b32_e32 v121, v2
	v_mov_b32_e32 v122, v2
	v_mov_b32_e32 v123, v2
	v_mov_b32_e32 v124, v2
	v_mov_b32_e32 v125, v2
	v_mov_b32_e32 v126, v2
	v_mov_b32_e32 v127, v2
	v_mov_b32_e32 v128, v2
	v_mov_b32_e32 v129, v2
	.p2align 6

.LBB0_968:
	s_lshl_b64 s[0:1], s[14:15], 27
	s_add_u32 s14, s11, s0
	s_addc_u32 s15, s38, s1
	s_lshl_b64 s[0:1], s[26:27], 2
	s_add_u32 s26, s24, s0
	s_addc_u32 s27, s25, s1
	s_add_u32 s0, s14, s20
	s_addc_u32 s1, s15, 0
	s_lshl_b32 s14, s92, 1
	s_add_u32 s28, s0, s14
	s_addc_u32 s29, s1, 0
	s_add_u32 s30, s22, s30
	s_addc_u32 s31, s23, 0
	s_add_u32 s34, s22, s20
	v_mov_b32_e32 v2, 0
	s_waitcnt vmcnt(0)
	v_cvt_pk_bf16_f32 v128, v7, v8
	v_cvt_pk_bf16_f32 v129, v4, v9
	v_cvt_pk_bf16_f32 v130, v5, v6
	v_cvt_pk_bf16_f32 v131, v10, v11
	s_addc_u32 s35, s23, 0
	s_mov_b32 s20, 3
	s_mov_b32 s48, 63
	v_mov_b32_e32 v3, v2
	v_mov_b32_e32 v4, v2
	v_mov_b32_e32 v5, v2
	v_mov_b32_e32 v6, v2
	v_mov_b32_e32 v7, v2
	v_mov_b32_e32 v8, v2
	v_mov_b32_e32 v9, v2
	v_mov_b32_e32 v10, v2
	v_mov_b32_e32 v11, v2
	v_mov_b32_e32 v12, v2
	v_mov_b32_e32 v13, v2
	v_mov_b32_e32 v14, v2
	v_mov_b32_e32 v15, v2
	v_mov_b32_e32 v16, v2
	v_mov_b32_e32 v17, v2
	v_mov_b32_e32 v18, v2
	v_mov_b32_e32 v19, v2
	v_mov_b32_e32 v20, v2
	v_mov_b32_e32 v21, v2
	v_mov_b32_e32 v22, v2
	v_mov_b32_e32 v23, v2
	v_mov_b32_e32 v24, v2
	v_mov_b32_e32 v25, v2
	v_mov_b32_e32 v26, v2
	v_mov_b32_e32 v27, v2
	v_mov_b32_e32 v28, v2
	v_mov_b32_e32 v29, v2
	v_mov_b32_e32 v30, v2
	v_mov_b32_e32 v31, v2
	v_mov_b32_e32 v32, v2
	v_mov_b32_e32 v33, v2
	v_mov_b32_e32 v34, v2
	v_mov_b32_e32 v35, v2
	v_mov_b32_e32 v36, v2
	v_mov_b32_e32 v37, v2
	v_mov_b32_e32 v38, v2
	v_mov_b32_e32 v39, v2
	v_mov_b32_e32 v40, v2
	v_mov_b32_e32 v41, v2
	v_mov_b32_e32 v42, v2
	v_mov_b32_e32 v43, v2
	v_mov_b32_e32 v44, v2
	v_mov_b32_e32 v45, v2
	v_mov_b32_e32 v46, v2
	v_mov_b32_e32 v47, v2
	v_mov_b32_e32 v48, v2
	v_mov_b32_e32 v49, v2
	v_mov_b32_e32 v50, v2
	v_mov_b32_e32 v51, v2
	v_mov_b32_e32 v52, v2
	v_mov_b32_e32 v53, v2
	v_mov_b32_e32 v54, v2
	v_mov_b32_e32 v55, v2
	v_mov_b32_e32 v56, v2
	v_mov_b32_e32 v57, v2
	v_mov_b32_e32 v58, v2
	v_mov_b32_e32 v59, v2
	v_mov_b32_e32 v60, v2
	v_mov_b32_e32 v61, v2
	v_mov_b32_e32 v62, v2
	v_mov_b32_e32 v63, v2
	v_mov_b32_e32 v64, v2
	v_mov_b32_e32 v65, v2
	s_branch .LBB0_970
	.p2align 6

.LBB0_1045:
	v_bfe_u32 v153, v12, 4, 2
	s_lshl_b32 s0, s0, 5
	v_and_b32_e32 v151, 15, v12
	v_lshlrev_b32_e32 v13, 4, v153
	v_lshlrev_b32_e32 v12, 2, v12
	s_and_b32 s45, s0, 0x60
	s_lshl_b32 s44, s1, 6
	v_lshl_or_b32 v13, v151, 6, v13
	s_lshl_b32 s1, s1, 13
	v_and_b32_e32 v12, 32, v12
	s_lshl_b32 s0, s45, 7
	v_bitop3_b32 v169, v13, s0, v12 bitop3:0xde
	s_add_u32 s0, s22, 0x1000080
	v_bitop3_b32 v14, v13, s1, v12 bitop3:0xde
	s_addc_u32 s1, s23, 0
	s_add_i32 m0, s6, 0x18000
	v_lshl_add_u64 v[12:13], s[0:1], 0, v[158:159]
	s_waitcnt vmcnt(4)
	s_barrier
	global_load_lds_dwordx4 v[12:13], off
	v_lshl_add_u64 v[12:13], s[0:1], 0, v[154:155]
	s_add_i32 m0, s6, 0x1a000
	s_mov_b64 s[28:29], 0x80
	s_add_i32 s48, s6, 0x8000
	s_add_i32 s49, s6, 0xa000
	global_load_lds_dwordx4 v[12:13], off
	v_lshl_add_u64 v[4:5], v[4:5], 0, s[28:29]
	s_mov_b32 m0, s48
	s_add_u32 s0, s22, 0x1040080
	global_load_lds_dwordx4 v[4:5], off
	v_lshl_add_u64 v[2:3], v[2:3], 0, s[28:29]
	s_mov_b32 m0, s49
	s_addc_u32 s1, s23, 0
	global_load_lds_dwordx4 v[2:3], off
	s_add_i32 m0, s6, 0x1c000
	v_lshl_add_u64 v[2:3], s[0:1], 0, v[158:159]
	global_load_lds_dwordx4 v[2:3], off
	v_lshl_add_u64 v[2:3], s[0:1], 0, v[154:155]
	s_add_i32 m0, s6, 0x1e000
	s_add_i32 s52, 0, 0x10000
	global_load_lds_dwordx4 v[2:3], off
	v_lshlrev_b32_e32 v2, 14, v6
	v_and_b32_e32 v2, 0xffff8000, v2
	v_lshl_add_u32 v2, v7, 11, v2
	v_and_b32_e32 v3, 1, v6
	v_lshl_or_b32 v2, v3, 6, v2
	v_lshl_add_u32 v162, v8, 1, v2
	v_lshlrev_b32_e32 v2, 14, v10
	v_and_b32_e32 v2, 0xffff8000, v2
	s_waitcnt vmcnt(6)
	v_lshl_add_u32 v2, v9, 11, v2
	v_and_b32_e32 v3, 1, v10
	v_lshl_or_b32 v2, v3, 6, v2
	v_add_u32_e32 v170, s52, v169
	s_add_i32 s54, 0, 0x14000
	s_add_i32 s52, s52, s5
	s_mov_b32 s46, 0x18000
	s_mov_b32 s47, 0x8000
	v_mov_b32_e32 v163, v159
	v_lshl_add_u32 v164, v11, 1, v2
	v_mov_b32_e32 v165, v159
	v_add_u32_e32 v171, 0, v14
	v_add_u32_e32 v172, s54, v169
	s_mov_b32 s30, 0x3fd744fd
	s_add_i32 s50, s6, 0xc000
	s_add_i32 s51, s6, 0xe000
	s_add_i32 s53, s52, 0x2000
	s_add_i32 s54, s54, s5
	s_mov_b32 s59, s2
	s_mov_b64 s[36:37], s[8:9]
	s_mov_b32 s55, 0
	s_barrier
	.p2align 6
.LBB0_1046:
	s_add_i32 s55, s55, 1
	s_mov_b64 s[0:1], s[26:27]
	s_lshr_b32 s26, s55, 2
	s_mul_i32 s26, s26, s74
	s_mov_b64 s[38:39], s[36:37]
	s_mov_b32 s37, s56
	s_add_i32 s56, s26, s2
	s_cmpk_lt_i32 s56, 0x100
	s_cselect_b64 s[40:41], -1, 0
	s_cmpk_gt_i32 s56, 0xff
	s_mov_b32 s36, s57
	s_cselect_b64 s[34:35], -1, 0
	s_and_b32 s57, s55, 3
	s_and_b64 s[26:27], s[40:41], exec
	s_cselect_b32 s26, s56, s37
	s_cselect_b32 s36, s57, s36
	s_ashr_i32 s27, s26, 31
	s_lshl_b64 s[26:27], s[26:27], 19
	s_add_u32 s26, s20, s26
	s_addc_u32 s27, s21, s27
	s_and_b64 s[42:43], s[40:41], exec
	s_cselect_b32 s60, s27, s1
	s_cselect_b32 s61, s26, s0
	s_ashr_i32 s37, s36, 31
	s_lshl_b64 s[36:37], s[36:37], 19
	s_add_u32 s36, s8, s36
	s_addc_u32 s37, s9, s37
	s_and_b64 s[40:41], s[40:41], exec
	s_cselect_b32 s62, s37, s39
	s_cselect_b32 s63, s36, s38
	s_add_u32 s64, s38, 0x100
	s_addc_u32 s65, s39, 0
	s_add_u32 s38, s0, 0x40080
	v_mov_b32_e32 v2, 0
	s_addc_u32 s39, s1, 0
	s_mov_b32 s69, -2
	v_mov_b32_e32 v3, v2
	v_mov_b32_e32 v4, v2
	v_mov_b32_e32 v5, v2
	v_mov_b32_e32 v6, v2
	v_mov_b32_e32 v7, v2
	v_mov_b32_e32 v8, v2
	v_mov_b32_e32 v9, v2
	v_mov_b32_e32 v14, v2
	v_mov_b32_e32 v15, v2
	v_mov_b32_e32 v16, v2
	v_mov_b32_e32 v17, v2
	v_mov_b32_e32 v22, v2
	v_mov_b32_e32 v23, v2
	v_mov_b32_e32 v24, v2
	v_mov_b32_e32 v25, v2
	v_mov_b32_e32 v30, v2
	v_mov_b32_e32 v31, v2
	v_mov_b32_e32 v32, v2
	v_mov_b32_e32 v33, v2
	v_mov_b32_e32 v38, v2
	v_mov_b32_e32 v39, v2
	v_mov_b32_e32 v40, v2
	v_mov_b32_e32 v41, v2
	v_mov_b32_e32 v46, v2
	v_mov_b32_e32 v47, v2
	v_mov_b32_e32 v48, v2
	v_mov_b32_e32 v49, v2
	v_mov_b32_e32 v54, v2
	v_mov_b32_e32 v55, v2
	v_mov_b32_e32 v56, v2
	v_mov_b32_e32 v57, v2
	v_mov_b32_e32 v10, v2
	v_mov_b32_e32 v11, v2
	v_mov_b32_e32 v12, v2
	v_mov_b32_e32 v13, v2
	v_mov_b32_e32 v18, v2
	v_mov_b32_e32 v19, v2
	v_mov_b32_e32 v20, v2
	v_mov_b32_e32 v21, v2
	v_mov_b32_e32 v26, v2
	v_mov_b32_e32 v27, v2
	v_mov_b32_e32 v28, v2
	v_mov_b32_e32 v29, v2
	v_mov_b32_e32 v34, v2
	v_mov_b32_e32 v35, v2
	v_mov_b32_e32 v36, v2
	v_mov_b32_e32 v37, v2
	v_mov_b32_e32 v42, v2
	v_mov_b32_e32 v43, v2
	v_mov_b32_e32 v44, v2
	v_mov_b32_e32 v45, v2
	v_mov_b32_e32 v50, v2
	v_mov_b32_e32 v51, v2
	v_mov_b32_e32 v52, v2
	v_mov_b32_e32 v53, v2
	v_mov_b32_e32 v58, v2
	v_mov_b32_e32 v59, v2
	v_mov_b32_e32 v60, v2
	v_mov_b32_e32 v61, v2
	v_mov_b32_e32 v62, v2
	v_mov_b32_e32 v63, v2
	v_mov_b32_e32 v64, v2
	v_mov_b32_e32 v65, v2
	v_mov_b32_e32 v66, v2
	v_mov_b32_e32 v67, v2
	v_mov_b32_e32 v68, v2
	v_mov_b32_e32 v69, v2
	v_mov_b32_e32 v70, v2
	v_mov_b32_e32 v71, v2
	v_mov_b32_e32 v72, v2
	v_mov_b32_e32 v73, v2
	v_mov_b32_e32 v78, v2
	v_mov_b32_e32 v79, v2
	v_mov_b32_e32 v80, v2
	v_mov_b32_e32 v81, v2
	v_mov_b32_e32 v86, v2
	v_mov_b32_e32 v87, v2
	s_waitcnt vmcnt(0)
	v_mov_b32_e32 v88, v2
	v_mov_b32_e32 v89, v2
	v_mov_b32_e32 v94, v2
	v_mov_b32_e32 v95, v2
	v_mov_b32_e32 v96, v2
	v_mov_b32_e32 v97, v2
	v_mov_b32_e32 v102, v2
	v_mov_b32_e32 v103, v2
	v_mov_b32_e32 v104, v2
	v_mov_b32_e32 v105, v2
	v_mov_b32_e32 v106, v2
	v_mov_b32_e32 v107, v2
	v_mov_b32_e32 v108, v2
	v_mov_b32_e32 v109, v2
	v_mov_b32_e32 v114, v2
	v_mov_b32_e32 v115, v2
	v_mov_b32_e32 v116, v2
	v_mov_b32_e32 v117, v2
	v_mov_b32_e32 v74, v2
	v_mov_b32_e32 v75, v2
	v_mov_b32_e32 v76, v2
	v_mov_b32_e32 v77, v2
	v_mov_b32_e32 v82, v2
	v_mov_b32_e32 v83, v2
	v_mov_b32_e32 v84, v2
	v_mov_b32_e32 v85, v2
	v_mov_b32_e32 v90, v2
	v_mov_b32_e32 v91, v2
	v_mov_b32_e32 v92, v2
	v_mov_b32_e32 v93, v2
	v_mov_b32_e32 v98, v2
	v_mov_b32_e32 v99, v2
	v_mov_b32_e32 v100, v2
	v_mov_b32_e32 v101, v2
	v_mov_b32_e32 v110, v2
	v_mov_b32_e32 v111, v2
	v_mov_b32_e32 v112, v2
	v_mov_b32_e32 v113, v2
	v_mov_b32_e32 v118, v2
	v_mov_b32_e32 v119, v2
	v_mov_b32_e32 v120, v2
	v_mov_b32_e32 v121, v2
	v_mov_b32_e32 v122, v2
	v_mov_b32_e32 v123, v2
	v_mov_b32_e32 v124, v2
	v_mov_b32_e32 v125, v2
	v_mov_b32_e32 v126, v2
	v_mov_b32_e32 v127, v2
	v_mov_b32_e32 v128, v2
	v_mov_b32_e32 v129, v2
	.p2align 6

.LBB0_1290:
	v_bfe_u32 v196, v2, 4, 2
	v_and_b32_e32 v195, 15, v2
	v_lshlrev_b32_e32 v3, 4, v196
	v_lshlrev_b32_e32 v2, 2, v2
	v_lshl_or_b32 v3, v195, 6, v3
	s_lshl_b32 s0, s8, 13
	v_and_b32_e32 v2, 32, v2
	v_bitop3_b32 v8, v3, s0, v2 bitop3:0xde
	s_lshl_b32 s0, s1, 5
	v_mov_b32_e32 v165, v163
	s_and_b32 s50, s0, 0x60
	v_lshl_add_u64 v[4:5], s[34:35], 0, v[164:165]
	v_mov_b32_e32 v167, v163
	s_lshl_b32 s0, s50, 7
	v_lshl_add_u64 v[6:7], s[34:35], 0, v[166:167]
	v_bitop3_b32 v197, v3, s0, v2 bitop3:0xde
	s_add_i32 m0, s45, 0x18000
	v_lshl_add_u64 v[2:3], v[4:5], 0, s[22:23]
	v_mov_b32_e32 v169, v163
	s_lshl_b32 s49, s8, 6
	s_waitcnt vmcnt(4)
	s_barrier
	global_load_lds_dwordx4 v[2:3], off
	v_lshl_add_u64 v[2:3], v[6:7], 0, s[22:23]
	s_add_i32 m0, s45, 0x1a000
	s_add_i32 s51, s45, 0x8000
	s_add_i32 s52, s45, 0xa000
	v_mov_b32_e32 v171, v163
	global_load_lds_dwordx4 v[2:3], off
	v_lshl_add_u64 v[2:3], s[20:21], 0, v[168:169]
	s_mov_b32 m0, s51
	s_add_u32 s0, s34, 0x20080
	global_load_lds_dwordx4 v[2:3], off
	v_lshl_add_u64 v[2:3], s[20:21], 0, v[170:171]
	s_mov_b32 m0, s52
	s_addc_u32 s1, s35, 0
	global_load_lds_dwordx4 v[2:3], off
	s_add_i32 m0, s45, 0x1c000
	v_lshl_add_u64 v[2:3], s[0:1], 0, v[164:165]
	global_load_lds_dwordx4 v[2:3], off
	v_lshl_add_u64 v[2:3], s[0:1], 0, v[166:167]
	s_add_i32 m0, s45, 0x1e000
	s_mov_b32 s53, 0
	global_load_lds_dwordx4 v[2:3], off
	s_waitcnt vmcnt(6)
	v_add_u32_e32 v169, 0, v8
	s_barrier
	s_waitcnt vmcnt(0)
	.p2align 6

.LBB0_1301:
	s_ashr_i32 s0, s54, 5
	s_ashr_i32 s1, s0, 31
	s_lshl_b64 s[0:1], s[0:1], 21
	s_add_u32 s14, s4, s0
	s_addc_u32 s15, s5, s1
	s_ashr_i32 s27, s26, 31
	s_lshl_b64 s[0:1], s[26:27], 18
	s_add_u32 s14, s14, s0
	s_addc_u32 s15, s15, s1
	s_and_b64 s[0:1], s[12:13], exec
	s_cselect_b32 s27, s15, s35
	s_cselect_b32 s29, s14, s34
	v_mov_b32_e32 v173, v163
	v_mov_b32_e32 v175, v163
	s_add_u32 s31, s34, 0x100
	v_mov_b32_e32 v34, 0
	s_addc_u32 s55, s35, 0
	v_lshl_add_u64 v[176:177], s[20:21], 0, v[174:175]
	v_lshl_add_u64 v[178:179], s[20:21], 0, v[172:173]
	s_mov_b32 s56, -2
	s_mov_b64 s[36:37], 0
	v_mov_b32_e32 v35, v34
	v_mov_b32_e32 v36, v34
	v_mov_b32_e32 v37, v34
	v_mov_b32_e32 v42, v34
	v_mov_b32_e32 v43, v34
	v_mov_b32_e32 v44, v34
	v_mov_b32_e32 v45, v34
	v_mov_b32_e32 v50, v34
	v_mov_b32_e32 v51, v34
	v_mov_b32_e32 v52, v34
	v_mov_b32_e32 v53, v34
	v_mov_b32_e32 v58, v34
	v_mov_b32_e32 v59, v34
	v_mov_b32_e32 v60, v34
	v_mov_b32_e32 v61, v34
	v_mov_b32_e32 v66, v34
	v_mov_b32_e32 v67, v34
	v_mov_b32_e32 v68, v34
	v_mov_b32_e32 v69, v34
	v_mov_b32_e32 v74, v34
	v_mov_b32_e32 v75, v34
	v_mov_b32_e32 v76, v34
	v_mov_b32_e32 v77, v34
	v_mov_b32_e32 v82, v34
	v_mov_b32_e32 v83, v34
	v_mov_b32_e32 v84, v34
	v_mov_b32_e32 v85, v34
	v_mov_b32_e32 v90, v34
	v_mov_b32_e32 v91, v34
	v_mov_b32_e32 v92, v34
	v_mov_b32_e32 v93, v34
	v_mov_b32_e32 v38, v34
	v_mov_b32_e32 v39, v34
	v_mov_b32_e32 v40, v34
	v_mov_b32_e32 v41, v34
	v_mov_b32_e32 v46, v34
	v_mov_b32_e32 v47, v34
	v_mov_b32_e32 v48, v34
	v_mov_b32_e32 v49, v34
	v_mov_b32_e32 v54, v34
	v_mov_b32_e32 v55, v34
	v_mov_b32_e32 v56, v34
	v_mov_b32_e32 v57, v34
	v_mov_b32_e32 v62, v34
	v_mov_b32_e32 v63, v34
	v_mov_b32_e32 v64, v34
	v_mov_b32_e32 v65, v34
	v_mov_b32_e32 v70, v34
	v_mov_b32_e32 v71, v34
	v_mov_b32_e32 v72, v34
	v_mov_b32_e32 v73, v34
	v_mov_b32_e32 v78, v34
	v_mov_b32_e32 v79, v34
	v_mov_b32_e32 v80, v34
	v_mov_b32_e32 v81, v34
	v_mov_b32_e32 v86, v34
	v_mov_b32_e32 v87, v34
	v_mov_b32_e32 v88, v34
	v_mov_b32_e32 v89, v34
	v_mov_b32_e32 v94, v34
	v_mov_b32_e32 v95, v34
	v_mov_b32_e32 v96, v34
	v_mov_b32_e32 v97, v34
	v_mov_b32_e32 v98, v34
	v_mov_b32_e32 v99, v34
	v_mov_b32_e32 v100, v34
	v_mov_b32_e32 v101, v34
	v_mov_b32_e32 v106, v34
	v_mov_b32_e32 v107, v34
	v_mov_b32_e32 v108, v34
	v_mov_b32_e32 v109, v34
	v_mov_b32_e32 v114, v34
	v_mov_b32_e32 v115, v34
	v_mov_b32_e32 v116, v34
	v_mov_b32_e32 v117, v34
	v_mov_b32_e32 v122, v34
	v_mov_b32_e32 v123, v34
	v_mov_b32_e32 v124, v34
	v_mov_b32_e32 v125, v34
	v_mov_b32_e32 v130, v34
	v_mov_b32_e32 v131, v34
	v_mov_b32_e32 v132, v34
	v_mov_b32_e32 v133, v34
	v_mov_b32_e32 v138, v34
	v_mov_b32_e32 v139, v34
	v_mov_b32_e32 v140, v34
	v_mov_b32_e32 v141, v34
	v_mov_b32_e32 v146, v34
	v_mov_b32_e32 v147, v34
	v_mov_b32_e32 v148, v34
	v_mov_b32_e32 v149, v34
	v_mov_b32_e32 v154, v34
	v_mov_b32_e32 v155, v34
	v_mov_b32_e32 v156, v34
	v_mov_b32_e32 v157, v34
	v_mov_b32_e32 v102, v34
	v_mov_b32_e32 v103, v34
	v_mov_b32_e32 v104, v34
	v_mov_b32_e32 v105, v34
	v_mov_b32_e32 v110, v34
	v_mov_b32_e32 v111, v34
	v_mov_b32_e32 v112, v34
	v_mov_b32_e32 v113, v34
	v_mov_b32_e32 v118, v34
	v_mov_b32_e32 v119, v34
	v_mov_b32_e32 v120, v34
	v_mov_b32_e32 v121, v34
	v_mov_b32_e32 v126, v34
	v_mov_b32_e32 v127, v34
	v_mov_b32_e32 v128, v34
	v_mov_b32_e32 v129, v34
	v_mov_b32_e32 v134, v34
	v_mov_b32_e32 v135, v34
	v_mov_b32_e32 v136, v34
	v_mov_b32_e32 v137, v34
	v_mov_b32_e32 v142, v34
	v_mov_b32_e32 v143, v34
	v_mov_b32_e32 v144, v34
	v_mov_b32_e32 v145, v34
	v_mov_b32_e32 v150, v34
	v_mov_b32_e32 v151, v34
	v_mov_b32_e32 v152, v34
	v_mov_b32_e32 v153, v34
	v_mov_b32_e32 v158, v34
	v_mov_b32_e32 v159, v34
	v_mov_b32_e32 v160, v34
	v_mov_b32_e32 v161, v34
	.p2align 6

.LBB0_1361:
	s_add_u32 s12, s14, 0x12100000
	s_addc_u32 s13, s15, 0
	s_lshl_b32 s0, s0, 5
	s_mov_b64 s[14:15], 0x80
	s_and_b32 s42, s0, 0x60
	s_add_i32 m0, s17, 0x18000
	v_lshl_add_u64 v[4:5], v[4:5], 0, s[14:15]
	s_lshl_b32 s41, s1, 6
	s_lshl_b32 s9, s1, 13
	s_lshl_b32 s16, s42, 7
	s_waitcnt vmcnt(4)
	s_barrier
	global_load_lds_dwordx4 v[4:5], off
	s_add_i32 m0, s17, 0x1a000
	s_add_u32 s0, s30, 0x8000
	v_lshl_add_u64 v[2:3], v[2:3], 0, s[14:15]
	s_addc_u32 s1, s31, 0
	s_add_i32 s43, s17, 0x8000
	global_load_lds_dwordx4 v[2:3], off
	v_lshl_add_u64 v[2:3], s[0:1], 0, v[152:153]
	s_mov_b32 m0, s43
	s_add_i32 s44, s17, 0xa000
	global_load_lds_dwordx4 v[2:3], off
	v_lshl_add_u64 v[2:3], s[0:1], 0, v[148:149]
	s_add_u32 s0, s28, 0x20080
	s_mov_b32 m0, s44
	s_addc_u32 s1, s29, 0
	global_load_lds_dwordx4 v[2:3], off
	s_add_i32 m0, s17, 0x1c000
	v_lshl_add_u64 v[2:3], s[0:1], 0, v[150:151]
	global_load_lds_dwordx4 v[2:3], off
	v_lshl_add_u64 v[2:3], s[0:1], 0, v[146:147]
	s_add_i32 m0, s17, 0x1e000
	v_bfe_u32 v167, v6, 4, 2
	global_load_lds_dwordx4 v[2:3], off
	v_and_b32_e32 v166, 15, v6
	v_lshlrev_b32_e32 v2, 4, v167
	v_lshlrev_b32_e32 v3, 2, v6
	v_lshl_or_b32 v2, v166, 6, v2
	v_and_b32_e32 v3, 32, v3
	v_bitop3_b32 v4, v2, s9, v3 bitop3:0xde
	v_bitop3_b32 v168, v2, s16, v3 bitop3:0xde
	v_lshlrev_b32_e32 v2, 10, v7
	v_and_b32_e32 v2, 0xfffff800, v2
	v_lshl_add_u32 v2, v8, 7, v2
	v_and_b32_e32 v3, 1, v7
	v_lshl_or_b32 v2, v3, 6, v2
	v_lshl_add_u32 v154, v9, 1, v2
	v_lshlrev_b32_e32 v2, 10, v11
	v_and_b32_e32 v2, 0xfffff800, v2
	s_waitcnt vmcnt(6)
	v_lshl_add_u32 v2, v10, 7, v2
	v_and_b32_e32 v3, 1, v11
	v_lshl_or_b32 v2, v3, 6, v2
	s_add_i32 s45, 0, 0x10000
	s_add_i32 s46, 0, 0x14000
	s_sext_i32_i8 s48, s8
	v_mov_b32_e32 v155, v151
	v_lshl_add_u32 v156, v12, 1, v2
	v_mov_b32_e32 v157, v151
	v_mov_b64_e32 v[158:159], 0x800
	v_mov_b64_e32 v[160:161], 0x7ff
	v_add_u32_e32 v169, s45, v168
	v_add_u32_e32 v170, 0, v4
	v_mov_b32_e32 v171, 0x7f7f7f7f
	v_add_u32_e32 v172, s46, v168
	s_mov_b32 s16, 0x3d000000
	s_mov_b32 s47, 0xc3d00000
	v_mov_b32_e32 v173, 0x43d00000
	s_barrier
	.p2align 6

.LBB0_1368:
	s_ashr_i32 s21, s20, 31
	s_lshl_b64 s[0:1], s[20:21], 18
	v_cmp_lt_i64_e32 vcc, s[22:23], v[158:159]
	s_add_u32 s22, s5, s0
	s_addc_u32 s23, s6, s1
	s_and_b64 s[0:1], vcc, exec
	s_cselect_b32 s21, s23, s31
	s_cselect_b32 s49, s22, s30
	s_ashr_i32 s0, s20, 5
	s_ashr_i32 s1, s0, 31
	s_lshl_b64 s[0:1], s[0:1], 20
	s_add_u32 s24, s7, s0
	s_addc_u32 s25, s10, s1
	s_ashr_i32 s19, s18, 31
	s_lshl_b64 s[0:1], s[18:19], 18
	s_add_u32 s24, s24, s0
	s_addc_u32 s25, s25, s1
	s_and_b64 s[0:1], vcc, exec
	s_cselect_b32 s19, s25, s29
	s_cselect_b32 s50, s24, s28
	s_add_u32 s51, s28, 0x100
	s_addc_u32 s52, s29, 0
	s_add_u32 s28, s30, 0xc000
	v_mov_b32_e32 v18, 0
	s_addc_u32 s29, s31, 0
	s_mov_b32 s53, -2
	v_mov_b32_e32 v19, v18
	v_mov_b32_e32 v20, v18
	v_mov_b32_e32 v21, v18
	v_mov_b32_e32 v22, v18
	v_mov_b32_e32 v23, v18
	v_mov_b32_e32 v24, v18
	v_mov_b32_e32 v25, v18
	v_mov_b32_e32 v34, v18
	v_mov_b32_e32 v35, v18
	v_mov_b32_e32 v36, v18
	v_mov_b32_e32 v37, v18
	v_mov_b32_e32 v38, v18
	v_mov_b32_e32 v39, v18
	v_mov_b32_e32 v40, v18
	v_mov_b32_e32 v41, v18
	v_mov_b32_e32 v50, v18
	v_mov_b32_e32 v51, v18
	v_mov_b32_e32 v52, v18
	v_mov_b32_e32 v53, v18
	v_mov_b32_e32 v54, v18
	v_mov_b32_e32 v55, v18
	v_mov_b32_e32 v56, v18
	v_mov_b32_e32 v57, v18
	v_mov_b32_e32 v66, v18
	v_mov_b32_e32 v67, v18
	v_mov_b32_e32 v68, v18
	v_mov_b32_e32 v69, v18
	v_mov_b32_e32 v70, v18
	v_mov_b32_e32 v71, v18
	v_mov_b32_e32 v72, v18
	v_mov_b32_e32 v73, v18
	v_mov_b32_e32 v26, v18
	v_mov_b32_e32 v27, v18
	v_mov_b32_e32 v28, v18
	v_mov_b32_e32 v29, v18
	v_mov_b32_e32 v30, v18
	v_mov_b32_e32 v31, v18
	v_mov_b32_e32 v32, v18
	v_mov_b32_e32 v33, v18
	v_mov_b32_e32 v42, v18
	v_mov_b32_e32 v43, v18
	v_mov_b32_e32 v44, v18
	v_mov_b32_e32 v45, v18
	v_mov_b32_e32 v46, v18
	v_mov_b32_e32 v47, v18
	v_mov_b32_e32 v48, v18
	v_mov_b32_e32 v49, v18
	v_mov_b32_e32 v58, v18
	v_mov_b32_e32 v59, v18
	v_mov_b32_e32 v60, v18
	v_mov_b32_e32 v61, v18
	v_mov_b32_e32 v62, v18
	v_mov_b32_e32 v63, v18
	v_mov_b32_e32 v64, v18
	v_mov_b32_e32 v65, v18
	v_mov_b32_e32 v74, v18
	v_mov_b32_e32 v75, v18
	v_mov_b32_e32 v76, v18
	v_mov_b32_e32 v77, v18
	v_mov_b32_e32 v78, v18
	v_mov_b32_e32 v79, v18
	v_mov_b32_e32 v80, v18
	v_mov_b32_e32 v81, v18
	v_mov_b32_e32 v82, v18
	v_mov_b32_e32 v83, v18
	v_mov_b32_e32 v84, v18
	v_mov_b32_e32 v85, v18
	v_mov_b32_e32 v86, v18
	v_mov_b32_e32 v87, v18
	v_mov_b32_e32 v88, v18
	v_mov_b32_e32 v89, v18
	v_mov_b32_e32 v98, v18
	v_mov_b32_e32 v99, v18
	v_mov_b32_e32 v100, v18
	v_mov_b32_e32 v101, v18
	v_mov_b32_e32 v102, v18
	v_mov_b32_e32 v103, v18
	v_mov_b32_e32 v104, v18
	v_mov_b32_e32 v105, v18
	v_mov_b32_e32 v114, v18
	v_mov_b32_e32 v115, v18
	v_mov_b32_e32 v116, v18
	v_mov_b32_e32 v117, v18
	v_mov_b32_e32 v118, v18
	v_mov_b32_e32 v119, v18
	v_mov_b32_e32 v120, v18
	v_mov_b32_e32 v121, v18
	v_mov_b32_e32 v130, v18
	v_mov_b32_e32 v131, v18
	v_mov_b32_e32 v132, v18
	v_mov_b32_e32 v133, v18
	v_mov_b32_e32 v134, v18
	v_mov_b32_e32 v135, v18
	v_mov_b32_e32 v136, v18
	v_mov_b32_e32 v137, v18
	v_mov_b32_e32 v90, v18
	v_mov_b32_e32 v91, v18
	v_mov_b32_e32 v92, v18
	v_mov_b32_e32 v93, v18
	v_mov_b32_e32 v94, v18
	v_mov_b32_e32 v95, v18
	v_mov_b32_e32 v96, v18
	v_mov_b32_e32 v97, v18
	v_mov_b32_e32 v106, v18
	v_mov_b32_e32 v107, v18
	v_mov_b32_e32 v108, v18
	v_mov_b32_e32 v109, v18
	v_mov_b32_e32 v110, v18
	v_mov_b32_e32 v111, v18
	v_mov_b32_e32 v112, v18
	v_mov_b32_e32 v113, v18
	v_mov_b32_e32 v122, v18
	v_mov_b32_e32 v123, v18
	v_mov_b32_e32 v124, v18
	v_mov_b32_e32 v125, v18
	v_mov_b32_e32 v126, v18
	v_mov_b32_e32 v127, v18
	v_mov_b32_e32 v128, v18
	v_mov_b32_e32 v129, v18
	v_mov_b32_e32 v138, v18
	v_mov_b32_e32 v139, v18
	v_mov_b32_e32 v140, v18
	v_mov_b32_e32 v141, v18
	v_mov_b32_e32 v142, v18
	v_mov_b32_e32 v143, v18
	v_mov_b32_e32 v144, v18
	v_mov_b32_e32 v145, v18
	.p2align 6

.LBB0_1504:
	s_add_u32 s36, s14, 0x12100000
	v_bfe_u32 v147, v16, 4, 2
	s_addc_u32 s37, s15, 0
	v_and_b32_e32 v146, 15, v16
	v_lshlrev_b32_e32 v17, 4, v147
	v_lshlrev_b32_e32 v16, 2, v16
	s_mov_b64 s[14:15], 0x80
	s_and_b32 s1, s1, 3
	s_lshl_b32 s38, s0, 6
	v_lshl_or_b32 v17, v146, 6, v17
	s_lshl_b32 s0, s0, 13
	v_and_b32_e32 v16, 32, v16
	s_add_i32 m0, s10, 0x18000
	v_lshl_add_u64 v[8:9], v[8:9], 0, s[14:15]
	v_bitop3_b32 v18, v17, s0, v16 bitop3:0xde
	s_lshl_b32 s39, s1, 5
	s_lshl_b32 s0, s1, 12
	s_waitcnt vmcnt(4)
	s_barrier
	global_load_lds_dwordx4 v[8:9], off
	v_lshl_add_u64 v[6:7], v[6:7], 0, s[14:15]
	s_add_i32 m0, s10, 0x1a000
	s_add_i32 s40, s10, 0x8000
	s_add_i32 s41, s10, 0xa000
	v_bitop3_b32 v148, v17, s0, v16 bitop3:0xde
	global_load_lds_dwordx4 v[6:7], off
	v_lshl_add_u64 v[4:5], v[4:5], 0, s[14:15]
	s_mov_b32 m0, s40
	s_add_u32 s0, s26, 0x40080
	global_load_lds_dwordx4 v[4:5], off
	v_lshl_add_u64 v[2:3], v[2:3], 0, s[14:15]
	s_mov_b32 m0, s41
	s_addc_u32 s1, s27, 0
	global_load_lds_dwordx4 v[2:3], off
	s_add_i32 m0, s10, 0x1c000
	v_lshl_add_u64 v[2:3], s[0:1], 0, v[134:135]
	global_load_lds_dwordx4 v[2:3], off
	v_lshl_add_u64 v[2:3], s[0:1], 0, v[130:131]
	s_add_i32 m0, s10, 0x1e000
	s_add_i32 s42, 0, 0x10000
	global_load_lds_dwordx4 v[2:3], off
	v_lshlrev_b32_e32 v2, 14, v10
	v_and_b32_e32 v2, 0xffff8000, v2
	v_lshl_add_u32 v2, v11, 11, v2
	v_and_b32_e32 v3, 1, v10
	v_lshl_or_b32 v2, v3, 6, v2
	v_lshl_add_u32 v138, v12, 1, v2
	v_lshlrev_b32_e32 v2, 14, v14
	v_and_b32_e32 v2, 0xffff8000, v2
	s_waitcnt vmcnt(6)
	v_lshl_add_u32 v2, v13, 11, v2
	v_and_b32_e32 v3, 1, v14
	v_lshl_or_b32 v2, v3, 6, v2
	s_add_i32 s43, 0, 0x14000
	s_sext_i32_i8 s44, s12
	v_mov_b32_e32 v139, v135
	v_lshl_add_u32 v140, v15, 1, v2
	v_mov_b32_e32 v141, v135
	v_mov_b64_e32 v[142:143], 0x800
	v_mov_b64_e32 v[144:145], 0x7ff
	v_add_u32_e32 v149, s42, v148
	v_add_u32_e32 v150, 0, v18
	v_add_u32_e32 v151, s43, v148
	s_barrier
	s_branch .LBB0_1506
	.p2align 6

.LBB0_1512:
	s_ashr_i32 s21, s20, 31
	s_lshl_b64 s[0:1], s[20:21], 19
	v_cmp_lt_i64_e32 vcc, s[22:23], v[142:143]
	s_add_u32 s22, s5, s0
	s_addc_u32 s23, s6, s1
	s_and_b64 s[0:1], vcc, exec
	s_cselect_b32 s21, s23, s29
	s_cselect_b32 s45, s22, s28
	s_ashr_i32 s19, s18, 31
	s_lshl_b64 s[0:1], s[18:19], 19
	s_add_u32 s24, s7, s0
	s_addc_u32 s25, s8, s1
	s_and_b64 s[0:1], vcc, exec
	s_cselect_b32 s19, s25, s27
	s_cselect_b32 s46, s24, s26
	s_add_u32 s47, s26, 0x100
	s_addc_u32 s48, s27, 0
	s_add_u32 s26, s28, 0x40080
	v_mov_b32_e32 v2, 0
	s_addc_u32 s27, s29, 0
	s_mov_b32 s49, -2
	v_mov_b32_e32 v3, v2
	v_mov_b32_e32 v4, v2
	v_mov_b32_e32 v5, v2
	v_mov_b32_e32 v6, v2
	v_mov_b32_e32 v7, v2
	v_mov_b32_e32 v8, v2
	v_mov_b32_e32 v9, v2
	v_mov_b32_e32 v10, v2
	v_mov_b32_e32 v11, v2
	v_mov_b32_e32 v12, v2
	v_mov_b32_e32 v13, v2
	v_mov_b32_e32 v14, v2
	v_mov_b32_e32 v15, v2
	v_mov_b32_e32 v16, v2
	v_mov_b32_e32 v17, v2
	v_mov_b32_e32 v26, v2
	v_mov_b32_e32 v27, v2
	v_mov_b32_e32 v28, v2
	v_mov_b32_e32 v29, v2
	v_mov_b32_e32 v30, v2
	v_mov_b32_e32 v31, v2
	v_mov_b32_e32 v32, v2
	v_mov_b32_e32 v33, v2
	v_mov_b32_e32 v42, v2
	v_mov_b32_e32 v43, v2
	v_mov_b32_e32 v44, v2
	v_mov_b32_e32 v45, v2
	v_mov_b32_e32 v46, v2
	v_mov_b32_e32 v47, v2
	v_mov_b32_e32 v48, v2
	v_mov_b32_e32 v49, v2
	v_mov_b32_e32 v18, v2
	v_mov_b32_e32 v19, v2
	v_mov_b32_e32 v20, v2
	v_mov_b32_e32 v21, v2
	v_mov_b32_e32 v22, v2
	v_mov_b32_e32 v23, v2
	v_mov_b32_e32 v24, v2
	v_mov_b32_e32 v25, v2
	v_mov_b32_e32 v34, v2
	v_mov_b32_e32 v35, v2
	v_mov_b32_e32 v36, v2
	v_mov_b32_e32 v37, v2
	v_mov_b32_e32 v38, v2
	v_mov_b32_e32 v39, v2
	v_mov_b32_e32 v40, v2
	v_mov_b32_e32 v41, v2
	v_mov_b32_e32 v50, v2
	v_mov_b32_e32 v51, v2
	v_mov_b32_e32 v52, v2
	v_mov_b32_e32 v53, v2
	v_mov_b32_e32 v54, v2
	v_mov_b32_e32 v55, v2
	v_mov_b32_e32 v56, v2
	v_mov_b32_e32 v57, v2
	v_mov_b32_e32 v58, v2
	v_mov_b32_e32 v59, v2
	v_mov_b32_e32 v60, v2
	v_mov_b32_e32 v61, v2
	v_mov_b32_e32 v62, v2
	v_mov_b32_e32 v63, v2
	v_mov_b32_e32 v64, v2
	v_mov_b32_e32 v65, v2
	v_mov_b32_e32 v66, v2
	v_mov_b32_e32 v67, v2
	v_mov_b32_e32 v68, v2
	v_mov_b32_e32 v69, v2
	v_mov_b32_e32 v70, v2
	v_mov_b32_e32 v71, v2
	v_mov_b32_e32 v72, v2
	v_mov_b32_e32 v73, v2
	v_mov_b32_e32 v74, v2
	v_mov_b32_e32 v75, v2
	v_mov_b32_e32 v76, v2
	v_mov_b32_e32 v77, v2
	v_mov_b32_e32 v82, v2
	v_mov_b32_e32 v83, v2
	v_mov_b32_e32 v84, v2
	v_mov_b32_e32 v85, v2
	v_mov_b32_e32 v90, v2
	v_mov_b32_e32 v91, v2
	v_mov_b32_e32 v92, v2
	v_mov_b32_e32 v93, v2
	v_mov_b32_e32 v98, v2
	v_mov_b32_e32 v99, v2
	v_mov_b32_e32 v100, v2
	v_mov_b32_e32 v101, v2
	v_mov_b32_e32 v106, v2
	v_mov_b32_e32 v107, v2
	v_mov_b32_e32 v108, v2
	v_mov_b32_e32 v109, v2
	v_mov_b32_e32 v114, v2
	v_mov_b32_e32 v115, v2
	v_mov_b32_e32 v116, v2
	v_mov_b32_e32 v117, v2
	v_mov_b32_e32 v78, v2
	v_mov_b32_e32 v79, v2
	v_mov_b32_e32 v80, v2
	v_mov_b32_e32 v81, v2
	v_mov_b32_e32 v86, v2
	v_mov_b32_e32 v87, v2
	v_mov_b32_e32 v88, v2
	v_mov_b32_e32 v89, v2
	v_mov_b32_e32 v94, v2
	v_mov_b32_e32 v95, v2
	v_mov_b32_e32 v96, v2
	v_mov_b32_e32 v97, v2
	v_mov_b32_e32 v102, v2
	v_mov_b32_e32 v103, v2
	v_mov_b32_e32 v104, v2
	v_mov_b32_e32 v105, v2
	v_mov_b32_e32 v110, v2
	v_mov_b32_e32 v111, v2
	v_mov_b32_e32 v112, v2
	v_mov_b32_e32 v113, v2
	v_mov_b32_e32 v118, v2
	v_mov_b32_e32 v119, v2
	v_mov_b32_e32 v120, v2
	v_mov_b32_e32 v121, v2
	v_mov_b32_e32 v122, v2
	v_mov_b32_e32 v123, v2
	v_mov_b32_e32 v124, v2
	v_mov_b32_e32 v125, v2
	v_mov_b32_e32 v126, v2
	v_mov_b32_e32 v127, v2
	v_mov_b32_e32 v128, v2
	v_mov_b32_e32 v129, v2
	.p2align 6

.LBB0_1644:
	s_ashr_i32 s43, s42, 31
	s_lshl_b64 s[0:1], s[42:43], 19
	s_add_u32 s0, s24, s0
	s_addc_u32 s1, s25, s1
	s_lshl_b32 s41, s40, 8
	s_and_b32 s41, s41, 0x600
	v_cmp_lt_i64_e32 vcc, s[44:45], v[162:163]
	s_add_u32 s44, s0, s41
	s_addc_u32 s45, s1, 0
	s_and_b64 s[0:1], vcc, exec
	s_cselect_b32 s43, s45, s49
	s_cselect_b32 s83, s44, s48
	s_ashr_i32 s41, s40, 31
	s_lshl_b64 s[0:1], s[40:41], 17
	s_add_u32 s46, s31, s0
	s_addc_u32 s47, s35, s1
	s_and_b64 s[0:1], vcc, exec
	v_mov_b32_e32 v2, 0
	s_mov_b32 s23, s94
	s_cselect_b32 s41, s47, s15
	s_cselect_b32 s94, s46, s14
	s_mov_b32 s56, 0
	s_mov_b64 s[50:51], -1
	s_mov_b64 s[54:55], 0
	v_mov_b32_e32 v3, v2
	v_mov_b32_e32 v4, v2
	v_mov_b32_e32 v5, v2
	v_mov_b32_e32 v10, v2
	v_mov_b32_e32 v11, v2
	v_mov_b32_e32 v12, v2
	v_mov_b32_e32 v13, v2
	v_mov_b32_e32 v18, v2
	v_mov_b32_e32 v19, v2
	v_mov_b32_e32 v20, v2
	v_mov_b32_e32 v21, v2
	v_mov_b32_e32 v34, v2
	v_mov_b32_e32 v35, v2
	v_mov_b32_e32 v36, v2
	v_mov_b32_e32 v37, v2
	v_mov_b32_e32 v50, v2
	v_mov_b32_e32 v51, v2
	v_mov_b32_e32 v52, v2
	v_mov_b32_e32 v53, v2
	v_mov_b32_e32 v58, v2
	v_mov_b32_e32 v59, v2
	v_mov_b32_e32 v60, v2
	v_mov_b32_e32 v61, v2
	v_mov_b32_e32 v66, v2
	v_mov_b32_e32 v67, v2
	v_mov_b32_e32 v68, v2
	v_mov_b32_e32 v69, v2
	v_mov_b32_e32 v74, v2
	v_mov_b32_e32 v75, v2
	v_mov_b32_e32 v76, v2
	v_mov_b32_e32 v77, v2
	v_mov_b32_e32 v6, v2
	v_mov_b32_e32 v7, v2
	v_mov_b32_e32 v8, v2
	v_mov_b32_e32 v9, v2
	v_mov_b32_e32 v14, v2
	v_mov_b32_e32 v15, v2
	v_mov_b32_e32 v16, v2
	v_mov_b32_e32 v17, v2
	v_mov_b32_e32 v22, v2
	v_mov_b32_e32 v23, v2
	v_mov_b32_e32 v24, v2
	v_mov_b32_e32 v25, v2
	v_mov_b32_e32 v38, v2
	v_mov_b32_e32 v39, v2
	v_mov_b32_e32 v40, v2
	v_mov_b32_e32 v41, v2
	v_mov_b32_e32 v54, v2
	v_mov_b32_e32 v55, v2
	v_mov_b32_e32 v56, v2
	v_mov_b32_e32 v57, v2
	v_mov_b32_e32 v62, v2
	v_mov_b32_e32 v63, v2
	v_mov_b32_e32 v64, v2
	v_mov_b32_e32 v65, v2
	v_mov_b32_e32 v70, v2
	v_mov_b32_e32 v71, v2
	v_mov_b32_e32 v72, v2
	v_mov_b32_e32 v73, v2
	v_mov_b32_e32 v78, v2
	v_mov_b32_e32 v79, v2
	v_mov_b32_e32 v80, v2
	v_mov_b32_e32 v81, v2
	v_mov_b32_e32 v82, v2
	v_mov_b32_e32 v83, v2
	v_mov_b32_e32 v84, v2
	v_mov_b32_e32 v85, v2
	v_mov_b32_e32 v90, v2
	v_mov_b32_e32 v91, v2
	v_mov_b32_e32 v92, v2
	v_mov_b32_e32 v93, v2
	v_mov_b32_e32 v98, v2
	v_mov_b32_e32 v99, v2
	v_mov_b32_e32 v100, v2
	v_mov_b32_e32 v101, v2
	v_mov_b32_e32 v106, v2
	v_mov_b32_e32 v107, v2
	v_mov_b32_e32 v108, v2
	v_mov_b32_e32 v109, v2
	v_mov_b32_e32 v114, v2
	v_mov_b32_e32 v115, v2
	v_mov_b32_e32 v116, v2
	v_mov_b32_e32 v117, v2
	v_mov_b32_e32 v122, v2
	v_mov_b32_e32 v123, v2
	v_mov_b32_e32 v124, v2
	v_mov_b32_e32 v125, v2
	v_mov_b32_e32 v130, v2
	v_mov_b32_e32 v131, v2
	v_mov_b32_e32 v132, v2
	v_mov_b32_e32 v133, v2
	v_mov_b32_e32 v138, v2
	v_mov_b32_e32 v139, v2
	v_mov_b32_e32 v140, v2
	v_mov_b32_e32 v141, v2
	v_mov_b32_e32 v86, v2
	v_mov_b32_e32 v87, v2
	v_mov_b32_e32 v88, v2
	v_mov_b32_e32 v89, v2
	v_mov_b32_e32 v94, v2
	v_mov_b32_e32 v95, v2
	v_mov_b32_e32 v96, v2
	v_mov_b32_e32 v97, v2
	v_mov_b32_e32 v102, v2
	v_mov_b32_e32 v103, v2
	v_mov_b32_e32 v104, v2
	v_mov_b32_e32 v105, v2
	v_mov_b32_e32 v110, v2
	v_mov_b32_e32 v111, v2
	v_mov_b32_e32 v112, v2
	v_mov_b32_e32 v113, v2
	v_mov_b32_e32 v118, v2
	v_mov_b32_e32 v119, v2
	v_mov_b32_e32 v120, v2
	v_mov_b32_e32 v121, v2
	v_mov_b32_e32 v126, v2
	v_mov_b32_e32 v127, v2
	v_mov_b32_e32 v128, v2
	v_mov_b32_e32 v129, v2
	v_mov_b32_e32 v134, v2
	v_mov_b32_e32 v135, v2
	v_mov_b32_e32 v136, v2
	v_mov_b32_e32 v137, v2
	v_mov_b32_e32 v142, v2
	v_mov_b32_e32 v143, v2
	v_mov_b32_e32 v144, v2
	v_mov_b32_e32 v145, v2
	.p2align 6

.LBB0_1784:
	v_bfe_u32 v166, v12, 4, 2
	s_lshl_b32 s0, s0, 5
	v_and_b32_e32 v151, 15, v12
	v_lshlrev_b32_e32 v13, 4, v166
	v_lshlrev_b32_e32 v12, 2, v12
	s_and_b32 s45, s0, 0x60
	s_lshl_b32 s44, s1, 6
	v_lshl_or_b32 v13, v151, 6, v13
	s_lshl_b32 s1, s1, 13
	v_and_b32_e32 v12, 32, v12
	s_lshl_b32 s0, s45, 7
	v_bitop3_b32 v167, v13, s0, v12 bitop3:0xde
	s_add_u32 s0, s22, 0x1800080
	v_bitop3_b32 v14, v13, s1, v12 bitop3:0xde
	s_addc_u32 s1, s23, 0
	s_add_i32 m0, s8, 0x18000
	v_lshl_add_u64 v[12:13], s[0:1], 0, v[156:157]
	s_waitcnt vmcnt(4)
	s_barrier
	global_load_lds_dwordx4 v[12:13], off
	v_lshl_add_u64 v[12:13], s[0:1], 0, v[152:153]
	s_add_i32 m0, s8, 0x1a000
	s_mov_b64 s[28:29], 0x80
	s_add_i32 s48, s8, 0x8000
	s_add_i32 s49, s8, 0xa000
	global_load_lds_dwordx4 v[12:13], off
	v_lshl_add_u64 v[4:5], v[4:5], 0, s[28:29]
	s_mov_b32 m0, s48
	s_add_u32 s0, s22, 0x1840080
	global_load_lds_dwordx4 v[4:5], off
	v_lshl_add_u64 v[2:3], v[2:3], 0, s[28:29]
	s_mov_b32 m0, s49
	s_addc_u32 s1, s23, 0
	global_load_lds_dwordx4 v[2:3], off
	s_add_i32 m0, s8, 0x1c000
	v_lshl_add_u64 v[2:3], s[0:1], 0, v[156:157]
	global_load_lds_dwordx4 v[2:3], off
	v_lshl_add_u64 v[2:3], s[0:1], 0, v[152:153]
	s_add_i32 m0, s8, 0x1e000
	s_add_i32 s52, 0, 0x10000
	global_load_lds_dwordx4 v[2:3], off
	v_lshlrev_b32_e32 v2, 14, v6
	v_and_b32_e32 v2, 0xffff8000, v2
	v_lshl_add_u32 v2, v7, 11, v2
	v_and_b32_e32 v3, 1, v6
	v_lshl_or_b32 v2, v3, 6, v2
	v_lshl_add_u32 v160, v8, 1, v2
	v_lshlrev_b32_e32 v2, 14, v10
	v_and_b32_e32 v2, 0xffff8000, v2
	s_waitcnt vmcnt(6)
	v_lshl_add_u32 v2, v9, 11, v2
	v_and_b32_e32 v3, 1, v10
	v_lshl_or_b32 v2, v3, 6, v2
	v_add_u32_e32 v168, s52, v167
	s_add_i32 s54, 0, 0x14000
	s_add_i32 s52, s52, s7
	s_mov_b32 s46, 0x18000
	s_mov_b32 s47, 0x8000
	v_mov_b32_e32 v161, v157
	v_lshl_add_u32 v162, v11, 1, v2
	v_mov_b32_e32 v163, v157
	v_add_u32_e32 v169, 0, v14
	v_add_u32_e32 v170, s54, v167
	s_mov_b32 s30, 0x3fd744fd
	s_add_i32 s50, s8, 0xc000
	s_add_i32 s51, s8, 0xe000
	s_add_i32 s53, s52, 0x2000
	s_add_i32 s54, s54, s7
	s_mov_b32 s59, s2
	s_mov_b64 s[36:37], s[24:25]
	s_mov_b32 s55, 0
	s_barrier
	.p2align 6
.LBB0_1785:
	s_add_i32 s55, s55, 1
	s_mov_b64 s[0:1], s[26:27]
	s_lshr_b32 s26, s55, 2
	s_mul_i32 s26, s26, s74
	s_mov_b64 s[38:39], s[36:37]
	s_mov_b32 s37, s56
	s_add_i32 s56, s26, s2
	s_cmpk_lt_i32 s56, 0x100
	s_cselect_b64 s[40:41], -1, 0
	s_cmpk_gt_i32 s56, 0xff
	s_mov_b32 s36, s57
	s_cselect_b64 s[34:35], -1, 0
	s_and_b32 s57, s55, 3
	s_and_b64 s[26:27], s[40:41], exec
	s_cselect_b32 s26, s56, s37
	s_cselect_b32 s36, s57, s36
	s_ashr_i32 s27, s26, 31
	s_lshl_b64 s[26:27], s[26:27], 19
	s_add_u32 s26, s5, s26
	s_addc_u32 s27, s6, s27
	s_and_b64 s[42:43], s[40:41], exec
	s_cselect_b32 s60, s27, s1
	s_cselect_b32 s61, s26, s0
	s_ashr_i32 s37, s36, 31
	s_lshl_b64 s[36:37], s[36:37], 19
	s_add_u32 s36, s24, s36
	s_addc_u32 s37, s25, s37
	s_and_b64 s[40:41], s[40:41], exec
	s_cselect_b32 s62, s37, s39
	s_cselect_b32 s63, s36, s38
	s_add_u32 s64, s38, 0x100
	s_addc_u32 s65, s39, 0
	s_add_u32 s38, s0, 0x40080
	v_mov_b32_e32 v2, 0
	s_addc_u32 s39, s1, 0
	s_mov_b32 s66, -2
	v_mov_b32_e32 v3, v2
	v_mov_b32_e32 v4, v2
	v_mov_b32_e32 v5, v2
	v_mov_b32_e32 v6, v2
	v_mov_b32_e32 v7, v2
	v_mov_b32_e32 v8, v2
	v_mov_b32_e32 v9, v2
	v_mov_b32_e32 v14, v2
	v_mov_b32_e32 v15, v2
	v_mov_b32_e32 v16, v2
	v_mov_b32_e32 v17, v2
	v_mov_b32_e32 v22, v2
	v_mov_b32_e32 v23, v2
	v_mov_b32_e32 v24, v2
	v_mov_b32_e32 v25, v2
	v_mov_b32_e32 v30, v2
	v_mov_b32_e32 v31, v2
	v_mov_b32_e32 v32, v2
	v_mov_b32_e32 v33, v2
	v_mov_b32_e32 v38, v2
	v_mov_b32_e32 v39, v2
	v_mov_b32_e32 v40, v2
	v_mov_b32_e32 v41, v2
	v_mov_b32_e32 v46, v2
	v_mov_b32_e32 v47, v2
	v_mov_b32_e32 v48, v2
	v_mov_b32_e32 v49, v2
	v_mov_b32_e32 v54, v2
	v_mov_b32_e32 v55, v2
	v_mov_b32_e32 v56, v2
	v_mov_b32_e32 v57, v2
	v_mov_b32_e32 v10, v2
	v_mov_b32_e32 v11, v2
	v_mov_b32_e32 v12, v2
	v_mov_b32_e32 v13, v2
	v_mov_b32_e32 v18, v2
	v_mov_b32_e32 v19, v2
	v_mov_b32_e32 v20, v2
	v_mov_b32_e32 v21, v2
	v_mov_b32_e32 v26, v2
	v_mov_b32_e32 v27, v2
	v_mov_b32_e32 v28, v2
	v_mov_b32_e32 v29, v2
	v_mov_b32_e32 v34, v2
	v_mov_b32_e32 v35, v2
	v_mov_b32_e32 v36, v2
	v_mov_b32_e32 v37, v2
	v_mov_b32_e32 v42, v2
	v_mov_b32_e32 v43, v2
	v_mov_b32_e32 v44, v2
	v_mov_b32_e32 v45, v2
	v_mov_b32_e32 v50, v2
	v_mov_b32_e32 v51, v2
	v_mov_b32_e32 v52, v2
	v_mov_b32_e32 v53, v2
	v_mov_b32_e32 v58, v2
	v_mov_b32_e32 v59, v2
	v_mov_b32_e32 v60, v2
	v_mov_b32_e32 v61, v2
	v_mov_b32_e32 v62, v2
	v_mov_b32_e32 v63, v2
	v_mov_b32_e32 v64, v2
	v_mov_b32_e32 v65, v2
	v_mov_b32_e32 v66, v2
	v_mov_b32_e32 v67, v2
	v_mov_b32_e32 v68, v2
	v_mov_b32_e32 v69, v2
	v_mov_b32_e32 v70, v2
	v_mov_b32_e32 v71, v2
	v_mov_b32_e32 v72, v2
	v_mov_b32_e32 v73, v2
	v_mov_b32_e32 v78, v2
	v_mov_b32_e32 v79, v2
	v_mov_b32_e32 v80, v2
	v_mov_b32_e32 v81, v2
	v_mov_b32_e32 v86, v2
	v_mov_b32_e32 v87, v2
	v_mov_b32_e32 v88, v2
	v_mov_b32_e32 v89, v2
	v_mov_b32_e32 v94, v2
	v_mov_b32_e32 v95, v2
	v_mov_b32_e32 v96, v2
	v_mov_b32_e32 v97, v2
	v_mov_b32_e32 v102, v2
	v_mov_b32_e32 v103, v2
	v_mov_b32_e32 v104, v2
	v_mov_b32_e32 v105, v2
	v_mov_b32_e32 v106, v2
	v_mov_b32_e32 v107, v2
	v_mov_b32_e32 v108, v2
	v_mov_b32_e32 v109, v2
	v_mov_b32_e32 v114, v2
	v_mov_b32_e32 v115, v2
	v_mov_b32_e32 v116, v2
	v_mov_b32_e32 v117, v2
	v_mov_b32_e32 v74, v2
	v_mov_b32_e32 v75, v2
	v_mov_b32_e32 v76, v2
	v_mov_b32_e32 v77, v2
	v_mov_b32_e32 v82, v2
	v_mov_b32_e32 v83, v2
	v_mov_b32_e32 v84, v2
	v_mov_b32_e32 v85, v2
	v_mov_b32_e32 v90, v2
	v_mov_b32_e32 v91, v2
	v_mov_b32_e32 v92, v2
	v_mov_b32_e32 v93, v2
	v_mov_b32_e32 v98, v2
	v_mov_b32_e32 v99, v2
	v_mov_b32_e32 v100, v2
	v_mov_b32_e32 v101, v2
	v_mov_b32_e32 v110, v2
	v_mov_b32_e32 v111, v2
	v_mov_b32_e32 v112, v2
	v_mov_b32_e32 v113, v2
	v_mov_b32_e32 v118, v2
	v_mov_b32_e32 v119, v2
	v_mov_b32_e32 v120, v2
	v_mov_b32_e32 v121, v2
	v_mov_b32_e32 v122, v2
	v_mov_b32_e32 v123, v2
	v_mov_b32_e32 v124, v2
	v_mov_b32_e32 v125, v2
	v_mov_b32_e32 v126, v2
	v_mov_b32_e32 v127, v2
	v_mov_b32_e32 v128, v2
	v_mov_b32_e32 v129, v2
	.p2align 6

.LBB0_2029:
	v_bfe_u32 v196, v2, 4, 2
	v_and_b32_e32 v195, 15, v2
	v_lshlrev_b32_e32 v3, 4, v196
	v_lshlrev_b32_e32 v2, 2, v2
	v_lshl_or_b32 v3, v195, 6, v3
	s_lshl_b32 s0, s12, 13
	v_and_b32_e32 v2, 32, v2
	v_bitop3_b32 v8, v3, s0, v2 bitop3:0xde
	s_lshl_b32 s0, s1, 5
	v_mov_b32_e32 v165, v163
	s_and_b32 s50, s0, 0x60
	v_lshl_add_u64 v[4:5], s[36:37], 0, v[164:165]
	v_mov_b32_e32 v167, v163
	s_lshl_b32 s0, s50, 7
	v_lshl_add_u64 v[6:7], s[36:37], 0, v[166:167]
	v_bitop3_b32 v197, v3, s0, v2 bitop3:0xde
	s_add_i32 m0, s45, 0x18000
	v_lshl_add_u64 v[2:3], v[4:5], 0, s[24:25]
	v_mov_b32_e32 v169, v163
	s_lshl_b32 s49, s12, 6
	s_waitcnt vmcnt(4)
	s_barrier
	global_load_lds_dwordx4 v[2:3], off
	v_lshl_add_u64 v[2:3], v[6:7], 0, s[24:25]
	s_add_i32 m0, s45, 0x1a000
	s_add_i32 s51, s45, 0x8000
	s_add_i32 s52, s45, 0xa000
	v_mov_b32_e32 v171, v163
	global_load_lds_dwordx4 v[2:3], off
	v_lshl_add_u64 v[2:3], s[22:23], 0, v[168:169]
	s_mov_b32 m0, s51
	s_add_u32 s0, s36, 0x20080
	global_load_lds_dwordx4 v[2:3], off
	v_lshl_add_u64 v[2:3], s[22:23], 0, v[170:171]
	s_mov_b32 m0, s52
	s_addc_u32 s1, s37, 0
	global_load_lds_dwordx4 v[2:3], off
	s_add_i32 m0, s45, 0x1c000
	v_lshl_add_u64 v[2:3], s[0:1], 0, v[164:165]
	global_load_lds_dwordx4 v[2:3], off
	v_lshl_add_u64 v[2:3], s[0:1], 0, v[166:167]
	s_add_i32 m0, s45, 0x1e000
	s_mov_b32 s53, 0
	global_load_lds_dwordx4 v[2:3], off
	s_waitcnt vmcnt(6)
	v_add_u32_e32 v169, 0, v8
	s_barrier
	.p2align 6

.LBB0_2040:
	s_ashr_i32 s0, s54, 5
	s_ashr_i32 s1, s0, 31
	s_lshl_b64 s[0:1], s[0:1], 21
	s_add_u32 s16, s4, s0
	s_addc_u32 s17, s5, s1
	s_ashr_i32 s29, s28, 31
	s_lshl_b64 s[0:1], s[28:29], 18
	s_add_u32 s16, s16, s0
	s_addc_u32 s17, s17, s1
	s_and_b64 s[0:1], s[14:15], exec
	s_cselect_b32 s29, s17, s37
	s_cselect_b32 s31, s16, s36
	v_mov_b32_e32 v173, v163
	v_mov_b32_e32 v175, v163
	s_add_u32 s35, s36, 0x100
	v_mov_b32_e32 v34, 0
	s_addc_u32 s55, s37, 0
	v_lshl_add_u64 v[176:177], s[22:23], 0, v[174:175]
	v_lshl_add_u64 v[178:179], s[22:23], 0, v[172:173]
	s_mov_b32 s56, -2
	s_mov_b64 s[38:39], 0
	v_mov_b32_e32 v35, v34
	v_mov_b32_e32 v36, v34
	v_mov_b32_e32 v37, v34
	v_mov_b32_e32 v42, v34
	v_mov_b32_e32 v43, v34
	v_mov_b32_e32 v44, v34
	v_mov_b32_e32 v45, v34
	v_mov_b32_e32 v50, v34
	v_mov_b32_e32 v51, v34
	v_mov_b32_e32 v52, v34
	v_mov_b32_e32 v53, v34
	v_mov_b32_e32 v58, v34
	v_mov_b32_e32 v59, v34
	v_mov_b32_e32 v60, v34
	v_mov_b32_e32 v61, v34
	v_mov_b32_e32 v66, v34
	v_mov_b32_e32 v67, v34
	v_mov_b32_e32 v68, v34
	v_mov_b32_e32 v69, v34
	v_mov_b32_e32 v74, v34
	v_mov_b32_e32 v75, v34
	v_mov_b32_e32 v76, v34
	v_mov_b32_e32 v77, v34
	v_mov_b32_e32 v82, v34
	v_mov_b32_e32 v83, v34
	v_mov_b32_e32 v84, v34
	v_mov_b32_e32 v85, v34
	v_mov_b32_e32 v90, v34
	v_mov_b32_e32 v91, v34
	v_mov_b32_e32 v92, v34
	v_mov_b32_e32 v93, v34
	v_mov_b32_e32 v38, v34
	v_mov_b32_e32 v39, v34
	v_mov_b32_e32 v40, v34
	v_mov_b32_e32 v41, v34
	v_mov_b32_e32 v46, v34
	v_mov_b32_e32 v47, v34
	v_mov_b32_e32 v48, v34
	v_mov_b32_e32 v49, v34
	v_mov_b32_e32 v54, v34
	v_mov_b32_e32 v55, v34
	v_mov_b32_e32 v56, v34
	v_mov_b32_e32 v57, v34
	v_mov_b32_e32 v62, v34
	v_mov_b32_e32 v63, v34
	v_mov_b32_e32 v64, v34
	v_mov_b32_e32 v65, v34
	v_mov_b32_e32 v70, v34
	v_mov_b32_e32 v71, v34
	v_mov_b32_e32 v72, v34
	v_mov_b32_e32 v73, v34
	v_mov_b32_e32 v78, v34
	v_mov_b32_e32 v79, v34
	v_mov_b32_e32 v80, v34
	v_mov_b32_e32 v81, v34
	v_mov_b32_e32 v86, v34
	v_mov_b32_e32 v87, v34
	v_mov_b32_e32 v88, v34
	v_mov_b32_e32 v89, v34
	v_mov_b32_e32 v94, v34
	v_mov_b32_e32 v95, v34
	v_mov_b32_e32 v96, v34
	v_mov_b32_e32 v97, v34
	v_mov_b32_e32 v98, v34
	v_mov_b32_e32 v99, v34
	v_mov_b32_e32 v100, v34
	v_mov_b32_e32 v101, v34
	v_mov_b32_e32 v106, v34
	v_mov_b32_e32 v107, v34
	v_mov_b32_e32 v108, v34
	v_mov_b32_e32 v109, v34
	v_mov_b32_e32 v114, v34
	v_mov_b32_e32 v115, v34
	v_mov_b32_e32 v116, v34
	v_mov_b32_e32 v117, v34
	v_mov_b32_e32 v122, v34
	v_mov_b32_e32 v123, v34
	v_mov_b32_e32 v124, v34
	v_mov_b32_e32 v125, v34
	v_mov_b32_e32 v130, v34
	v_mov_b32_e32 v131, v34
	v_mov_b32_e32 v132, v34
	v_mov_b32_e32 v133, v34
	v_mov_b32_e32 v138, v34
	v_mov_b32_e32 v139, v34
	v_mov_b32_e32 v140, v34
	v_mov_b32_e32 v141, v34
	v_mov_b32_e32 v146, v34
	v_mov_b32_e32 v147, v34
	v_mov_b32_e32 v148, v34
	v_mov_b32_e32 v149, v34
	v_mov_b32_e32 v154, v34
	v_mov_b32_e32 v155, v34
	v_mov_b32_e32 v156, v34
	v_mov_b32_e32 v157, v34
	v_mov_b32_e32 v102, v34
	v_mov_b32_e32 v103, v34
	v_mov_b32_e32 v104, v34
	v_mov_b32_e32 v105, v34
	v_mov_b32_e32 v110, v34
	v_mov_b32_e32 v111, v34
	v_mov_b32_e32 v112, v34
	v_mov_b32_e32 v113, v34
	v_mov_b32_e32 v118, v34
	v_mov_b32_e32 v119, v34
	v_mov_b32_e32 v120, v34
	v_mov_b32_e32 v121, v34
	v_mov_b32_e32 v126, v34
	v_mov_b32_e32 v127, v34
	v_mov_b32_e32 v128, v34
	v_mov_b32_e32 v129, v34
	v_mov_b32_e32 v134, v34
	v_mov_b32_e32 v135, v34
	v_mov_b32_e32 v136, v34
	v_mov_b32_e32 v137, v34
	v_mov_b32_e32 v142, v34
	v_mov_b32_e32 v143, v34
	v_mov_b32_e32 v144, v34
	v_mov_b32_e32 v145, v34
	v_mov_b32_e32 v150, v34
	v_mov_b32_e32 v151, v34
	v_mov_b32_e32 v152, v34
	v_mov_b32_e32 v153, v34
	v_mov_b32_e32 v158, v34
	v_mov_b32_e32 v159, v34
	v_mov_b32_e32 v160, v34
	v_mov_b32_e32 v161, v34
	.p2align 6

.LBB0_2100:
	s_add_u32 s14, s14, 0x12100000
	s_addc_u32 s15, s15, 0
	s_lshl_b32 s0, s0, 5
	s_mov_b64 s[16:17], 0x80
	s_and_b32 s42, s0, 0x60
	s_add_i32 m0, s10, 0x18000
	v_lshl_add_u64 v[4:5], v[4:5], 0, s[16:17]
	s_lshl_b32 s41, s1, 6
	s_lshl_b32 s13, s1, 13
	s_lshl_b32 s18, s42, 7
	s_waitcnt vmcnt(4)
	s_barrier
	global_load_lds_dwordx4 v[4:5], off
	s_add_i32 m0, s10, 0x1a000
	s_add_u32 s0, s34, 0x8000
	v_lshl_add_u64 v[2:3], v[2:3], 0, s[16:17]
	s_addc_u32 s1, s35, 0
	s_add_i32 s43, s10, 0x8000
	global_load_lds_dwordx4 v[2:3], off
	v_lshl_add_u64 v[2:3], s[0:1], 0, v[152:153]
	s_mov_b32 m0, s43
	s_add_i32 s44, s10, 0xa000
	global_load_lds_dwordx4 v[2:3], off
	v_lshl_add_u64 v[2:3], s[0:1], 0, v[148:149]
	s_add_u32 s0, s30, 0x20080
	s_mov_b32 m0, s44
	s_addc_u32 s1, s31, 0
	global_load_lds_dwordx4 v[2:3], off
	s_add_i32 m0, s10, 0x1c000
	v_lshl_add_u64 v[2:3], s[0:1], 0, v[150:151]
	global_load_lds_dwordx4 v[2:3], off
	v_lshl_add_u64 v[2:3], s[0:1], 0, v[146:147]
	s_add_i32 m0, s10, 0x1e000
	v_bfe_u32 v167, v6, 4, 2
	global_load_lds_dwordx4 v[2:3], off
	v_and_b32_e32 v166, 15, v6
	v_lshlrev_b32_e32 v2, 4, v167
	v_lshlrev_b32_e32 v3, 2, v6
	v_lshl_or_b32 v2, v166, 6, v2
	v_and_b32_e32 v3, 32, v3
	v_bitop3_b32 v4, v2, s13, v3 bitop3:0xde
	v_bitop3_b32 v168, v2, s18, v3 bitop3:0xde
	v_lshlrev_b32_e32 v2, 10, v7
	v_and_b32_e32 v2, 0xfffff800, v2
	v_lshl_add_u32 v2, v8, 7, v2
	v_and_b32_e32 v3, 1, v7
	v_lshl_or_b32 v2, v3, 6, v2
	v_lshl_add_u32 v154, v9, 1, v2
	v_lshlrev_b32_e32 v2, 10, v11
	v_and_b32_e32 v2, 0xfffff800, v2
	s_waitcnt vmcnt(6)
	v_lshl_add_u32 v2, v10, 7, v2
	v_and_b32_e32 v3, 1, v11
	v_lshl_or_b32 v2, v3, 6, v2
	s_add_i32 s45, 0, 0x10000
	s_add_i32 s46, 0, 0x14000
	s_sext_i32_i8 s48, s12
	v_mov_b32_e32 v155, v151
	v_lshl_add_u32 v156, v12, 1, v2
	v_mov_b32_e32 v157, v151
	v_mov_b64_e32 v[158:159], 0x800
	v_mov_b64_e32 v[160:161], 0x7ff
	v_add_u32_e32 v169, s45, v168
	v_add_u32_e32 v170, 0, v4
	v_mov_b32_e32 v171, 0x7f7f7f7f
	v_add_u32_e32 v172, s46, v168
	s_mov_b32 s18, 0x3d000000
	s_mov_b32 s47, 0xc3d00000
	v_mov_b32_e32 v173, 0x43d00000
	s_barrier
	.p2align 6

.LBB0_2107:
	s_ashr_i32 s23, s22, 31
	s_lshl_b64 s[0:1], s[22:23], 18
	v_cmp_lt_i64_e32 vcc, s[24:25], v[158:159]
	s_add_u32 s24, s5, s0
	s_addc_u32 s25, s6, s1
	s_and_b64 s[0:1], vcc, exec
	s_cselect_b32 s23, s25, s35
	s_cselect_b32 s49, s24, s34
	s_ashr_i32 s0, s22, 5
	s_ashr_i32 s1, s0, 31
	s_lshl_b64 s[0:1], s[0:1], 20
	s_add_u32 s26, s7, s0
	s_addc_u32 s27, s8, s1
	s_ashr_i32 s21, s20, 31
	s_lshl_b64 s[0:1], s[20:21], 18
	s_add_u32 s26, s26, s0
	s_addc_u32 s27, s27, s1
	s_and_b64 s[0:1], vcc, exec
	s_cselect_b32 s21, s27, s31
	s_cselect_b32 s50, s26, s30
	s_add_u32 s51, s30, 0x100
	s_addc_u32 s52, s31, 0
	s_add_u32 s30, s34, 0xc000
	v_mov_b32_e32 v18, 0
	s_addc_u32 s31, s35, 0
	s_mov_b32 s53, -2
	v_mov_b32_e32 v19, v18
	v_mov_b32_e32 v20, v18
	v_mov_b32_e32 v21, v18
	v_mov_b32_e32 v22, v18
	v_mov_b32_e32 v23, v18
	v_mov_b32_e32 v24, v18
	v_mov_b32_e32 v25, v18
	v_mov_b32_e32 v34, v18
	v_mov_b32_e32 v35, v18
	v_mov_b32_e32 v36, v18
	v_mov_b32_e32 v37, v18
	v_mov_b32_e32 v38, v18
	v_mov_b32_e32 v39, v18
	v_mov_b32_e32 v40, v18
	v_mov_b32_e32 v41, v18
	v_mov_b32_e32 v50, v18
	v_mov_b32_e32 v51, v18
	v_mov_b32_e32 v52, v18
	v_mov_b32_e32 v53, v18
	v_mov_b32_e32 v54, v18
	v_mov_b32_e32 v55, v18
	v_mov_b32_e32 v56, v18
	v_mov_b32_e32 v57, v18
	v_mov_b32_e32 v66, v18
	v_mov_b32_e32 v67, v18
	v_mov_b32_e32 v68, v18
	v_mov_b32_e32 v69, v18
	v_mov_b32_e32 v70, v18
	v_mov_b32_e32 v71, v18
	v_mov_b32_e32 v72, v18
	v_mov_b32_e32 v73, v18
	v_mov_b32_e32 v26, v18
	v_mov_b32_e32 v27, v18
	v_mov_b32_e32 v28, v18
	v_mov_b32_e32 v29, v18
	v_mov_b32_e32 v30, v18
	v_mov_b32_e32 v31, v18
	v_mov_b32_e32 v32, v18
	v_mov_b32_e32 v33, v18
	v_mov_b32_e32 v42, v18
	v_mov_b32_e32 v43, v18
	v_mov_b32_e32 v44, v18
	v_mov_b32_e32 v45, v18
	v_mov_b32_e32 v46, v18
	v_mov_b32_e32 v47, v18
	v_mov_b32_e32 v48, v18
	v_mov_b32_e32 v49, v18
	v_mov_b32_e32 v58, v18
	v_mov_b32_e32 v59, v18
	v_mov_b32_e32 v60, v18
	v_mov_b32_e32 v61, v18
	v_mov_b32_e32 v62, v18
	v_mov_b32_e32 v63, v18
	v_mov_b32_e32 v64, v18
	v_mov_b32_e32 v65, v18
	v_mov_b32_e32 v74, v18
	v_mov_b32_e32 v75, v18
	v_mov_b32_e32 v76, v18
	v_mov_b32_e32 v77, v18
	v_mov_b32_e32 v78, v18
	v_mov_b32_e32 v79, v18
	v_mov_b32_e32 v80, v18
	v_mov_b32_e32 v81, v18
	v_mov_b32_e32 v82, v18
	v_mov_b32_e32 v83, v18
	v_mov_b32_e32 v84, v18
	v_mov_b32_e32 v85, v18
	v_mov_b32_e32 v86, v18
	v_mov_b32_e32 v87, v18
	v_mov_b32_e32 v88, v18
	v_mov_b32_e32 v89, v18
	v_mov_b32_e32 v98, v18
	v_mov_b32_e32 v99, v18
	v_mov_b32_e32 v100, v18
	v_mov_b32_e32 v101, v18
	v_mov_b32_e32 v102, v18
	v_mov_b32_e32 v103, v18
	v_mov_b32_e32 v104, v18
	v_mov_b32_e32 v105, v18
	v_mov_b32_e32 v114, v18
	v_mov_b32_e32 v115, v18
	v_mov_b32_e32 v116, v18
	v_mov_b32_e32 v117, v18
	v_mov_b32_e32 v118, v18
	v_mov_b32_e32 v119, v18
	v_mov_b32_e32 v120, v18
	v_mov_b32_e32 v121, v18
	v_mov_b32_e32 v130, v18
	v_mov_b32_e32 v131, v18
	v_mov_b32_e32 v132, v18
	v_mov_b32_e32 v133, v18
	v_mov_b32_e32 v134, v18
	v_mov_b32_e32 v135, v18
	v_mov_b32_e32 v136, v18
	v_mov_b32_e32 v137, v18
	v_mov_b32_e32 v90, v18
	v_mov_b32_e32 v91, v18
	v_mov_b32_e32 v92, v18
	v_mov_b32_e32 v93, v18
	v_mov_b32_e32 v94, v18
	v_mov_b32_e32 v95, v18
	v_mov_b32_e32 v96, v18
	v_mov_b32_e32 v97, v18
	v_mov_b32_e32 v106, v18
	v_mov_b32_e32 v107, v18
	v_mov_b32_e32 v108, v18
	v_mov_b32_e32 v109, v18
	v_mov_b32_e32 v110, v18
	v_mov_b32_e32 v111, v18
	v_mov_b32_e32 v112, v18
	v_mov_b32_e32 v113, v18
	v_mov_b32_e32 v122, v18
	v_mov_b32_e32 v123, v18
	v_mov_b32_e32 v124, v18
	v_mov_b32_e32 v125, v18
	v_mov_b32_e32 v126, v18
	v_mov_b32_e32 v127, v18
	v_mov_b32_e32 v128, v18
	v_mov_b32_e32 v129, v18
	v_mov_b32_e32 v138, v18
	v_mov_b32_e32 v139, v18
	v_mov_b32_e32 v140, v18
	v_mov_b32_e32 v141, v18
	v_mov_b32_e32 v142, v18
	v_mov_b32_e32 v143, v18
	v_mov_b32_e32 v144, v18
	v_mov_b32_e32 v145, v18
	.p2align 6

.LBB0_2243:
	v_bfe_u32 v144, v12, 4, 2
	v_and_b32_e32 v143, 15, v12
	v_lshlrev_b32_e32 v13, 4, v144
	v_lshlrev_b32_e32 v12, 2, v12
	s_and_b32 s1, s1, 3
	s_lshl_b32 s40, s0, 6
	v_lshl_or_b32 v13, v143, 6, v13
	s_lshl_b32 s0, s0, 13
	v_and_b32_e32 v12, 32, v12
	v_bitop3_b32 v14, v13, s0, v12 bitop3:0xde
	s_lshl_b32 s41, s1, 5
	s_lshl_b32 s0, s1, 12
	v_bitop3_b32 v145, v13, s0, v12 bitop3:0xde
	s_add_u32 s0, s22, 0x1a00080
	s_addc_u32 s1, s23, 0
	s_add_i32 m0, s9, 0x18000
	v_lshl_add_u64 v[12:13], s[0:1], 0, v[134:135]
	s_waitcnt vmcnt(4)
	s_barrier
	global_load_lds_dwordx4 v[12:13], off
	v_lshl_add_u64 v[12:13], s[0:1], 0, v[130:131]
	s_add_i32 m0, s9, 0x1a000
	s_mov_b64 s[24:25], 0x80
	s_add_i32 s42, s9, 0x8000
	s_add_i32 s43, s9, 0xa000
	global_load_lds_dwordx4 v[12:13], off
	v_lshl_add_u64 v[4:5], v[4:5], 0, s[24:25]
	s_mov_b32 m0, s42
	s_add_u32 s0, s22, 0x1a40080
	global_load_lds_dwordx4 v[4:5], off
	v_lshl_add_u64 v[2:3], v[2:3], 0, s[24:25]
	s_mov_b32 m0, s43
	s_addc_u32 s1, s23, 0
	global_load_lds_dwordx4 v[2:3], off
	s_add_i32 m0, s9, 0x1c000
	v_lshl_add_u64 v[2:3], s[0:1], 0, v[134:135]
	global_load_lds_dwordx4 v[2:3], off
	v_lshl_add_u64 v[2:3], s[0:1], 0, v[130:131]
	s_add_i32 m0, s9, 0x1e000
	s_add_i32 s48, 0, 0x10000
	global_load_lds_dwordx4 v[2:3], off
	v_lshlrev_b32_e32 v2, 14, v6
	v_and_b32_e32 v2, 0xffff8000, v2
	v_lshl_add_u32 v2, v7, 11, v2
	v_and_b32_e32 v3, 1, v6
	v_lshl_or_b32 v2, v3, 6, v2
	v_lshl_add_u32 v138, v8, 1, v2
	v_lshlrev_b32_e32 v2, 14, v10
	v_and_b32_e32 v2, 0xffff8000, v2
	s_waitcnt vmcnt(6)
	v_lshl_add_u32 v2, v9, 11, v2
	v_and_b32_e32 v3, 1, v10
	v_lshl_or_b32 v2, v3, 6, v2
	v_add_u32_e32 v146, s48, v145
	s_add_i32 s44, 0, 0x14000
	s_add_i32 s48, s48, s8
	v_mov_b32_e32 v139, v135
	v_lshl_add_u32 v140, v11, 1, v2
	v_mov_b32_e32 v141, v135
	v_add_u32_e32 v147, 0, v14
	v_add_u32_e32 v148, s44, v145
	s_movk_i32 s45, 0x600
	s_add_i32 s46, s9, 0xc000
	s_add_i32 s47, s9, 0xe000
	s_add_i32 s49, s48, 0x2000
	s_mov_b32 s54, s2
	s_mov_b64 s[28:29], s[10:11]
	s_mov_b32 s50, 0
	s_barrier
	.p2align 6
.LBB0_2244:
	s_add_i32 s50, s50, 1
	s_mov_b64 s[0:1], s[16:17]
	s_mul_hi_u32 s16, s50, 0xaaaaaaab
	s_lshr_b32 s16, s16, 1
	s_mul_i32 s17, s16, s74
	s_mov_b64 s[30:31], s[28:29]
	s_mov_b32 s29, s51
	s_add_i32 s51, s17, s2
	s_cmpk_lt_i32 s51, 0x100
	s_cselect_b64 s[34:35], -1, 0
	s_cmpk_gt_i32 s51, 0xff
	s_mul_i32 s16, s16, 3
	s_mov_b32 s28, s52
	s_cselect_b64 s[26:27], -1, 0
	s_sub_i32 s52, s50, s16
	s_and_b64 s[16:17], s[34:35], exec
	s_cselect_b32 s16, s51, s29
	s_cselect_b32 s28, s52, s28
	s_ashr_i32 s17, s16, 31
	s_lshl_b64 s[16:17], s[16:17], 19
	s_add_u32 s16, s6, s16
	s_addc_u32 s17, s7, s17
	s_and_b64 s[36:37], s[34:35], exec
	s_cselect_b32 s55, s17, s1
	s_cselect_b32 s56, s16, s0
	s_ashr_i32 s29, s28, 31
	s_lshl_b64 s[28:29], s[28:29], 19
	s_add_u32 s28, s10, s28
	s_addc_u32 s29, s11, s29
	s_and_b64 s[34:35], s[34:35], exec
	s_cselect_b32 s57, s29, s31
	s_cselect_b32 s58, s28, s30
	s_add_u32 s59, s30, 0x100
	s_addc_u32 s60, s31, 0
	s_add_u32 s30, s0, 0x40080
	v_mov_b32_e32 v2, 0
	s_addc_u32 s31, s1, 0
	s_mov_b32 s61, -2
	v_mov_b32_e32 v3, v2
	v_mov_b32_e32 v4, v2
	v_mov_b32_e32 v5, v2
	v_mov_b32_e32 v6, v2
	v_mov_b32_e32 v7, v2
	v_mov_b32_e32 v8, v2
	v_mov_b32_e32 v9, v2
	v_mov_b32_e32 v10, v2
	v_mov_b32_e32 v11, v2
	v_mov_b32_e32 v12, v2
	v_mov_b32_e32 v13, v2
	v_mov_b32_e32 v14, v2
	v_mov_b32_e32 v15, v2
	v_mov_b32_e32 v16, v2
	v_mov_b32_e32 v17, v2
	v_mov_b32_e32 v26, v2
	v_mov_b32_e32 v27, v2
	v_mov_b32_e32 v28, v2
	v_mov_b32_e32 v29, v2
	v_mov_b32_e32 v30, v2
	v_mov_b32_e32 v31, v2
	v_mov_b32_e32 v32, v2
	v_mov_b32_e32 v33, v2
	v_mov_b32_e32 v42, v2
	v_mov_b32_e32 v43, v2
	v_mov_b32_e32 v44, v2
	v_mov_b32_e32 v45, v2
	v_mov_b32_e32 v46, v2
	v_mov_b32_e32 v47, v2
	v_mov_b32_e32 v48, v2
	v_mov_b32_e32 v49, v2
	v_mov_b32_e32 v18, v2
	v_mov_b32_e32 v19, v2
	v_mov_b32_e32 v20, v2
	v_mov_b32_e32 v21, v2
	v_mov_b32_e32 v22, v2
	v_mov_b32_e32 v23, v2
	v_mov_b32_e32 v24, v2
	v_mov_b32_e32 v25, v2
	v_mov_b32_e32 v34, v2
	v_mov_b32_e32 v35, v2
	v_mov_b32_e32 v36, v2
	v_mov_b32_e32 v37, v2
	v_mov_b32_e32 v38, v2
	v_mov_b32_e32 v39, v2
	v_mov_b32_e32 v40, v2
	v_mov_b32_e32 v41, v2
	v_mov_b32_e32 v50, v2
	v_mov_b32_e32 v51, v2
	v_mov_b32_e32 v52, v2
	v_mov_b32_e32 v53, v2
	v_mov_b32_e32 v54, v2
	v_mov_b32_e32 v55, v2
	v_mov_b32_e32 v56, v2
	v_mov_b32_e32 v57, v2
	v_mov_b32_e32 v58, v2
	v_mov_b32_e32 v59, v2
	v_mov_b32_e32 v60, v2
	v_mov_b32_e32 v61, v2
	v_mov_b32_e32 v62, v2
	v_mov_b32_e32 v63, v2
	v_mov_b32_e32 v64, v2
	v_mov_b32_e32 v65, v2
	v_mov_b32_e32 v66, v2
	v_mov_b32_e32 v67, v2
	v_mov_b32_e32 v68, v2
	v_mov_b32_e32 v69, v2
	v_mov_b32_e32 v70, v2
	v_mov_b32_e32 v71, v2
	v_mov_b32_e32 v72, v2
	v_mov_b32_e32 v73, v2
	v_mov_b32_e32 v74, v2
	v_mov_b32_e32 v75, v2
	v_mov_b32_e32 v76, v2
	v_mov_b32_e32 v77, v2
	v_mov_b32_e32 v78, v2
	v_mov_b32_e32 v79, v2
	v_mov_b32_e32 v80, v2
	v_mov_b32_e32 v81, v2
	v_mov_b32_e32 v90, v2
	v_mov_b32_e32 v91, v2
	v_mov_b32_e32 v92, v2
	v_mov_b32_e32 v93, v2
	v_mov_b32_e32 v94, v2
	v_mov_b32_e32 v95, v2
	v_mov_b32_e32 v96, v2
	v_mov_b32_e32 v97, v2
	v_mov_b32_e32 v106, v2
	v_mov_b32_e32 v107, v2
	v_mov_b32_e32 v108, v2
	v_mov_b32_e32 v109, v2
	v_mov_b32_e32 v110, v2
	v_mov_b32_e32 v111, v2
	v_mov_b32_e32 v112, v2
	v_mov_b32_e32 v113, v2
	v_mov_b32_e32 v82, v2
	v_mov_b32_e32 v83, v2
	v_mov_b32_e32 v84, v2
	v_mov_b32_e32 v85, v2
	v_mov_b32_e32 v86, v2
	v_mov_b32_e32 v87, v2
	v_mov_b32_e32 v88, v2
	v_mov_b32_e32 v89, v2
	v_mov_b32_e32 v98, v2
	v_mov_b32_e32 v99, v2
	v_mov_b32_e32 v100, v2
	v_mov_b32_e32 v101, v2
	v_mov_b32_e32 v102, v2
	v_mov_b32_e32 v103, v2
	v_mov_b32_e32 v104, v2
	v_mov_b32_e32 v105, v2
	v_mov_b32_e32 v114, v2
	v_mov_b32_e32 v115, v2
	v_mov_b32_e32 v116, v2
	v_mov_b32_e32 v117, v2
	v_mov_b32_e32 v118, v2
	v_mov_b32_e32 v119, v2
	v_mov_b32_e32 v120, v2
	v_mov_b32_e32 v121, v2
	v_mov_b32_e32 v122, v2
	v_mov_b32_e32 v123, v2
	v_mov_b32_e32 v124, v2
	v_mov_b32_e32 v125, v2
	v_mov_b32_e32 v126, v2
	v_mov_b32_e32 v127, v2
	v_mov_b32_e32 v128, v2
	v_mov_b32_e32 v129, v2
	.p2align 6

.LBB0_2316:
	s_add_u32 s22, s18, 0x12100000
	s_addc_u32 s23, s19, 0
	s_add_u32 s24, s18, 0x2100000
	s_addc_u32 s25, s19, 0
	v_bfe_u32 v163, v18, 4, 2
	s_add_u32 s26, s18, 0x2900000
	v_and_b32_e32 v162, 15, v18
	v_lshlrev_b32_e32 v19, 4, v163
	v_lshlrev_b32_e32 v18, 2, v18
	s_mov_b64 s[30:31], 0x80
	s_addc_u32 s27, s19, 0
	s_and_b32 s14, s10, 3
	s_lshl_b32 s45, s0, 6
	v_lshl_or_b32 v19, v162, 6, v19
	s_lshl_b32 s0, s0, 13
	v_and_b32_e32 v18, 32, v18
	s_add_i32 m0, s17, 0x18000
	v_lshl_add_u64 v[8:9], v[8:9], 0, s[30:31]
	v_bitop3_b32 v20, v19, s0, v18 bitop3:0xde
	s_lshl_b32 s28, s14, 5
	s_lshl_b32 s0, s14, 12
	s_waitcnt vmcnt(4)
	s_barrier
	global_load_lds_dwordx4 v[8:9], off
	v_lshl_add_u64 v[6:7], v[6:7], 0, s[30:31]
	s_add_i32 m0, s17, 0x1a000
	s_add_i32 s46, s17, 0x8000
	s_add_i32 s47, s17, 0xa000
	global_load_lds_dwordx4 v[6:7], off
	v_lshl_add_u64 v[4:5], v[4:5], 0, s[30:31]
	s_mov_b32 m0, s46
	s_add_u32 s12, s36, 0x18080
	global_load_lds_dwordx4 v[4:5], off
	v_lshl_add_u64 v[2:3], v[2:3], 0, s[30:31]
	s_mov_b32 m0, s47
	s_addc_u32 s13, s37, 0
	global_load_lds_dwordx4 v[2:3], off
	s_add_i32 m0, s17, 0x1c000
	v_lshl_add_u64 v[2:3], s[12:13], 0, v[142:143]
	global_load_lds_dwordx4 v[2:3], off
	v_lshl_add_u64 v[2:3], s[12:13], 0, v[138:139]
	s_add_i32 m0, s17, 0x1e000
	v_bitop3_b32 v164, v19, s0, v18 bitop3:0xde
	global_load_lds_dwordx4 v[2:3], off
	v_lshrrev_b32_e32 v3, 1, v10
	v_mul_lo_u32 v2, v11, s1
	s_movk_i32 s0, 0x1800
	v_mad_u64_u32 v[2:3], s[12:13], v3, s0, v[2:3]
	v_or_b32_e32 v2, v2, v12
	s_sext_i32_i8 s57, s11
	s_mov_b64 s[10:11], 0x18080
	v_add_lshl_u32 v2, v2, v13, 1
	v_mov_b32_e32 v3, v143
	v_lshl_add_u64 v[146:147], v[2:3], 0, s[10:11]
	v_lshrrev_b32_e32 v3, 1, v15
	v_mul_lo_u32 v2, v14, s1
	v_mad_u64_u32 v[2:3], s[0:1], v3, s0, v[2:3]
	s_waitcnt vmcnt(6)
	v_or_b32_e32 v2, v2, v16
	v_add_lshl_u32 v2, v2, v17, 1
	v_mov_b32_e32 v3, v143
	s_add_i32 s49, 0, 0x10000
	s_add_i32 s50, 0, 0x14000
	s_or_b32 s48, s14, -16
	s_mov_b32 s29, s21
	v_lshl_add_u64 v[148:149], v[2:3], 0, s[10:11]
	v_mov_b64_e32 v[150:151], 0x600
	v_mov_b64_e32 v[152:153], 0x5ff
	v_add_u32_e32 v165, s49, v164
	v_add_u32_e32 v166, 0, v20
	v_add_u32_e32 v167, s50, v164
	s_mov_b32 s51, 0xc3d00000
	s_movk_i32 s52, 0x600
	v_mov_b32_e32 v168, 0x43d00000
	s_mov_b32 s53, 0
	s_barrier
	s_branch .LBB0_2318
	.p2align 6

.LBB0_2324:
	s_add_u32 s20, s36, 0x100
	v_mov_b32_e32 v2, 0
	s_addc_u32 s58, s37, 0
	s_mov_b32 s59, -2
	v_mov_b32_e32 v3, v2
	v_mov_b32_e32 v4, v2
	v_mov_b32_e32 v5, v2
	v_mov_b32_e32 v6, v2
	v_mov_b32_e32 v7, v2
	v_mov_b32_e32 v8, v2
	v_mov_b32_e32 v9, v2
	v_mov_b32_e32 v14, v2
	v_mov_b32_e32 v15, v2
	v_mov_b32_e32 v16, v2
	v_mov_b32_e32 v17, v2
	v_mov_b32_e32 v22, v2
	v_mov_b32_e32 v23, v2
	v_mov_b32_e32 v24, v2
	v_mov_b32_e32 v25, v2
	v_mov_b32_e32 v30, v2
	v_mov_b32_e32 v31, v2
	v_mov_b32_e32 v32, v2
	v_mov_b32_e32 v33, v2
	v_mov_b32_e32 v38, v2
	v_mov_b32_e32 v39, v2
	v_mov_b32_e32 v40, v2
	v_mov_b32_e32 v41, v2
	v_mov_b32_e32 v46, v2
	v_mov_b32_e32 v47, v2
	v_mov_b32_e32 v48, v2
	v_mov_b32_e32 v49, v2
	v_mov_b32_e32 v54, v2
	v_mov_b32_e32 v55, v2
	v_mov_b32_e32 v56, v2
	v_mov_b32_e32 v57, v2
	v_mov_b32_e32 v10, v2
	v_mov_b32_e32 v11, v2
	v_mov_b32_e32 v12, v2
	v_mov_b32_e32 v13, v2
	v_mov_b32_e32 v18, v2
	v_mov_b32_e32 v19, v2
	v_mov_b32_e32 v20, v2
	v_mov_b32_e32 v21, v2
	v_mov_b32_e32 v26, v2
	v_mov_b32_e32 v27, v2
	v_mov_b32_e32 v28, v2
	v_mov_b32_e32 v29, v2
	v_mov_b32_e32 v34, v2
	v_mov_b32_e32 v35, v2
	v_mov_b32_e32 v36, v2
	v_mov_b32_e32 v37, v2
	v_mov_b32_e32 v42, v2
	v_mov_b32_e32 v43, v2
	v_mov_b32_e32 v44, v2
	v_mov_b32_e32 v45, v2
	v_mov_b32_e32 v50, v2
	v_mov_b32_e32 v51, v2
	v_mov_b32_e32 v52, v2
	v_mov_b32_e32 v53, v2
	v_mov_b32_e32 v58, v2
	v_mov_b32_e32 v59, v2
	v_mov_b32_e32 v60, v2
	v_mov_b32_e32 v61, v2
	v_mov_b32_e32 v62, v2
	v_mov_b32_e32 v63, v2
	v_mov_b32_e32 v64, v2
	v_mov_b32_e32 v65, v2
	v_mov_b32_e32 v66, v2
	v_mov_b32_e32 v67, v2
	v_mov_b32_e32 v68, v2
	v_mov_b32_e32 v69, v2
	v_mov_b32_e32 v70, v2
	v_mov_b32_e32 v71, v2
	v_mov_b32_e32 v72, v2
	v_mov_b32_e32 v73, v2
	v_mov_b32_e32 v78, v2
	v_mov_b32_e32 v79, v2
	v_mov_b32_e32 v80, v2
	v_mov_b32_e32 v81, v2
	v_mov_b32_e32 v86, v2
	v_mov_b32_e32 v87, v2
	v_mov_b32_e32 v88, v2
	v_mov_b32_e32 v89, v2
	v_mov_b32_e32 v94, v2
	v_mov_b32_e32 v95, v2
	v_mov_b32_e32 v96, v2
	v_mov_b32_e32 v97, v2
	v_mov_b32_e32 v102, v2
	v_mov_b32_e32 v103, v2
	v_mov_b32_e32 v104, v2
	v_mov_b32_e32 v105, v2
	v_mov_b32_e32 v110, v2
	v_mov_b32_e32 v111, v2
	v_mov_b32_e32 v112, v2
	v_mov_b32_e32 v113, v2
	v_mov_b32_e32 v118, v2
	v_mov_b32_e32 v119, v2
	v_mov_b32_e32 v120, v2
	v_mov_b32_e32 v121, v2
	v_mov_b32_e32 v74, v2
	v_mov_b32_e32 v75, v2
	v_mov_b32_e32 v76, v2
	v_mov_b32_e32 v77, v2
	v_mov_b32_e32 v82, v2
	v_mov_b32_e32 v83, v2
	v_mov_b32_e32 v84, v2
	v_mov_b32_e32 v85, v2
	v_mov_b32_e32 v90, v2
	v_mov_b32_e32 v91, v2
	v_mov_b32_e32 v92, v2
	v_mov_b32_e32 v93, v2
	v_mov_b32_e32 v98, v2
	v_mov_b32_e32 v99, v2
	v_mov_b32_e32 v100, v2
	v_mov_b32_e32 v101, v2
	v_mov_b32_e32 v106, v2
	v_mov_b32_e32 v107, v2
	v_mov_b32_e32 v108, v2
	v_mov_b32_e32 v109, v2
	v_mov_b32_e32 v114, v2
	v_mov_b32_e32 v115, v2
	v_mov_b32_e32 v116, v2
	v_mov_b32_e32 v117, v2
	v_mov_b32_e32 v122, v2
	v_mov_b32_e32 v123, v2
	v_mov_b32_e32 v124, v2
	v_mov_b32_e32 v125, v2
	v_mov_b32_e32 v126, v2
	v_mov_b32_e32 v127, v2
	v_mov_b32_e32 v128, v2
	v_mov_b32_e32 v129, v2
	.p2align 6

.LBB0_2336:
	s_add_u32 s12, s18, 0x1e100000
	s_addc_u32 s13, s19, 0
	s_add_u32 s14, s18, 0x2a100000
	s_addc_u32 s15, s19, 0
	v_bfe_u32 v145, v10, 4, 2
	s_lshl_b32 s0, s0, 5
	s_mov_b64 s[16:17], 0x80
	v_and_b32_e32 v144, 15, v10
	v_lshlrev_b32_e32 v11, 4, v145
	v_lshlrev_b32_e32 v10, 2, v10
	s_and_b32 s54, s0, 0x60
	s_add_i32 m0, s27, 0x18000
	v_lshl_add_u64 v[8:9], v[8:9], 0, s[16:17]
	s_lshl_b32 s53, s1, 6
	v_lshl_or_b32 v11, v144, 6, v11
	s_lshl_b32 s1, s1, 13
	v_and_b32_e32 v10, 32, v10
	s_lshl_b32 s0, s54, 7
	s_waitcnt vmcnt(4)
	s_barrier
	global_load_lds_dwordx4 v[8:9], off
	v_lshl_add_u64 v[6:7], v[6:7], 0, s[16:17]
	s_add_i32 m0, s27, 0x1a000
	s_add_i32 s56, s27, 0x8000
	s_add_i32 s57, s27, 0xa000
	v_bitop3_b32 v146, v11, s0, v10 bitop3:0xde
	global_load_lds_dwordx4 v[6:7], off
	v_lshl_add_u64 v[4:5], v[4:5], 0, s[16:17]
	s_mov_b32 m0, s56
	s_add_u32 s0, s28, 0x10080
	v_bitop3_b32 v12, v11, s1, v10 bitop3:0xde
	global_load_lds_dwordx4 v[4:5], off
	v_lshl_add_u64 v[2:3], v[2:3], 0, s[16:17]
	s_mov_b32 m0, s57
	s_addc_u32 s1, s29, 0
	global_load_lds_dwordx4 v[2:3], off
	s_add_i32 m0, s27, 0x1c000
	v_lshl_add_u64 v[2:3], s[0:1], 0, v[134:135]
	global_load_lds_dwordx4 v[2:3], off
	v_lshl_add_u64 v[2:3], s[0:1], 0, v[130:131]
	s_add_i32 m0, s27, 0x1e000
	s_add_i32 s58, 0, 0x10000
	global_load_lds_dwordx4 v[2:3], off
	s_waitcnt vmcnt(6)
	s_add_i32 s59, 0, 0x14000
	s_sext_i32_i8 s55, s10
	v_mov_b64_e32 v[138:139], 0x800
	v_mov_b64_e32 v[140:141], 0x7ff
	v_add_u32_e32 v147, s58, v146
	v_add_u32_e32 v148, 0, v12
	v_add_u32_e32 v149, s59, v146
	s_movk_i32 s60, 0x7ff
	s_mov_b32 s61, 0xc3d00000
	v_mov_b32_e32 v150, 0x43d00000
	s_barrier
	.p2align 6

.LBB0_2343:
	s_ashr_i32 s21, s20, 31
	s_lshl_b64 s[0:1], s[20:21], 17
	v_cmp_lt_i64_e32 vcc, s[22:23], v[138:139]
	s_add_u32 s22, s6, s0
	s_addc_u32 s23, s4, s1
	s_and_b64 s[0:1], vcc, exec
	s_cselect_b32 s21, s23, s31
	s_cselect_b32 s62, s22, s30
	s_ashr_i32 s19, s18, 31
	s_lshl_b64 s[0:1], s[18:19], 17
	s_add_u32 s24, s7, s0
	s_addc_u32 s25, s8, s1
	s_and_b64 s[0:1], vcc, exec
	v_mov_b32_e32 v2, 0
	s_cselect_b32 s19, s25, s29
	s_cselect_b32 s63, s24, s28
	s_mov_b32 s38, 0
	s_mov_b64 s[34:35], -1
	s_mov_b64 s[36:37], 0
	v_mov_b32_e32 v3, v2
	v_mov_b32_e32 v4, v2
	v_mov_b32_e32 v5, v2
	v_mov_b32_e32 v6, v2
	v_mov_b32_e32 v7, v2
	v_mov_b32_e32 v8, v2
	v_mov_b32_e32 v9, v2
	v_mov_b32_e32 v18, v2
	v_mov_b32_e32 v19, v2
	v_mov_b32_e32 v20, v2
	v_mov_b32_e32 v21, v2
	v_mov_b32_e32 v22, v2
	v_mov_b32_e32 v23, v2
	v_mov_b32_e32 v24, v2
	v_mov_b32_e32 v25, v2
	v_mov_b32_e32 v34, v2
	v_mov_b32_e32 v35, v2
	v_mov_b32_e32 v36, v2
	v_mov_b32_e32 v37, v2
	v_mov_b32_e32 v38, v2
	v_mov_b32_e32 v39, v2
	v_mov_b32_e32 v40, v2
	v_mov_b32_e32 v41, v2
	v_mov_b32_e32 v50, v2
	v_mov_b32_e32 v51, v2
	v_mov_b32_e32 v52, v2
	v_mov_b32_e32 v53, v2
	v_mov_b32_e32 v54, v2
	v_mov_b32_e32 v55, v2
	v_mov_b32_e32 v56, v2
	v_mov_b32_e32 v57, v2
	v_mov_b32_e32 v10, v2
	v_mov_b32_e32 v11, v2
	v_mov_b32_e32 v12, v2
	v_mov_b32_e32 v13, v2
	v_mov_b32_e32 v14, v2
	v_mov_b32_e32 v15, v2
	v_mov_b32_e32 v16, v2
	v_mov_b32_e32 v17, v2
	v_mov_b32_e32 v26, v2
	v_mov_b32_e32 v27, v2
	v_mov_b32_e32 v28, v2
	v_mov_b32_e32 v29, v2
	v_mov_b32_e32 v30, v2
	v_mov_b32_e32 v31, v2
	v_mov_b32_e32 v32, v2
	v_mov_b32_e32 v33, v2
	v_mov_b32_e32 v42, v2
	v_mov_b32_e32 v43, v2
	v_mov_b32_e32 v44, v2
	v_mov_b32_e32 v45, v2
	v_mov_b32_e32 v46, v2
	v_mov_b32_e32 v47, v2
	v_mov_b32_e32 v48, v2
	v_mov_b32_e32 v49, v2
	v_mov_b32_e32 v58, v2
	v_mov_b32_e32 v59, v2
	v_mov_b32_e32 v60, v2
	v_mov_b32_e32 v61, v2
	v_mov_b32_e32 v62, v2
	v_mov_b32_e32 v63, v2
	v_mov_b32_e32 v64, v2
	v_mov_b32_e32 v65, v2
	v_mov_b32_e32 v66, v2
	v_mov_b32_e32 v67, v2
	v_mov_b32_e32 v68, v2
	v_mov_b32_e32 v69, v2
	v_mov_b32_e32 v70, v2
	v_mov_b32_e32 v71, v2
	v_mov_b32_e32 v72, v2
	v_mov_b32_e32 v73, v2
	v_mov_b32_e32 v82, v2
	v_mov_b32_e32 v83, v2
	v_mov_b32_e32 v84, v2
	v_mov_b32_e32 v85, v2
	v_mov_b32_e32 v86, v2
	v_mov_b32_e32 v87, v2
	v_mov_b32_e32 v88, v2
	v_mov_b32_e32 v89, v2
	v_mov_b32_e32 v98, v2
	v_mov_b32_e32 v99, v2
	v_mov_b32_e32 v100, v2
	v_mov_b32_e32 v101, v2
	v_mov_b32_e32 v102, v2
	v_mov_b32_e32 v103, v2
	v_mov_b32_e32 v104, v2
	v_mov_b32_e32 v105, v2
	v_mov_b32_e32 v114, v2
	v_mov_b32_e32 v115, v2
	v_mov_b32_e32 v116, v2
	v_mov_b32_e32 v117, v2
	v_mov_b32_e32 v118, v2
	v_mov_b32_e32 v119, v2
	v_mov_b32_e32 v120, v2
	v_mov_b32_e32 v121, v2
	v_mov_b32_e32 v74, v2
	v_mov_b32_e32 v75, v2
	v_mov_b32_e32 v76, v2
	v_mov_b32_e32 v77, v2
	v_mov_b32_e32 v78, v2
	v_mov_b32_e32 v79, v2
	v_mov_b32_e32 v80, v2
	v_mov_b32_e32 v81, v2
	v_mov_b32_e32 v90, v2
	v_mov_b32_e32 v91, v2
	v_mov_b32_e32 v92, v2
	v_mov_b32_e32 v93, v2
	v_mov_b32_e32 v94, v2
	v_mov_b32_e32 v95, v2
	v_mov_b32_e32 v96, v2
	v_mov_b32_e32 v97, v2
	v_mov_b32_e32 v106, v2
	v_mov_b32_e32 v107, v2
	v_mov_b32_e32 v108, v2
	v_mov_b32_e32 v109, v2
	v_mov_b32_e32 v110, v2
	v_mov_b32_e32 v111, v2
	v_mov_b32_e32 v112, v2
	v_mov_b32_e32 v113, v2
	v_mov_b32_e32 v122, v2
	v_mov_b32_e32 v123, v2
	v_mov_b32_e32 v124, v2
	v_mov_b32_e32 v125, v2
	v_mov_b32_e32 v126, v2
	v_mov_b32_e32 v127, v2
	v_mov_b32_e32 v128, v2
	v_mov_b32_e32 v129, v2
	.p2align 6

.LBB0_2402:
	s_or_b64 exec, exec, s[10:11]
	s_waitcnt lgkmcnt(0)
	s_barrier
	s_load_dwordx4 s[36:39], s[84:85], 0x100
	s_and_b32 s0, s74, 7
	s_ashr_i32 s4, s2, 3
	s_cmp_eq_u32 s0, 0
	s_cselect_b64 s[10:11], -1, 0
	s_and_b64 s[0:1], s[10:11], exec
	s_movk_i32 s6, 0x100
	s_cselect_b32 s5, s4, s2
	s_cselect_b32 s7, s6, 0x800
	s_lshl_b32 s4, s2, 8
	s_mov_b32 s16, 0
	s_cmp_lt_i32 s5, s7
	v_mov_b32_e32 v2, v0
	s_waitcnt lgkmcnt(0)
	s_mov_b32 s0, s37
	s_cbranch_scc0 .LBB0_2438
	s_ashr_i32 s9, s74, 3
	s_and_b32 s8, s4, 0x700
	s_and_b64 s[0:1], s[10:11], exec
	s_cselect_b32 s8, s8, 0
	s_cselect_b32 s9, s9, s74
	s_add_u32 s35, s38, 0x12100000
	s_addc_u32 s48, s39, 0
	s_add_u32 s49, s38, 0x1e100000
	s_addc_u32 s50, s39, 0
	s_add_u32 s51, s38, 0x2a100000
	s_addc_u32 s52, s39, 0
	s_add_u32 s53, s38, 0x32100000
	s_addc_u32 s54, s39, 0
	s_movk_i32 s55, 0xc0
	v_mov_b32_e32 v3, 0
	s_mov_b32 s56, 0x2aaaaaab
	s_add_i32 s57, 0, 0x8000
	s_mov_b32 s17, s16
	s_mov_b32 s18, s16
	s_mov_b32 s19, s16
	s_mov_b32 s20, s16
	s_mov_b32 s21, s16
	s_mov_b32 s22, s16
	s_mov_b32 s23, s16
	s_mov_b32 s24, s16
	s_mov_b32 s25, s16
	s_mov_b32 s26, s16
	s_mov_b32 s27, s16
	s_mov_b32 s28, s16
	s_mov_b32 s29, s16
	s_mov_b32 s30, s16
	s_mov_b32 s31, s16
	v_mov_b32_e32 v170, 0x7f7f7f7f
	s_mov_b32 s58, 0x42ddb3d8
	s_mov_b32 s34, 0x3dd53b94
	s_movk_i32 s59, 0x4000
	s_mov_b64 s[36:37], 0x6000
	v_mov_b32_e32 v171, 0xf149f2ca
	s_branch .LBB0_2405
	.p2align 6

.LBB0_2411:
	s_or_b64 exec, exec, s[44:45]
	s_waitcnt vmcnt(0)
	s_waitcnt vmcnt(0) lgkmcnt(0)
	ds_write_b128 v179, v[36:39] offset:16384
	ds_write_b128 v180, v[40:43] offset:16384
	ds_write_b128 v183, v[44:47] offset:45056
	v_lshlrev_b32_e32 v36, 4, v59
	s_and_saveexec_b64 s[10:11], s[12:13]
	v_add3_u32 v37, 0, v58, v36
	ds_write_b128 v37, v[124:127] offset:45056
	s_or_b64 exec, exec, s[10:11]
	v_max_f32_e32 v40, 0xf149f2ca, v2
	v_cndmask_b32_e32 v185, v40, v171, vcc
	v_and_b32_e32 v37, 63, v54
	v_mul_f32_e32 v2, 0xbdd53b94, v185
	v_fmamk_f32 v20, v20, 0x3dd53b94, v2
	v_fmamk_f32 v21, v21, 0x3dd53b94, v2
	v_fmamk_f32 v22, v22, 0x3dd53b94, v2
	v_fmamk_f32 v23, v23, 0x3dd53b94, v2
	v_fmamk_f32 v24, v24, 0x3dd53b94, v2
	v_fmamk_f32 v25, v25, 0x3dd53b94, v2
	v_fmamk_f32 v26, v26, 0x3dd53b94, v2
	v_fmamk_f32 v27, v27, 0x3dd53b94, v2
	v_fmamk_f32 v28, v28, 0x3dd53b94, v2
	v_fmamk_f32 v29, v29, 0x3dd53b94, v2
	v_fmamk_f32 v30, v30, 0x3dd53b94, v2
	v_fmamk_f32 v31, v31, 0x3dd53b94, v2
	v_fmamk_f32 v32, v32, 0x3dd53b94, v2
	v_fmamk_f32 v33, v33, 0x3dd53b94, v2
	v_fmamk_f32 v34, v34, 0x3dd53b94, v2
	v_fmamk_f32 v35, v35, 0x3dd53b94, v2
	v_pk_fma_f32 v[132:133], v[18:19], s[34:35], v[2:3] op_sel_hi:[1,0,0]
	v_pk_fma_f32 v[138:139], v[16:17], s[34:35], v[2:3] op_sel_hi:[1,0,0]
	v_pk_fma_f32 v[142:143], v[14:15], s[34:35], v[2:3] op_sel_hi:[1,0,0]
	v_pk_fma_f32 v[128:129], v[12:13], s[34:35], v[2:3] op_sel_hi:[1,0,0]
	v_pk_fma_f32 v[130:131], v[10:11], s[34:35], v[2:3] op_sel_hi:[1,0,0]
	v_pk_fma_f32 v[134:135], v[8:9], s[34:35], v[2:3] op_sel_hi:[1,0,0]
	v_pk_fma_f32 v[136:137], v[6:7], s[34:35], v[2:3] op_sel_hi:[1,0,0]
	v_pk_fma_f32 v[140:141], v[4:5], s[34:35], v[2:3] op_sel_hi:[1,0,0]
	v_and_b32_e32 v2, 0x3fffffc0, v54
	v_lshlrev_b32_e32 v4, 4, v37
	v_exp_f32_e32 v150, v20
	v_sub_f32_e32 v20, 0xf149f2ca, v40
	v_lshl_add_u32 v157, v2, 2, 0
	v_lshlrev_b32_e32 v2, 3, v37
	v_and_b32_e32 v4, 0xc0, v4
	v_lshlrev_b32_e32 v5, 1, v37
	v_mad_i64_i32 v[38:39], s[0:1], v57, s55, 0
	v_mul_f32_e32 v20, 0x3dd53b94, v20
	v_and_or_b32 v4, v2, 24, v4
	v_and_b32_e32 v5, 32, v5
	v_and_b32_e32 v2, 0x100, v2
	v_exp_f32_e32 v20, v20
	v_or3_b32 v2, v4, v5, v2
	s_add_i32 s0, 0, 0x4000
	v_mov_b64_e32 v[4:5], s[14:15]
	v_add_u32_e32 v176, s0, v2
	v_mad_i64_i32 v[4:5], s[0:1], v55, s55, v[4:5]
	v_add_u32_e32 v178, 0, v2
	v_lshl_add_u64 v[158:159], v[4:5], 0, v[52:53]
	v_lshl_add_u64 v[4:5], s[14:15], 0, v[38:39]
	v_and_b32_e32 v2, 15, v54
	v_exp_f32_e32 v151, v21
	v_exp_f32_e32 v152, v22
	v_exp_f32_e32 v153, v23
	v_exp_f32_e32 v154, v24
	v_exp_f32_e32 v165, v25
	v_exp_f32_e32 v166, v26
	v_exp_f32_e32 v168, v27
	v_exp_f32_e32 v145, v28
	v_exp_f32_e32 v146, v29
	v_exp_f32_e32 v147, v30
	v_exp_f32_e32 v148, v31
	v_exp_f32_e32 v149, v32
	v_exp_f32_e32 v155, v33
	v_exp_f32_e32 v164, v34
	v_exp_f32_e32 v167, v35
	v_add_u32_e32 v18, 0, v58
	v_lshl_add_u64 v[160:161], v[4:5], 0, v[50:51]
	v_lshl_add_u64 v[4:5], s[42:43], 0, v[48:49]
	v_lshlrev_b32_e32 v2, 4, v2
	v_mov_b32_e32 v16, v3
	v_mov_b32_e32 v17, v3
	v_and_b32_e32 v156, 0xffffffe0, v56
	v_cndmask_b32_e64 v184, v20, 1.0, vcc
	v_cmp_gt_u32_e64 s[10:11], 32, v37
	v_lshl_add_u64 v[162:163], v[4:5], 0, v[2:3]
	v_mov_b32_e32 v2, v3
	v_mov_b32_e32 v4, v3
	v_mov_b32_e32 v5, v3
	v_mov_b32_e32 v6, v3
	v_mov_b32_e32 v7, v3
	v_mov_b32_e32 v8, v3
	v_mov_b32_e32 v9, v3
	v_mov_b32_e32 v10, v3
	v_mov_b32_e32 v11, v3
	v_mov_b32_e32 v12, v3
	v_mov_b32_e32 v13, v3
	v_mov_b32_e32 v14, v3
	v_mov_b32_e32 v15, v3
	v_add_u32_e32 v186, v18, v36
	v_mov_b64_e32 v[66:67], v[16:17]
	v_mov_b64_e32 v[50:51], v[16:17]
	v_mov_b64_e32 v[34:35], v[16:17]
	v_mov_b64_e32 v[64:65], v[14:15]
	v_mov_b64_e32 v[62:63], v[12:13]
	v_mov_b64_e32 v[60:61], v[10:11]
	v_mov_b64_e32 v[58:59], v[8:9]
	v_mov_b64_e32 v[56:57], v[6:7]
	v_mov_b64_e32 v[54:55], v[4:5]
	v_mov_b64_e32 v[52:53], v[2:3]
	v_mov_b64_e32 v[48:49], v[14:15]
	v_mov_b64_e32 v[46:47], v[12:13]
	v_mov_b64_e32 v[44:45], v[10:11]
	v_mov_b64_e32 v[42:43], v[8:9]
	v_mov_b64_e32 v[40:41], v[6:7]
	v_mov_b64_e32 v[38:39], v[4:5]
	v_mov_b64_e32 v[36:37], v[2:3]
	v_mov_b64_e32 v[32:33], v[14:15]
	v_mov_b64_e32 v[30:31], v[12:13]
	v_mov_b64_e32 v[28:29], v[10:11]
	v_mov_b64_e32 v[26:27], v[8:9]
	v_mov_b64_e32 v[24:25], v[6:7]
	v_mov_b64_e32 v[22:23], v[4:5]
	v_mov_b64_e32 v[20:21], v[2:3]
	v_mov_b64_e32 v[18:19], v[16:17]
	v_lshl_add_u32 v175, v172, 2, v157
	v_lshlrev_b32_e32 v174, 4, v173
	v_mov_b32_e32 v177, 0
	s_mov_b32 s44, -1
	v_mov_b64_e32 v[16:17], v[14:15]
	v_mov_b64_e32 v[14:15], v[12:13]
	v_mov_b64_e32 v[12:13], v[10:11]
	v_mov_b64_e32 v[10:11], v[8:9]
	v_mov_b64_e32 v[8:9], v[6:7]
	v_mov_b64_e32 v[6:7], v[4:5]
	v_mov_b64_e32 v[4:5], v[2:3]
	s_waitcnt lgkmcnt(0)
	s_barrier
	.p2align 6

.LBB0_2493:
	v_bfe_u32 v166, v12, 4, 2
	s_lshl_b32 s0, s0, 5
	v_and_b32_e32 v151, 15, v12
	v_lshlrev_b32_e32 v13, 4, v166
	v_lshlrev_b32_e32 v12, 2, v12
	s_and_b32 s46, s0, 0x60
	s_lshl_b32 s45, s1, 6
	v_lshl_or_b32 v13, v151, 6, v13
	s_lshl_b32 s1, s1, 13
	v_and_b32_e32 v12, 32, v12
	s_lshl_b32 s0, s46, 7
	v_bitop3_b32 v167, v13, s0, v12 bitop3:0xde
	s_add_u32 s0, s18, 0x1da0080
	v_bitop3_b32 v14, v13, s1, v12 bitop3:0xde
	s_addc_u32 s1, s19, 0
	s_add_i32 m0, s9, 0x18000
	v_lshl_add_u64 v[12:13], s[0:1], 0, v[156:157]
	s_waitcnt vmcnt(4)
	s_barrier
	global_load_lds_dwordx4 v[12:13], off
	v_lshl_add_u64 v[12:13], s[0:1], 0, v[152:153]
	s_add_i32 m0, s9, 0x1a000
	s_mov_b64 s[26:27], 0x80
	s_add_i32 s49, s9, 0x8000
	s_add_i32 s50, s9, 0xa000
	global_load_lds_dwordx4 v[12:13], off
	v_lshl_add_u64 v[4:5], v[4:5], 0, s[26:27]
	s_mov_b32 m0, s49
	s_add_u32 s0, s18, 0x1de0080
	global_load_lds_dwordx4 v[4:5], off
	v_lshl_add_u64 v[2:3], v[2:3], 0, s[26:27]
	s_mov_b32 m0, s50
	s_addc_u32 s1, s19, 0
	global_load_lds_dwordx4 v[2:3], off
	s_add_i32 m0, s9, 0x1c000
	v_lshl_add_u64 v[2:3], s[0:1], 0, v[156:157]
	global_load_lds_dwordx4 v[2:3], off
	v_lshl_add_u64 v[2:3], s[0:1], 0, v[152:153]
	s_add_i32 m0, s9, 0x1e000
	s_add_i32 s53, 0, 0x10000
	global_load_lds_dwordx4 v[2:3], off
	v_lshlrev_b32_e32 v2, 14, v6
	v_and_b32_e32 v2, 0xffff8000, v2
	v_lshl_add_u32 v2, v7, 11, v2
	v_and_b32_e32 v3, 1, v6
	v_lshl_or_b32 v2, v3, 6, v2
	v_lshl_add_u32 v160, v8, 1, v2
	v_lshlrev_b32_e32 v2, 14, v10
	v_and_b32_e32 v2, 0xffff8000, v2
	s_waitcnt vmcnt(6)
	v_lshl_add_u32 v2, v9, 11, v2
	v_and_b32_e32 v3, 1, v10
	v_lshl_or_b32 v2, v3, 6, v2
	v_add_u32_e32 v168, s53, v167
	s_add_i32 s55, 0, 0x14000
	s_add_i32 s53, s53, s8
	s_mov_b32 s47, 0x18000
	s_mov_b32 s48, 0x8000
	v_mov_b32_e32 v161, v157
	v_lshl_add_u32 v162, v11, 1, v2
	v_mov_b32_e32 v163, v157
	v_add_u32_e32 v169, 0, v14
	v_add_u32_e32 v170, s55, v167
	s_mov_b32 s28, 0x3fd744fd
	s_add_i32 s51, s9, 0xc000
	s_add_i32 s52, s9, 0xe000
	s_add_i32 s54, s53, 0x2000
	s_add_i32 s55, s55, s8
	s_mov_b32 s60, s2
	s_mov_b64 s[34:35], s[22:23]
	s_mov_b32 s56, 0
	s_barrier
	.p2align 6
.LBB0_2494:
	s_add_i32 s56, s56, 1
	s_mov_b64 s[0:1], s[24:25]
	s_lshr_b32 s24, s56, 2
	s_mul_i32 s24, s24, s74
	s_mov_b64 s[36:37], s[34:35]
	s_mov_b32 s35, s57
	s_add_i32 s57, s24, s2
	s_cmpk_lt_i32 s57, 0x100
	s_cselect_b64 s[38:39], -1, 0
	s_cmpk_gt_i32 s57, 0xff
	s_mov_b32 s34, s58
	s_cselect_b64 s[30:31], -1, 0
	s_and_b32 s58, s56, 3
	s_and_b64 s[24:25], s[38:39], exec
	s_cselect_b32 s24, s57, s35
	s_cselect_b32 s34, s58, s34
	s_ashr_i32 s25, s24, 31
	s_lshl_b64 s[24:25], s[24:25], 19
	s_add_u32 s24, s6, s24
	s_addc_u32 s25, s7, s25
	s_and_b64 s[40:41], s[38:39], exec
	s_cselect_b32 s61, s25, s1
	s_cselect_b32 s62, s24, s0
	s_ashr_i32 s35, s34, 31
	s_lshl_b64 s[34:35], s[34:35], 19
	s_add_u32 s34, s22, s34
	s_addc_u32 s35, s23, s35
	s_and_b64 s[38:39], s[38:39], exec
	s_cselect_b32 s63, s35, s37
	s_cselect_b32 s64, s34, s36
	s_add_u32 s65, s36, 0x100
	s_addc_u32 s67, s37, 0
	s_add_u32 s36, s0, 0x40080
	v_mov_b32_e32 v2, 0
	s_addc_u32 s37, s1, 0
	s_mov_b32 s69, -2
	v_mov_b32_e32 v3, v2
	v_mov_b32_e32 v4, v2
	v_mov_b32_e32 v5, v2
	v_mov_b32_e32 v6, v2
	v_mov_b32_e32 v7, v2
	v_mov_b32_e32 v8, v2
	v_mov_b32_e32 v9, v2
	v_mov_b32_e32 v14, v2
	v_mov_b32_e32 v15, v2
	v_mov_b32_e32 v16, v2
	v_mov_b32_e32 v17, v2
	v_mov_b32_e32 v22, v2
	v_mov_b32_e32 v23, v2
	v_mov_b32_e32 v24, v2
	v_mov_b32_e32 v25, v2
	v_mov_b32_e32 v30, v2
	v_mov_b32_e32 v31, v2
	v_mov_b32_e32 v32, v2
	v_mov_b32_e32 v33, v2
	v_mov_b32_e32 v38, v2
	v_mov_b32_e32 v39, v2
	v_mov_b32_e32 v40, v2
	v_mov_b32_e32 v41, v2
	v_mov_b32_e32 v46, v2
	v_mov_b32_e32 v47, v2
	v_mov_b32_e32 v48, v2
	v_mov_b32_e32 v49, v2
	v_mov_b32_e32 v54, v2
	v_mov_b32_e32 v55, v2
	v_mov_b32_e32 v56, v2
	v_mov_b32_e32 v57, v2
	v_mov_b32_e32 v10, v2
	v_mov_b32_e32 v11, v2
	v_mov_b32_e32 v12, v2
	v_mov_b32_e32 v13, v2
	v_mov_b32_e32 v18, v2
	v_mov_b32_e32 v19, v2
	v_mov_b32_e32 v20, v2
	v_mov_b32_e32 v21, v2
	v_mov_b32_e32 v26, v2
	v_mov_b32_e32 v27, v2
	v_mov_b32_e32 v28, v2
	v_mov_b32_e32 v29, v2
	v_mov_b32_e32 v34, v2
	v_mov_b32_e32 v35, v2
	v_mov_b32_e32 v36, v2
	v_mov_b32_e32 v37, v2
	v_mov_b32_e32 v42, v2
	v_mov_b32_e32 v43, v2
	v_mov_b32_e32 v44, v2
	v_mov_b32_e32 v45, v2
	v_mov_b32_e32 v50, v2
	v_mov_b32_e32 v51, v2
	v_mov_b32_e32 v52, v2
	v_mov_b32_e32 v53, v2
	v_mov_b32_e32 v58, v2
	v_mov_b32_e32 v59, v2
	v_mov_b32_e32 v60, v2
	v_mov_b32_e32 v61, v2
	v_mov_b32_e32 v62, v2
	v_mov_b32_e32 v63, v2
	v_mov_b32_e32 v64, v2
	v_mov_b32_e32 v65, v2
	v_mov_b32_e32 v66, v2
	v_mov_b32_e32 v67, v2
	v_mov_b32_e32 v68, v2
	v_mov_b32_e32 v69, v2
	v_mov_b32_e32 v70, v2
	v_mov_b32_e32 v71, v2
	v_mov_b32_e32 v72, v2
	v_mov_b32_e32 v73, v2
	v_mov_b32_e32 v78, v2
	v_mov_b32_e32 v79, v2
	v_mov_b32_e32 v80, v2
	v_mov_b32_e32 v81, v2
	v_mov_b32_e32 v86, v2
	v_mov_b32_e32 v87, v2
	v_mov_b32_e32 v88, v2
	v_mov_b32_e32 v89, v2
	v_mov_b32_e32 v94, v2
	v_mov_b32_e32 v95, v2
	v_mov_b32_e32 v96, v2
	v_mov_b32_e32 v97, v2
	v_mov_b32_e32 v102, v2
	v_mov_b32_e32 v103, v2
	v_mov_b32_e32 v104, v2
	v_mov_b32_e32 v105, v2
	v_mov_b32_e32 v106, v2
	v_mov_b32_e32 v107, v2
	v_mov_b32_e32 v108, v2
	v_mov_b32_e32 v109, v2
	v_mov_b32_e32 v114, v2
	v_mov_b32_e32 v115, v2
	v_mov_b32_e32 v116, v2
	v_mov_b32_e32 v117, v2
	v_mov_b32_e32 v74, v2
	v_mov_b32_e32 v75, v2
	v_mov_b32_e32 v76, v2
	v_mov_b32_e32 v77, v2
	v_mov_b32_e32 v82, v2
	v_mov_b32_e32 v83, v2
	v_mov_b32_e32 v84, v2
	v_mov_b32_e32 v85, v2
	v_mov_b32_e32 v90, v2
	v_mov_b32_e32 v91, v2
	v_mov_b32_e32 v92, v2
	v_mov_b32_e32 v93, v2
	v_mov_b32_e32 v98, v2
	v_mov_b32_e32 v99, v2
	v_mov_b32_e32 v100, v2
	v_mov_b32_e32 v101, v2
	v_mov_b32_e32 v110, v2
	v_mov_b32_e32 v111, v2
	v_mov_b32_e32 v112, v2
	v_mov_b32_e32 v113, v2
	v_mov_b32_e32 v118, v2
	v_mov_b32_e32 v119, v2
	v_mov_b32_e32 v120, v2
	v_mov_b32_e32 v121, v2
	v_mov_b32_e32 v122, v2
	v_mov_b32_e32 v123, v2
	v_mov_b32_e32 v124, v2
	v_mov_b32_e32 v125, v2
	v_mov_b32_e32 v126, v2
	v_mov_b32_e32 v127, v2
	v_mov_b32_e32 v128, v2
	v_mov_b32_e32 v129, v2
	.p2align 6

.LBB0_2737:
	v_bfe_u32 v195, v2, 4, 2
	v_and_b32_e32 v194, 15, v2
	v_lshlrev_b32_e32 v3, 4, v195
	v_lshlrev_b32_e32 v2, 2, v2
	v_lshl_or_b32 v3, v194, 6, v3
	s_lshl_b32 s0, s6, 13
	v_and_b32_e32 v2, 32, v2
	v_bitop3_b32 v8, v3, s0, v2 bitop3:0xde
	s_lshl_b32 s0, s1, 5
	v_mov_b32_e32 v165, v163
	s_and_b32 s50, s0, 0x60
	v_lshl_add_u64 v[4:5], s[30:31], 0, v[164:165]
	v_mov_b32_e32 v167, v163
	s_lshl_b32 s0, s50, 7
	v_lshl_add_u64 v[6:7], s[30:31], 0, v[166:167]
	v_bitop3_b32 v196, v3, s0, v2 bitop3:0xde
	s_add_i32 m0, s45, 0x18000
	v_lshl_add_u64 v[2:3], v[4:5], 0, s[20:21]
	v_mov_b32_e32 v169, v163
	s_lshl_b32 s49, s6, 6
	s_waitcnt vmcnt(4)
	s_barrier
	global_load_lds_dwordx4 v[2:3], off
	v_lshl_add_u64 v[2:3], v[6:7], 0, s[20:21]
	s_add_i32 m0, s45, 0x1a000
	s_add_i32 s51, s45, 0x8000
	s_add_i32 s52, s45, 0xa000
	v_mov_b32_e32 v171, v163
	global_load_lds_dwordx4 v[2:3], off
	v_lshl_add_u64 v[2:3], s[18:19], 0, v[168:169]
	s_mov_b32 m0, s51
	s_add_u32 s0, s30, 0x20080
	global_load_lds_dwordx4 v[2:3], off
	v_lshl_add_u64 v[2:3], s[18:19], 0, v[170:171]
	s_mov_b32 m0, s52
	s_addc_u32 s1, s31, 0
	global_load_lds_dwordx4 v[2:3], off
	s_add_i32 m0, s45, 0x1c000
	v_lshl_add_u64 v[2:3], s[0:1], 0, v[164:165]
	global_load_lds_dwordx4 v[2:3], off
	v_lshl_add_u64 v[2:3], s[0:1], 0, v[166:167]
	s_add_i32 m0, s45, 0x1e000
	s_mov_b32 s53, 0
	global_load_lds_dwordx4 v[2:3], off
	s_waitcnt vmcnt(6)
	v_add_u32_e32 v169, 0, v8
	s_barrier
	.p2align 6

.LBB0_2808:
	s_add_u32 s10, s14, 0x12100000
	s_addc_u32 s11, s15, 0
	s_lshl_b32 s0, s0, 5
	s_mov_b64 s[12:13], 0x80
	s_and_b32 s42, s0, 0x60
	s_add_i32 m0, s25, 0x18000
	v_lshl_add_u64 v[4:5], v[4:5], 0, s[12:13]
	s_lshl_b32 s15, s1, 6
	s_lshl_b32 s7, s1, 13
	s_lshl_b32 s14, s42, 7
	s_waitcnt vmcnt(4)
	s_barrier
	global_load_lds_dwordx4 v[4:5], off
	s_add_i32 m0, s25, 0x1a000
	s_add_u32 s0, s28, 0x8000
	v_lshl_add_u64 v[2:3], v[2:3], 0, s[12:13]
	s_addc_u32 s1, s29, 0
	s_add_i32 s43, s25, 0x8000
	global_load_lds_dwordx4 v[2:3], off
	v_lshl_add_u64 v[2:3], s[0:1], 0, v[152:153]
	s_mov_b32 m0, s43
	s_add_i32 s44, s25, 0xa000
	global_load_lds_dwordx4 v[2:3], off
	v_lshl_add_u64 v[2:3], s[0:1], 0, v[148:149]
	s_add_u32 s0, s26, 0x20080
	s_mov_b32 m0, s44
	s_addc_u32 s1, s27, 0
	global_load_lds_dwordx4 v[2:3], off
	s_add_i32 m0, s25, 0x1c000
	v_lshl_add_u64 v[2:3], s[0:1], 0, v[150:151]
	global_load_lds_dwordx4 v[2:3], off
	v_lshl_add_u64 v[2:3], s[0:1], 0, v[146:147]
	s_add_i32 m0, s25, 0x1e000
	v_bfe_u32 v166, v6, 4, 2
	global_load_lds_dwordx4 v[2:3], off
	v_and_b32_e32 v1, 15, v6
	v_lshlrev_b32_e32 v2, 4, v166
	v_lshlrev_b32_e32 v3, 2, v6
	v_lshl_or_b32 v2, v1, 6, v2
	v_and_b32_e32 v3, 32, v3
	v_bitop3_b32 v4, v2, s7, v3 bitop3:0xde
	v_bitop3_b32 v167, v2, s14, v3 bitop3:0xde
	v_lshlrev_b32_e32 v2, 10, v7
	v_and_b32_e32 v2, 0xfffff800, v2
	v_lshl_add_u32 v2, v8, 7, v2
	v_and_b32_e32 v3, 1, v7
	v_lshl_or_b32 v2, v3, 6, v2
	v_lshl_add_u32 v154, v9, 1, v2
	v_lshlrev_b32_e32 v2, 10, v11
	v_and_b32_e32 v2, 0xfffff800, v2
	s_waitcnt vmcnt(6)
	v_lshl_add_u32 v2, v10, 7, v2
	v_and_b32_e32 v3, 1, v11
	v_lshl_or_b32 v2, v3, 6, v2
	s_add_i32 s45, 0, 0x10000
	s_add_i32 s46, 0, 0x14000
	s_sext_i32_i8 s48, s6
	v_mov_b32_e32 v155, v151
	v_lshl_add_u32 v156, v12, 1, v2
	v_mov_b32_e32 v157, v151
	v_mov_b64_e32 v[158:159], 0x800
	v_mov_b64_e32 v[160:161], 0x7ff
	v_add_u32_e32 v168, s45, v167
	v_add_u32_e32 v169, 0, v4
	v_mov_b32_e32 v170, 0x7f7f7f7f
	v_add_u32_e32 v171, s46, v167
	s_mov_b32 s14, 0x3d000000
	s_mov_b32 s47, 0xc3d00000
	v_mov_b32_e32 v172, 0x43d00000
	s_barrier
	.p2align 6

.LBB0_2815:
	s_ashr_i32 s19, s18, 31
	s_lshl_b64 s[0:1], s[18:19], 18
	v_cmp_lt_i64_e32 vcc, s[20:21], v[158:159]
	s_add_u32 s20, s5, s0
	s_addc_u32 s21, s8, s1
	s_and_b64 s[0:1], vcc, exec
	s_cselect_b32 s19, s21, s29
	s_cselect_b32 s49, s20, s28
	s_ashr_i32 s0, s18, 5
	s_ashr_i32 s1, s0, 31
	s_lshl_b64 s[0:1], s[0:1], 20
	s_add_u32 s22, s9, s0
	s_addc_u32 s23, s36, s1
	s_ashr_i32 s17, s16, 31
	s_lshl_b64 s[0:1], s[16:17], 18
	s_add_u32 s22, s22, s0
	s_addc_u32 s23, s23, s1
	s_and_b64 s[0:1], vcc, exec
	s_cselect_b32 s17, s23, s27
	s_cselect_b32 s50, s22, s26
	s_add_u32 s51, s26, 0x100
	s_addc_u32 s52, s27, 0
	s_add_u32 s26, s28, 0xc000
	v_mov_b32_e32 v18, 0
	s_addc_u32 s27, s29, 0
	s_mov_b32 s53, -2
	v_mov_b32_e32 v19, v18
	v_mov_b32_e32 v20, v18
	v_mov_b32_e32 v21, v18
	v_mov_b32_e32 v22, v18
	v_mov_b32_e32 v23, v18
	v_mov_b32_e32 v24, v18
	v_mov_b32_e32 v25, v18
	v_mov_b32_e32 v34, v18
	v_mov_b32_e32 v35, v18
	v_mov_b32_e32 v36, v18
	v_mov_b32_e32 v37, v18
	v_mov_b32_e32 v38, v18
	v_mov_b32_e32 v39, v18
	v_mov_b32_e32 v40, v18
	v_mov_b32_e32 v41, v18
	v_mov_b32_e32 v50, v18
	v_mov_b32_e32 v51, v18
	v_mov_b32_e32 v52, v18
	v_mov_b32_e32 v53, v18
	v_mov_b32_e32 v54, v18
	v_mov_b32_e32 v55, v18
	v_mov_b32_e32 v56, v18
	v_mov_b32_e32 v57, v18
	v_mov_b32_e32 v66, v18
	v_mov_b32_e32 v67, v18
	v_mov_b32_e32 v68, v18
	v_mov_b32_e32 v69, v18
	v_mov_b32_e32 v70, v18
	v_mov_b32_e32 v71, v18
	v_mov_b32_e32 v72, v18
	v_mov_b32_e32 v73, v18
	v_mov_b32_e32 v26, v18
	v_mov_b32_e32 v27, v18
	v_mov_b32_e32 v28, v18
	v_mov_b32_e32 v29, v18
	v_mov_b32_e32 v30, v18
	v_mov_b32_e32 v31, v18
	v_mov_b32_e32 v32, v18
	v_mov_b32_e32 v33, v18
	v_mov_b32_e32 v42, v18
	v_mov_b32_e32 v43, v18
	v_mov_b32_e32 v44, v18
	v_mov_b32_e32 v45, v18
	v_mov_b32_e32 v46, v18
	v_mov_b32_e32 v47, v18
	v_mov_b32_e32 v48, v18
	v_mov_b32_e32 v49, v18
	v_mov_b32_e32 v58, v18
	v_mov_b32_e32 v59, v18
	v_mov_b32_e32 v60, v18
	v_mov_b32_e32 v61, v18
	v_mov_b32_e32 v62, v18
	v_mov_b32_e32 v63, v18
	v_mov_b32_e32 v64, v18
	v_mov_b32_e32 v65, v18
	v_mov_b32_e32 v74, v18
	v_mov_b32_e32 v75, v18
	v_mov_b32_e32 v76, v18
	v_mov_b32_e32 v77, v18
	v_mov_b32_e32 v78, v18
	v_mov_b32_e32 v79, v18
	v_mov_b32_e32 v80, v18
	v_mov_b32_e32 v81, v18
	v_mov_b32_e32 v82, v18
	v_mov_b32_e32 v83, v18
	v_mov_b32_e32 v84, v18
	v_mov_b32_e32 v85, v18
	v_mov_b32_e32 v86, v18
	v_mov_b32_e32 v87, v18
	v_mov_b32_e32 v88, v18
	v_mov_b32_e32 v89, v18
	v_mov_b32_e32 v98, v18
	v_mov_b32_e32 v99, v18
	v_mov_b32_e32 v100, v18
	v_mov_b32_e32 v101, v18
	v_mov_b32_e32 v102, v18
	v_mov_b32_e32 v103, v18
	v_mov_b32_e32 v104, v18
	v_mov_b32_e32 v105, v18
	v_mov_b32_e32 v114, v18
	v_mov_b32_e32 v115, v18
	v_mov_b32_e32 v116, v18
	v_mov_b32_e32 v117, v18
	v_mov_b32_e32 v118, v18
	v_mov_b32_e32 v119, v18
	v_mov_b32_e32 v120, v18
	v_mov_b32_e32 v121, v18
	v_mov_b32_e32 v130, v18
	v_mov_b32_e32 v131, v18
	v_mov_b32_e32 v132, v18
	v_mov_b32_e32 v133, v18
	v_mov_b32_e32 v134, v18
	v_mov_b32_e32 v135, v18
	v_mov_b32_e32 v136, v18
	v_mov_b32_e32 v137, v18
	v_mov_b32_e32 v90, v18
	v_mov_b32_e32 v91, v18
	v_mov_b32_e32 v92, v18
	v_mov_b32_e32 v93, v18
	v_mov_b32_e32 v94, v18
	v_mov_b32_e32 v95, v18
	v_mov_b32_e32 v96, v18
	v_mov_b32_e32 v97, v18
	v_mov_b32_e32 v106, v18
	v_mov_b32_e32 v107, v18
	v_mov_b32_e32 v108, v18
	v_mov_b32_e32 v109, v18
	v_mov_b32_e32 v110, v18
	v_mov_b32_e32 v111, v18
	v_mov_b32_e32 v112, v18
	v_mov_b32_e32 v113, v18
	v_mov_b32_e32 v122, v18
	v_mov_b32_e32 v123, v18
	v_mov_b32_e32 v124, v18
	v_mov_b32_e32 v125, v18
	v_mov_b32_e32 v126, v18
	v_mov_b32_e32 v127, v18
	v_mov_b32_e32 v128, v18
	v_mov_b32_e32 v129, v18
	v_mov_b32_e32 v138, v18
	v_mov_b32_e32 v139, v18
	v_mov_b32_e32 v140, v18
	v_mov_b32_e32 v141, v18
	v_mov_b32_e32 v142, v18
	v_mov_b32_e32 v143, v18
	v_mov_b32_e32 v144, v18
	v_mov_b32_e32 v145, v18
	.p2align 6
